# table build with 32 loads in flight + transposed reduction; P0 gain-fold LDS reads batched; x to bf16 loop unrolled x4; epilogue vmcnt(16) instead of vmcnt(0)
# speedup vs baseline: 1.0128x; 1.0072x over previous
; __device__ __forceinline__ unsigned f2bf(float f) { unsigned u = __builtin_bit_cast(unsigned, f); return (u + 0x7fffu + ((u >> 16) & 1u)) >> 16; }
; __device__ __forceinline__ void transpose_item(const float* W, int K, int N, bf16_t* WT, LAS float* scr, int item, int lane, const float* gam, const float* bet, float* sdst) {
;     ...
;     if (gam) {
;         const int n = lane & 31, h = lane >> 5; float sa = 0.f, ta = 0.f;
; #pragma unroll 8
;         for (int i = 0; i < 32; ++i) { const int kk = h * 32 + i; const float w = scr[kk * 33 + n]; const float wg = w * scr[64 * 33 + kk];
;             scr[kk * 33 + n] = wg; sa += bf_lo(f2bf(wg)); ta += w * scr[64 * 33 + 64 + kk]; }
;         sa += __shfl_xor(sa, 32); ta += __shfl_xor(ta, 32);
;         if (lane < 32) { unsafeAtomicAdd(sdst + n0 + lane, sa); unsafeAtomicAdd(sdst + ST_N + n0 + lane, ta); }
.LBB0_84:
	v_add_u32_e32 v42, s8, v14
	ds_read2_b32 v[32:33], v3 offset1:33
	ds_read2_b32 v[34:35], v3 offset0:66 offset1:99
	ds_read2_b32 v[36:37], v3 offset0:132 offset1:165
	ds_read2_b32 v[38:39], v3 offset0:198 offset1:231
	ds_read_b128 v[44:47], v42
	ds_read_b128 v[48:51], v42 offset:16
	ds_read_b128 v[52:55], v42 offset:256
	ds_read_b128 v[56:59], v42 offset:272
	s_add_i32 s8, s8, 32
	s_cmpk_eq_i32 s8, 0x80
	s_waitcnt lgkmcnt(0)
	v_mul_f32_e32 v40, v32, v44
	v_mul_f32_e32 v60, v32, v52
	ds_write_b32 v3, v40
	v_bfe_u32 v41, v40, 16, 1
	v_add3_u32 v41, v40, v41, s3
	v_and_b32_e32 v61, 0xffff0000, v41
	v_pk_add_f32 v[6:7], v[6:7], v[60:61]
	v_mul_f32_e32 v62, v33, v45
	v_mul_f32_e32 v60, v33, v53
	ds_write_b32 v3, v62 offset:132
	v_bfe_u32 v63, v62, 16, 1
	v_add3_u32 v63, v62, v63, s3
	v_and_b32_e32 v61, 0xffff0000, v63
	v_pk_add_f32 v[6:7], v[6:7], v[60:61]
	v_mul_f32_e32 v40, v34, v46
	v_mul_f32_e32 v60, v34, v54
	ds_write_b32 v3, v40 offset:264
	v_bfe_u32 v41, v40, 16, 1
	v_add3_u32 v41, v40, v41, s3
	v_and_b32_e32 v61, 0xffff0000, v41
	v_pk_add_f32 v[6:7], v[6:7], v[60:61]
	v_mul_f32_e32 v62, v35, v47
	v_mul_f32_e32 v60, v35, v55
	ds_write_b32 v3, v62 offset:396
	v_bfe_u32 v63, v62, 16, 1
	v_add3_u32 v63, v62, v63, s3
	v_and_b32_e32 v61, 0xffff0000, v63
	v_pk_add_f32 v[6:7], v[6:7], v[60:61]
	v_mul_f32_e32 v40, v36, v48
	v_mul_f32_e32 v60, v36, v56
	ds_write_b32 v3, v40 offset:528
	v_bfe_u32 v41, v40, 16, 1
	v_add3_u32 v41, v40, v41, s3
	v_and_b32_e32 v61, 0xffff0000, v41
	v_pk_add_f32 v[6:7], v[6:7], v[60:61]
	v_mul_f32_e32 v62, v37, v49
	v_mul_f32_e32 v60, v37, v57
	ds_write_b32 v3, v62 offset:660
	v_bfe_u32 v63, v62, 16, 1
	v_add3_u32 v63, v62, v63, s3
	v_and_b32_e32 v61, 0xffff0000, v63
	v_pk_add_f32 v[6:7], v[6:7], v[60:61]
	v_mul_f32_e32 v40, v38, v50
	v_mul_f32_e32 v60, v38, v58
	ds_write_b32 v3, v40 offset:792
	v_bfe_u32 v41, v40, 16, 1
	v_add3_u32 v41, v40, v41, s3
	v_and_b32_e32 v61, 0xffff0000, v41
	v_pk_add_f32 v[6:7], v[6:7], v[60:61]
	v_mul_f32_e32 v62, v39, v51
	v_mul_f32_e32 v60, v39, v59
	ds_write_b32 v3, v62 offset:924
	v_bfe_u32 v63, v62, 16, 1
	v_add3_u32 v63, v62, v63, s3
	v_and_b32_e32 v61, 0xffff0000, v63
	v_pk_add_f32 v[6:7], v[6:7], v[60:61]
	v_add_u32_e32 v3, 0x420, v3
	s_cbranch_scc0 .LBB0_84
	v_and_b32_e32 v32, 64, v31
	v_xor_b32_e32 v3, 32, v31
	v_add_u32_e32 v32, 64, v32
	v_cmp_lt_i32_e32 vcc, v3, v32
	s_nop 1
	v_cndmask_b32_e32 v3, v31, v3, vcc
	v_lshlrev_b32_e32 v32, 2, v3
	ds_bpermute_b32 v3, v32, v7
	ds_bpermute_b32 v32, v32, v6
	s_and_saveexec_b64 s[8:9], s[4:5]
	s_cbranch_execz .LBB0_44
	s_add_u32 s10, s60, s68
	s_addc_u32 s11, s61, s69
	s_waitcnt lgkmcnt(0)
	v_add_f32_e32 v32, v6, v32
	v_add_f32_e32 v3, v7, v3
	v_lshl_add_u64 v[6:7], v[4:5], 2, s[10:11]
	global_atomic_add_f32 v[6:7], v3, off
	v_add_co_u32_e32 v6, vcc, 0x10000, v6
	s_nop 1
	v_addc_co_u32_e32 v7, vcc, 0, v7, vcc
	global_atomic_add_f32 v[6:7], v32, off
	s_branch .LBB0_44

; __device__ __forceinline__ u32x4 pack8f(f32x4 a, f32x4 b) { u32x4 w; w.x = cvt_pk_bf16(a[0], a[1]); w.y = cvt_pk_bf16(a[2], a[3]); w.z = cvt_pk_bf16(b[0], b[1]); w.w = cvt_pk_bf16(b[2], b[3]); return w; }
; __global__ void __launch_bounds__(NTHR, 2) mega_fwd(Args) {
;     ...
;             { const int n8 = MTOK * DM / 8; const f32x4* x4 = (const f32x4*)INP(0); u32x4* xb = WSP(u32x4, WS_XB);
;               for (int i = gw * 64 + lane; i < n8; i += NGW * 64) { const f32x4 a = x4[2 * i], b = x4[2 * i + 1];
;                   const int row = i >> 9, c8 = i & 511;
;                   xb[(size_t)(row >> 8) * (BM_ * DM / 8) + (size_t)(c8 >> 3) * (BM_ * 8) + (row & 255) * 8 + (c8 & 7)] = pack8f(a, b); } }
.LBB0_90:
	s_or_b64 exec, exec, s[4:5]
	s_mov_b32 s3, 0x800000
	v_cmp_gt_i32_e32 vcc, s3, v6
	s_and_saveexec_b64 s[4:5], vcc
	s_load_dwordx2 s[84:85], s[0:1], 0xb8
	v_readlane_b32 s86, v248, 5
	v_readlane_b32 s87, v248, 6
	s_cbranch_execz .LBB0_93
	s_load_dwordx2 s[6:7], s[46:47], 0x0
	s_waitcnt lgkmcnt(0)
	s_add_u32 s8, s48, 0x31800000
	v_and_b32_e32 v0, 7, v4
	v_mov_b32_e32 v1, 0
	s_addc_u32 s9, s49, 0
	v_lshlrev_b32_e32 v2, 1, v6
	s_lshl_b32 s3, s40, 10
	v_lshlrev_b32_e32 v7, 8, v6
	s_lshl_b32 s12, s40, 17
	s_mov_b64 s[10:11], 0
	v_lshlrev_b32_e32 v4, 4, v0
	v_mov_b32_e32 v5, v1
	s_mov_b32 s13, 0x7fffff
	s_cmpk_lg_i32 s40, 0x100
	s_cbranch_scc1 .LBB0_92
	v_lshlrev_b32_e32 v16, 5, v6
	v_and_b32_e32 v17, 0x1f800, v7
	v_lshlrev_b32_e32 v17, 4, v17
	v_lshrrev_b32_e32 v18, 2, v6
	v_and_b32_e32 v18, 0x7f80, v18
	v_add3_u32 v17, v17, v18, v4
	s_mov_b32 s3, 16
.Lxb_loop:
	global_load_dwordx4 v[20:23], v16, s[6:7]
	global_load_dwordx4 v[24:27], v16, s[6:7] offset:16
	s_add_u32 s12, s6, 0x400000
	s_addc_u32 s13, s7, 0
	global_load_dwordx4 v[28:31], v16, s[12:13]
	global_load_dwordx4 v[32:35], v16, s[12:13] offset:16
	s_add_u32 s12, s6, 0x800000
	s_addc_u32 s13, s7, 0
	global_load_dwordx4 v[36:39], v16, s[12:13]
	global_load_dwordx4 v[40:43], v16, s[12:13] offset:16
	s_add_u32 s12, s6, 0xc00000
	s_addc_u32 s13, s7, 0
	global_load_dwordx4 v[44:47], v16, s[12:13]
	global_load_dwordx4 v[48:51], v16, s[12:13] offset:16
	s_add_u32 s6, s6, 0x1000000
	s_addc_u32 s7, s7, 0
	s_waitcnt vmcnt(6)
	v_cvt_pk_bf16_f32 v20, v20, v21
	v_cvt_pk_bf16_f32 v21, v22, v23
	v_cvt_pk_bf16_f32 v22, v24, v25
	v_cvt_pk_bf16_f32 v23, v26, v27
	global_store_dwordx4 v17, v[20:23], s[8:9]
	s_waitcnt vmcnt(5)
	v_cvt_pk_bf16_f32 v28, v28, v29
	v_cvt_pk_bf16_f32 v29, v30, v31
	v_cvt_pk_bf16_f32 v30, v32, v33
	v_cvt_pk_bf16_f32 v31, v34, v35
	s_add_u32 s12, s8, 0x200000
	s_addc_u32 s13, s9, 0
	global_store_dwordx4 v17, v[28:31], s[12:13]
	s_waitcnt vmcnt(4)
	v_cvt_pk_bf16_f32 v36, v36, v37
	v_cvt_pk_bf16_f32 v37, v38, v39
	v_cvt_pk_bf16_f32 v38, v40, v41
	v_cvt_pk_bf16_f32 v39, v42, v43
	s_add_u32 s12, s8, 0x400000
	s_addc_u32 s13, s9, 0
	global_store_dwordx4 v17, v[36:39], s[12:13]
	s_waitcnt vmcnt(3)
	v_cvt_pk_bf16_f32 v44, v44, v45
	v_cvt_pk_bf16_f32 v45, v46, v47
	v_cvt_pk_bf16_f32 v46, v48, v49
	v_cvt_pk_bf16_f32 v47, v50, v51
	s_add_u32 s12, s8, 0x600000
	s_addc_u32 s13, s9, 0
	global_store_dwordx4 v17, v[44:47], s[12:13]
	s_add_u32 s8, s8, 0x800000
	s_addc_u32 s9, s9, 0
	s_sub_u32 s3, s3, 1
	s_cmp_lg_u32 s3, 0
	s_cbranch_scc1 .Lxb_loop
	s_branch .LBB0_93

; #define LAS __attribute__((address_space(3)))
; __device__ __forceinline__ void build_tbl(const f32x2* PS, int pm, LAS unsigned char* lds, int wid, int lane) {
;     LAS f32x2* tbl = (LAS f32x2*)(lds + TBL_OFF);
;     const f32x2* p = PS + ((size_t)pm * BM + wid * 32) * 64 + lane;
; #pragma unroll 8
;     for (int i = 0; i < 32; ++i) {
;         const f32x2 v = p[(size_t)i * 64];
;         const float a = wave_sum(v.x), b = wave_sum(v.y);
;         if (lane == 0) { const float mu = a * (1.f / DM), var = fmaxf(b * (1.f / DM) - mu * mu, 0.f); tbl[wid * 32 + i] = (f32x2){mu, 1.f / sqrtf(var + LN_EPS)}; }
;     }
; }
; __device__ __forceinline__ void ensure_tbl(const f32x2* PS, int sid, int pm, const EpiCtx& X) {
;     volatile LAS unsigned* keyw = (volatile LAS unsigned*)(X.lds + MISC_OFF) + KEY_WORD;
;     const unsigned key = (unsigned)(sid * 64 + pm + 1);
;     if ((unsigned)__builtin_amdgcn_readfirstlane((int)keyw[0]) != key) {
;         build_tbl(PS, pm, X.lds, X.wid, X.lane);
.LBB0_692:
	v_mov_b32_e32 v128, s54
	ds_read_b32 v128, v128
	s_add_i32 s25, s60, 1
	s_ashr_i32 s61, s60, 31
	s_waitcnt lgkmcnt(0)
	v_readfirstlane_b32 s18, v128
	s_cmp_eq_u32 s18, s25
	s_cbranch_scc1 .LBB0_714
	s_ashr_i32 s61, s60, 31
	s_lshl_b64 s[18:19], s[60:61], 17
	v_lshl_add_u64 v[222:223], v[154:155], 0, s[18:19]
	s_mov_b64 s[18:19], 0x1000
	global_load_dwordx2 v[128:129], v[222:223], off offset:-2048
	global_load_dwordx2 v[130:131], v[222:223], off offset:-1536
	global_load_dwordx2 v[132:133], v[222:223], off offset:-1024
	global_load_dwordx2 v[134:135], v[222:223], off offset:-512
	global_load_dwordx2 v[136:137], v[222:223], off
	global_load_dwordx2 v[138:139], v[222:223], off offset:512
	global_load_dwordx2 v[170:171], v[222:223], off offset:1024
	global_load_dwordx2 v[172:173], v[222:223], off offset:1536
	v_lshl_add_u64 v[222:223], v[222:223], 0, s[18:19]
	global_load_dwordx2 v[174:175], v[222:223], off offset:-2048
	global_load_dwordx2 v[176:177], v[222:223], off offset:-1536
	global_load_dwordx2 v[178:179], v[222:223], off offset:-1024
	global_load_dwordx2 v[180:181], v[222:223], off offset:-512
	global_load_dwordx2 v[182:183], v[222:223], off
	global_load_dwordx2 v[184:185], v[222:223], off offset:512
	global_load_dwordx2 v[186:187], v[222:223], off offset:1024
	global_load_dwordx2 v[188:189], v[222:223], off offset:1536
	v_lshl_add_u64 v[222:223], v[222:223], 0, s[18:19]
	global_load_dwordx2 v[190:191], v[222:223], off offset:-2048
	global_load_dwordx2 v[192:193], v[222:223], off offset:-1536
	global_load_dwordx2 v[194:195], v[222:223], off offset:-1024
	global_load_dwordx2 v[196:197], v[222:223], off offset:-512
	global_load_dwordx2 v[198:199], v[222:223], off
	global_load_dwordx2 v[200:201], v[222:223], off offset:512
	global_load_dwordx2 v[202:203], v[222:223], off offset:1024
	global_load_dwordx2 v[204:205], v[222:223], off offset:1536
	v_lshl_add_u64 v[222:223], v[222:223], 0, s[18:19]
	global_load_dwordx2 v[206:207], v[222:223], off offset:-2048
	global_load_dwordx2 v[208:209], v[222:223], off offset:-1536
	global_load_dwordx2 v[210:211], v[222:223], off offset:-1024
	global_load_dwordx2 v[212:213], v[222:223], off offset:-512
	global_load_dwordx2 v[214:215], v[222:223], off
	global_load_dwordx2 v[216:217], v[222:223], off offset:512
	global_load_dwordx2 v[218:219], v[222:223], off offset:1024
	global_load_dwordx2 v[220:221], v[222:223], off offset:1536
	s_waitcnt vmcnt(0)
	v_permlane32_swap_b32_e32 v128, v190
	v_permlane32_swap_b32_e32 v129, v191
	v_permlane32_swap_b32_e32 v130, v192
	v_permlane32_swap_b32_e32 v131, v193
	v_permlane32_swap_b32_e32 v132, v194
	v_permlane32_swap_b32_e32 v133, v195
	v_permlane32_swap_b32_e32 v134, v196
	v_permlane32_swap_b32_e32 v135, v197
	v_permlane32_swap_b32_e32 v136, v198
	v_permlane32_swap_b32_e32 v137, v199
	v_permlane32_swap_b32_e32 v138, v200
	v_permlane32_swap_b32_e32 v139, v201
	v_permlane32_swap_b32_e32 v170, v202
	v_permlane32_swap_b32_e32 v171, v203
	v_permlane32_swap_b32_e32 v172, v204
	v_permlane32_swap_b32_e32 v173, v205
	v_permlane32_swap_b32_e32 v174, v206
	v_permlane32_swap_b32_e32 v175, v207
	v_permlane32_swap_b32_e32 v176, v208
	v_permlane32_swap_b32_e32 v177, v209
	v_permlane32_swap_b32_e32 v178, v210
	v_permlane32_swap_b32_e32 v179, v211
	v_permlane32_swap_b32_e32 v180, v212
	v_permlane32_swap_b32_e32 v181, v213
	v_permlane32_swap_b32_e32 v182, v214
	v_permlane32_swap_b32_e32 v183, v215
	v_permlane32_swap_b32_e32 v184, v216
	v_permlane32_swap_b32_e32 v185, v217
	v_permlane32_swap_b32_e32 v186, v218
	v_permlane32_swap_b32_e32 v187, v219
	v_permlane32_swap_b32_e32 v188, v220
	v_permlane32_swap_b32_e32 v189, v221
	v_pk_add_f32 v[128:129], v[128:129], v[190:191]
	v_pk_add_f32 v[130:131], v[130:131], v[192:193]
	v_pk_add_f32 v[132:133], v[132:133], v[194:195]
	v_pk_add_f32 v[134:135], v[134:135], v[196:197]
	v_pk_add_f32 v[136:137], v[136:137], v[198:199]
	v_pk_add_f32 v[138:139], v[138:139], v[200:201]
	v_pk_add_f32 v[170:171], v[170:171], v[202:203]
	v_pk_add_f32 v[172:173], v[172:173], v[204:205]
	v_pk_add_f32 v[174:175], v[174:175], v[206:207]
	v_pk_add_f32 v[176:177], v[176:177], v[208:209]
	v_pk_add_f32 v[178:179], v[178:179], v[210:211]
	v_pk_add_f32 v[180:181], v[180:181], v[212:213]
	v_pk_add_f32 v[182:183], v[182:183], v[214:215]
	v_pk_add_f32 v[184:185], v[184:185], v[216:217]
	v_pk_add_f32 v[186:187], v[186:187], v[218:219]
	v_pk_add_f32 v[188:189], v[188:189], v[220:221]
	s_nop 1
	v_permlane16_swap_b32_e32 v128, v174
	v_permlane16_swap_b32_e32 v129, v175
	v_permlane16_swap_b32_e32 v130, v176
	v_permlane16_swap_b32_e32 v131, v177
	v_permlane16_swap_b32_e32 v132, v178
	v_permlane16_swap_b32_e32 v133, v179
	v_permlane16_swap_b32_e32 v134, v180
	v_permlane16_swap_b32_e32 v135, v181
	v_permlane16_swap_b32_e32 v136, v182
	v_permlane16_swap_b32_e32 v137, v183
	v_permlane16_swap_b32_e32 v138, v184
	v_permlane16_swap_b32_e32 v139, v185
	v_permlane16_swap_b32_e32 v170, v186
	v_permlane16_swap_b32_e32 v171, v187
	v_permlane16_swap_b32_e32 v172, v188
	v_permlane16_swap_b32_e32 v173, v189
	v_pk_add_f32 v[128:129], v[128:129], v[174:175]
	v_pk_add_f32 v[130:131], v[130:131], v[176:177]
	v_pk_add_f32 v[132:133], v[132:133], v[178:179]
	v_pk_add_f32 v[134:135], v[134:135], v[180:181]
	v_pk_add_f32 v[136:137], v[136:137], v[182:183]
	v_pk_add_f32 v[138:139], v[138:139], v[184:185]
	v_pk_add_f32 v[170:171], v[170:171], v[186:187]
	v_pk_add_f32 v[172:173], v[172:173], v[188:189]
	s_nop 1
	v_add_f32_dpp v128, v128, v128 row_ror:8 row_mask:0xf bank_mask:0xf
	v_add_f32_dpp v129, v129, v129 row_ror:8 row_mask:0xf bank_mask:0xf
	v_add_f32_dpp v130, v130, v130 row_ror:8 row_mask:0xf bank_mask:0xf
; __device__ __forceinline__ void build_tbl(const f32x2* PS, int pm, LAS unsigned char* lds, int wid, int lane) {
;     ...
;     for (int i = 0; i < 32; ++i) {
;         const f32x2 v = p[(size_t)i * 64];
;         const float a = wave_sum(v.x), b = wave_sum(v.y);
;         if (lane == 0) { const float mu = a * (1.f / DM), var = fmaxf(b * (1.f / DM) - mu * mu, 0.f); tbl[wid * 32 + i] = (f32x2){mu, 1.f / sqrtf(var + LN_EPS)}; }
;     }
	v_add_f32_dpp v131, v131, v131 row_ror:8 row_mask:0xf bank_mask:0xf
	v_add_f32_dpp v132, v132, v132 row_ror:8 row_mask:0xf bank_mask:0xf
	v_add_f32_dpp v133, v133, v133 row_ror:8 row_mask:0xf bank_mask:0xf
	v_add_f32_dpp v134, v134, v134 row_ror:8 row_mask:0xf bank_mask:0xf
	v_add_f32_dpp v135, v135, v135 row_ror:8 row_mask:0xf bank_mask:0xf
	v_add_f32_dpp v136, v136, v136 row_ror:8 row_mask:0xf bank_mask:0xf
	v_add_f32_dpp v137, v137, v137 row_ror:8 row_mask:0xf bank_mask:0xf
	v_add_f32_dpp v138, v138, v138 row_ror:8 row_mask:0xf bank_mask:0xf
	v_add_f32_dpp v139, v139, v139 row_ror:8 row_mask:0xf bank_mask:0xf
	v_add_f32_dpp v170, v170, v170 row_ror:8 row_mask:0xf bank_mask:0xf
	v_add_f32_dpp v171, v171, v171 row_ror:8 row_mask:0xf bank_mask:0xf
	v_add_f32_dpp v172, v172, v172 row_ror:8 row_mask:0xf bank_mask:0xf
	v_add_f32_dpp v173, v173, v173 row_ror:8 row_mask:0xf bank_mask:0xf
	v_add_f32_dpp v128, v128, v128 row_ror:4 row_mask:0xf bank_mask:0xf
	v_add_f32_dpp v129, v129, v129 row_ror:4 row_mask:0xf bank_mask:0xf
	v_add_f32_dpp v130, v130, v130 row_ror:4 row_mask:0xf bank_mask:0xf
	v_add_f32_dpp v131, v131, v131 row_ror:4 row_mask:0xf bank_mask:0xf
	v_add_f32_dpp v132, v132, v132 row_ror:4 row_mask:0xf bank_mask:0xf
	v_add_f32_dpp v133, v133, v133 row_ror:4 row_mask:0xf bank_mask:0xf
	v_add_f32_dpp v134, v134, v134 row_ror:4 row_mask:0xf bank_mask:0xf
	v_add_f32_dpp v135, v135, v135 row_ror:4 row_mask:0xf bank_mask:0xf
	v_add_f32_dpp v136, v136, v136 row_ror:4 row_mask:0xf bank_mask:0xf
	v_add_f32_dpp v137, v137, v137 row_ror:4 row_mask:0xf bank_mask:0xf
	v_add_f32_dpp v138, v138, v138 row_ror:4 row_mask:0xf bank_mask:0xf
	v_add_f32_dpp v139, v139, v139 row_ror:4 row_mask:0xf bank_mask:0xf
	v_add_f32_dpp v170, v170, v170 row_ror:4 row_mask:0xf bank_mask:0xf
	v_add_f32_dpp v171, v171, v171 row_ror:4 row_mask:0xf bank_mask:0xf
	v_add_f32_dpp v172, v172, v172 row_ror:4 row_mask:0xf bank_mask:0xf
	v_add_f32_dpp v173, v173, v173 row_ror:4 row_mask:0xf bank_mask:0xf
	v_add_f32_dpp v128, v128, v128 row_ror:2 row_mask:0xf bank_mask:0xf
	v_add_f32_dpp v129, v129, v129 row_ror:2 row_mask:0xf bank_mask:0xf
	v_add_f32_dpp v130, v130, v130 row_ror:2 row_mask:0xf bank_mask:0xf
	v_add_f32_dpp v131, v131, v131 row_ror:2 row_mask:0xf bank_mask:0xf
	v_add_f32_dpp v132, v132, v132 row_ror:2 row_mask:0xf bank_mask:0xf
	v_add_f32_dpp v133, v133, v133 row_ror:2 row_mask:0xf bank_mask:0xf
	v_add_f32_dpp v134, v134, v134 row_ror:2 row_mask:0xf bank_mask:0xf
	v_add_f32_dpp v135, v135, v135 row_ror:2 row_mask:0xf bank_mask:0xf
	v_add_f32_dpp v136, v136, v136 row_ror:2 row_mask:0xf bank_mask:0xf
	v_add_f32_dpp v137, v137, v137 row_ror:2 row_mask:0xf bank_mask:0xf
	v_add_f32_dpp v138, v138, v138 row_ror:2 row_mask:0xf bank_mask:0xf
	v_add_f32_dpp v139, v139, v139 row_ror:2 row_mask:0xf bank_mask:0xf
	v_add_f32_dpp v170, v170, v170 row_ror:2 row_mask:0xf bank_mask:0xf
	v_add_f32_dpp v171, v171, v171 row_ror:2 row_mask:0xf bank_mask:0xf
	v_add_f32_dpp v172, v172, v172 row_ror:2 row_mask:0xf bank_mask:0xf
	v_add_f32_dpp v173, v173, v173 row_ror:2 row_mask:0xf bank_mask:0xf
	v_add_f32_dpp v128, v128, v128 row_ror:1 row_mask:0xf bank_mask:0xf
	v_add_f32_dpp v129, v129, v129 row_ror:1 row_mask:0xf bank_mask:0xf
	v_add_f32_dpp v130, v130, v130 row_ror:1 row_mask:0xf bank_mask:0xf
	v_add_f32_dpp v131, v131, v131 row_ror:1 row_mask:0xf bank_mask:0xf
	v_add_f32_dpp v132, v132, v132 row_ror:1 row_mask:0xf bank_mask:0xf
	v_add_f32_dpp v133, v133, v133 row_ror:1 row_mask:0xf bank_mask:0xf
	v_add_f32_dpp v134, v134, v134 row_ror:1 row_mask:0xf bank_mask:0xf
	v_add_f32_dpp v135, v135, v135 row_ror:1 row_mask:0xf bank_mask:0xf
	v_add_f32_dpp v136, v136, v136 row_ror:1 row_mask:0xf bank_mask:0xf
	v_add_f32_dpp v137, v137, v137 row_ror:1 row_mask:0xf bank_mask:0xf
	v_add_f32_dpp v138, v138, v138 row_ror:1 row_mask:0xf bank_mask:0xf
	v_add_f32_dpp v139, v139, v139 row_ror:1 row_mask:0xf bank_mask:0xf
	v_add_f32_dpp v170, v170, v170 row_ror:1 row_mask:0xf bank_mask:0xf
	v_add_f32_dpp v171, v171, v171 row_ror:1 row_mask:0xf bank_mask:0xf
	v_add_f32_dpp v172, v172, v172 row_ror:1 row_mask:0xf bank_mask:0xf
	v_add_f32_dpp v173, v173, v173 row_ror:1 row_mask:0xf bank_mask:0xf
	s_nop 1
	v_mul_f32_e32 v128, s22, v128
	v_mul_f32_e32 v129, s22, v129
	v_fma_f32 v129, -v128, v128, v129
	v_max_f32_e32 v129, 0, v129
	v_add_f32_e32 v129, 0x3727c5ac, v129
	v_mul_f32_e32 v224, 0x4f800000, v129
	v_cmp_gt_f32_e32 vcc, s55, v129
	s_nop 1
	v_cndmask_b32_e32 v129, v129, v224, vcc
	v_sqrt_f32_e32 v224, v129
	s_nop 0
	v_add_u32_e32 v225, -1, v224
	v_fma_f32 v227, -v225, v224, v129
	v_add_u32_e32 v226, 1, v224
	v_cmp_ge_f32_e64 s[18:19], 0, v227
	s_nop 1
	v_cndmask_b32_e64 v225, v224, v225, s[18:19]
	v_fma_f32 v224, -v226, v224, v129
	v_cmp_lt_f32_e64 s[18:19], 0, v224
	s_nop 1
	v_cndmask_b32_e64 v224, v225, v226, s[18:19]
	v_mul_f32_e32 v225, 0x37800000, v224
	v_cndmask_b32_e32 v224, v224, v225, vcc
	v_cmp_class_f32_e32 vcc, v129, v167
	s_nop 1
	v_cndmask_b32_e32 v129, v224, v129, vcc
	v_div_scale_f32 v224, s[18:19], v129, v129, 1.0
	v_rcp_f32_e32 v225, v224
	s_nop 0
	v_fma_f32 v226, -v224, v225, 1.0
	v_fmac_f32_e32 v225, v226, v225
	v_div_scale_f32 v226, vcc, 1.0, v129, 1.0
	v_mul_f32_e32 v227, v226, v225
	v_fma_f32 v228, -v224, v227, v226
	v_fmac_f32_e32 v227, v228, v225
	v_fma_f32 v224, -v224, v227, v226
	v_div_fmas_f32 v224, v224, v225, v227
	v_div_fixup_f32 v129, v224, v129, 1.0
	v_mul_f32_e32 v130, s22, v130
	v_mul_f32_e32 v131, s22, v131
	v_fma_f32 v131, -v130, v130, v131
	v_max_f32_e32 v131, 0, v131
	v_add_f32_e32 v131, 0x3727c5ac, v131
	v_mul_f32_e32 v224, 0x4f800000, v131
; __device__ __forceinline__ void build_tbl(const f32x2* PS, int pm, LAS unsigned char* lds, int wid, int lane) {
;     ...
;     for (int i = 0; i < 32; ++i) {
;         const f32x2 v = p[(size_t)i * 64];
;         const float a = wave_sum(v.x), b = wave_sum(v.y);
;         if (lane == 0) { const float mu = a * (1.f / DM), var = fmaxf(b * (1.f / DM) - mu * mu, 0.f); tbl[wid * 32 + i] = (f32x2){mu, 1.f / sqrtf(var + LN_EPS)}; }
;     }
	v_cmp_gt_f32_e32 vcc, s55, v131
	s_nop 1
	v_cndmask_b32_e32 v131, v131, v224, vcc
	v_sqrt_f32_e32 v224, v131
	s_nop 0
	v_add_u32_e32 v225, -1, v224
	v_fma_f32 v227, -v225, v224, v131
	v_add_u32_e32 v226, 1, v224
	v_cmp_ge_f32_e64 s[18:19], 0, v227
	s_nop 1
	v_cndmask_b32_e64 v225, v224, v225, s[18:19]
	v_fma_f32 v224, -v226, v224, v131
	v_cmp_lt_f32_e64 s[18:19], 0, v224
	s_nop 1
	v_cndmask_b32_e64 v224, v225, v226, s[18:19]
	v_mul_f32_e32 v225, 0x37800000, v224
	v_cndmask_b32_e32 v224, v224, v225, vcc
	v_cmp_class_f32_e32 vcc, v131, v167
	s_nop 1
	v_cndmask_b32_e32 v131, v224, v131, vcc
	v_div_scale_f32 v224, s[18:19], v131, v131, 1.0
	v_rcp_f32_e32 v225, v224
	s_nop 0
	v_fma_f32 v226, -v224, v225, 1.0
	v_fmac_f32_e32 v225, v226, v225
	v_div_scale_f32 v226, vcc, 1.0, v131, 1.0
	v_mul_f32_e32 v227, v226, v225
	v_fma_f32 v228, -v224, v227, v226
	v_fmac_f32_e32 v227, v228, v225
	v_fma_f32 v224, -v224, v227, v226
	v_div_fmas_f32 v224, v224, v225, v227
	v_div_fixup_f32 v131, v224, v131, 1.0
	v_mul_f32_e32 v132, s22, v132
	v_mul_f32_e32 v133, s22, v133
	v_fma_f32 v133, -v132, v132, v133
	v_max_f32_e32 v133, 0, v133
	v_add_f32_e32 v133, 0x3727c5ac, v133
	v_mul_f32_e32 v224, 0x4f800000, v133
	v_cmp_gt_f32_e32 vcc, s55, v133
	s_nop 1
	v_cndmask_b32_e32 v133, v133, v224, vcc
	v_sqrt_f32_e32 v224, v133
	s_nop 0
	v_add_u32_e32 v225, -1, v224
	v_fma_f32 v227, -v225, v224, v133
	v_add_u32_e32 v226, 1, v224
	v_cmp_ge_f32_e64 s[18:19], 0, v227
	s_nop 1
	v_cndmask_b32_e64 v225, v224, v225, s[18:19]
	v_fma_f32 v224, -v226, v224, v133
	v_cmp_lt_f32_e64 s[18:19], 0, v224
	s_nop 1
	v_cndmask_b32_e64 v224, v225, v226, s[18:19]
	v_mul_f32_e32 v225, 0x37800000, v224
	v_cndmask_b32_e32 v224, v224, v225, vcc
	v_cmp_class_f32_e32 vcc, v133, v167
	s_nop 1
	v_cndmask_b32_e32 v133, v224, v133, vcc
	v_div_scale_f32 v224, s[18:19], v133, v133, 1.0
	v_rcp_f32_e32 v225, v224
	s_nop 0
	v_fma_f32 v226, -v224, v225, 1.0
	v_fmac_f32_e32 v225, v226, v225
	v_div_scale_f32 v226, vcc, 1.0, v133, 1.0
	v_mul_f32_e32 v227, v226, v225
	v_fma_f32 v228, -v224, v227, v226
	v_fmac_f32_e32 v227, v228, v225
	v_fma_f32 v224, -v224, v227, v226
	v_div_fmas_f32 v224, v224, v225, v227
	v_div_fixup_f32 v133, v224, v133, 1.0
	v_mul_f32_e32 v134, s22, v134
	v_mul_f32_e32 v135, s22, v135
	v_fma_f32 v135, -v134, v134, v135
	v_max_f32_e32 v135, 0, v135
	v_add_f32_e32 v135, 0x3727c5ac, v135
	v_mul_f32_e32 v224, 0x4f800000, v135
	v_cmp_gt_f32_e32 vcc, s55, v135
	s_nop 1
	v_cndmask_b32_e32 v135, v135, v224, vcc
	v_sqrt_f32_e32 v224, v135
	s_nop 0
	v_add_u32_e32 v225, -1, v224
	v_fma_f32 v227, -v225, v224, v135
	v_add_u32_e32 v226, 1, v224
	v_cmp_ge_f32_e64 s[18:19], 0, v227
	s_nop 1
	v_cndmask_b32_e64 v225, v224, v225, s[18:19]
	v_fma_f32 v224, -v226, v224, v135
	v_cmp_lt_f32_e64 s[18:19], 0, v224
	s_nop 1
	v_cndmask_b32_e64 v224, v225, v226, s[18:19]
	v_mul_f32_e32 v225, 0x37800000, v224
	v_cndmask_b32_e32 v224, v224, v225, vcc
	v_cmp_class_f32_e32 vcc, v135, v167
	s_nop 1
	v_cndmask_b32_e32 v135, v224, v135, vcc
	v_div_scale_f32 v224, s[18:19], v135, v135, 1.0
	v_rcp_f32_e32 v225, v224
	s_nop 0
	v_fma_f32 v226, -v224, v225, 1.0
	v_fmac_f32_e32 v225, v226, v225
	v_div_scale_f32 v226, vcc, 1.0, v135, 1.0
	v_mul_f32_e32 v227, v226, v225
	v_fma_f32 v228, -v224, v227, v226
	v_fmac_f32_e32 v227, v228, v225
	v_fma_f32 v224, -v224, v227, v226
	v_div_fmas_f32 v224, v224, v225, v227
	v_div_fixup_f32 v135, v224, v135, 1.0
	v_mul_f32_e32 v136, s22, v136
	v_mul_f32_e32 v137, s22, v137
	v_fma_f32 v137, -v136, v136, v137
	v_max_f32_e32 v137, 0, v137
	v_add_f32_e32 v137, 0x3727c5ac, v137
	v_mul_f32_e32 v224, 0x4f800000, v137
	v_cmp_gt_f32_e32 vcc, s55, v137
	s_nop 1
	v_cndmask_b32_e32 v137, v137, v224, vcc
	v_sqrt_f32_e32 v224, v137
	s_nop 0
	v_add_u32_e32 v225, -1, v224
	v_fma_f32 v227, -v225, v224, v137
	v_add_u32_e32 v226, 1, v224
	v_cmp_ge_f32_e64 s[18:19], 0, v227
	s_nop 1
	v_cndmask_b32_e64 v225, v224, v225, s[18:19]
	v_fma_f32 v224, -v226, v224, v137
	v_cmp_lt_f32_e64 s[18:19], 0, v224
	s_nop 1
	v_cndmask_b32_e64 v224, v225, v226, s[18:19]
	v_mul_f32_e32 v225, 0x37800000, v224
	v_cndmask_b32_e32 v224, v224, v225, vcc
	v_cmp_class_f32_e32 vcc, v137, v167
	s_nop 1
	v_cndmask_b32_e32 v137, v224, v137, vcc
	v_div_scale_f32 v224, s[18:19], v137, v137, 1.0
	v_rcp_f32_e32 v225, v224
	s_nop 0
	v_fma_f32 v226, -v224, v225, 1.0
	v_fmac_f32_e32 v225, v226, v225
	v_div_scale_f32 v226, vcc, 1.0, v137, 1.0
; __device__ __forceinline__ void build_tbl(const f32x2* PS, int pm, LAS unsigned char* lds, int wid, int lane) {
;     ...
;     for (int i = 0; i < 32; ++i) {
;         const f32x2 v = p[(size_t)i * 64];
;         const float a = wave_sum(v.x), b = wave_sum(v.y);
;         if (lane == 0) { const float mu = a * (1.f / DM), var = fmaxf(b * (1.f / DM) - mu * mu, 0.f); tbl[wid * 32 + i] = (f32x2){mu, 1.f / sqrtf(var + LN_EPS)}; }
;     }
	v_mul_f32_e32 v227, v226, v225
	v_fma_f32 v228, -v224, v227, v226
	v_fmac_f32_e32 v227, v228, v225
	v_fma_f32 v224, -v224, v227, v226
	v_div_fmas_f32 v224, v224, v225, v227
	v_div_fixup_f32 v137, v224, v137, 1.0
	v_mul_f32_e32 v138, s22, v138
	v_mul_f32_e32 v139, s22, v139
	v_fma_f32 v139, -v138, v138, v139
	v_max_f32_e32 v139, 0, v139
	v_add_f32_e32 v139, 0x3727c5ac, v139
	v_mul_f32_e32 v224, 0x4f800000, v139
	v_cmp_gt_f32_e32 vcc, s55, v139
	s_nop 1
	v_cndmask_b32_e32 v139, v139, v224, vcc
	v_sqrt_f32_e32 v224, v139
	s_nop 0
	v_add_u32_e32 v225, -1, v224
	v_fma_f32 v227, -v225, v224, v139
	v_add_u32_e32 v226, 1, v224
	v_cmp_ge_f32_e64 s[18:19], 0, v227
	s_nop 1
	v_cndmask_b32_e64 v225, v224, v225, s[18:19]
	v_fma_f32 v224, -v226, v224, v139
	v_cmp_lt_f32_e64 s[18:19], 0, v224
	s_nop 1
	v_cndmask_b32_e64 v224, v225, v226, s[18:19]
	v_mul_f32_e32 v225, 0x37800000, v224
	v_cndmask_b32_e32 v224, v224, v225, vcc
	v_cmp_class_f32_e32 vcc, v139, v167
	s_nop 1
	v_cndmask_b32_e32 v139, v224, v139, vcc
	v_div_scale_f32 v224, s[18:19], v139, v139, 1.0
	v_rcp_f32_e32 v225, v224
	s_nop 0
	v_fma_f32 v226, -v224, v225, 1.0
	v_fmac_f32_e32 v225, v226, v225
	v_div_scale_f32 v226, vcc, 1.0, v139, 1.0
	v_mul_f32_e32 v227, v226, v225
	v_fma_f32 v228, -v224, v227, v226
	v_fmac_f32_e32 v227, v228, v225
	v_fma_f32 v224, -v224, v227, v226
	v_div_fmas_f32 v224, v224, v225, v227
	v_div_fixup_f32 v139, v224, v139, 1.0
	v_mul_f32_e32 v170, s22, v170
	v_mul_f32_e32 v171, s22, v171
	v_fma_f32 v171, -v170, v170, v171
	v_max_f32_e32 v171, 0, v171
	v_add_f32_e32 v171, 0x3727c5ac, v171
	v_mul_f32_e32 v224, 0x4f800000, v171
	v_cmp_gt_f32_e32 vcc, s55, v171
	s_nop 1
	v_cndmask_b32_e32 v171, v171, v224, vcc
	v_sqrt_f32_e32 v224, v171
	s_nop 0
	v_add_u32_e32 v225, -1, v224
	v_fma_f32 v227, -v225, v224, v171
	v_add_u32_e32 v226, 1, v224
	v_cmp_ge_f32_e64 s[18:19], 0, v227
	s_nop 1
	v_cndmask_b32_e64 v225, v224, v225, s[18:19]
	v_fma_f32 v224, -v226, v224, v171
	v_cmp_lt_f32_e64 s[18:19], 0, v224
	s_nop 1
	v_cndmask_b32_e64 v224, v225, v226, s[18:19]
	v_mul_f32_e32 v225, 0x37800000, v224
	v_cndmask_b32_e32 v224, v224, v225, vcc
	v_cmp_class_f32_e32 vcc, v171, v167
	s_nop 1
	v_cndmask_b32_e32 v171, v224, v171, vcc
	v_div_scale_f32 v224, s[18:19], v171, v171, 1.0
	v_rcp_f32_e32 v225, v224
	s_nop 0
	v_fma_f32 v226, -v224, v225, 1.0
	v_fmac_f32_e32 v225, v226, v225
	v_div_scale_f32 v226, vcc, 1.0, v171, 1.0
	v_mul_f32_e32 v227, v226, v225
	v_fma_f32 v228, -v224, v227, v226
	v_fmac_f32_e32 v227, v228, v225
	v_fma_f32 v224, -v224, v227, v226
	v_div_fmas_f32 v224, v224, v225, v227
	v_div_fixup_f32 v171, v224, v171, 1.0
	v_mul_f32_e32 v172, s22, v172
	v_mul_f32_e32 v173, s22, v173
	v_fma_f32 v173, -v172, v172, v173
	v_max_f32_e32 v173, 0, v173
	v_add_f32_e32 v173, 0x3727c5ac, v173
	v_mul_f32_e32 v224, 0x4f800000, v173
	v_cmp_gt_f32_e32 vcc, s55, v173
	s_nop 1
	v_cndmask_b32_e32 v173, v173, v224, vcc
	v_sqrt_f32_e32 v224, v173
	s_nop 0
	v_add_u32_e32 v225, -1, v224
	v_fma_f32 v227, -v225, v224, v173
	v_add_u32_e32 v226, 1, v224
	v_cmp_ge_f32_e64 s[18:19], 0, v227
	s_nop 1
	v_cndmask_b32_e64 v225, v224, v225, s[18:19]
	v_fma_f32 v224, -v226, v224, v173
	v_cmp_lt_f32_e64 s[18:19], 0, v224
	s_nop 1
	v_cndmask_b32_e64 v224, v225, v226, s[18:19]
	v_mul_f32_e32 v225, 0x37800000, v224
	v_cndmask_b32_e32 v224, v224, v225, vcc
	v_cmp_class_f32_e32 vcc, v173, v167
	s_nop 1
	v_cndmask_b32_e32 v173, v224, v173, vcc
	v_div_scale_f32 v224, s[18:19], v173, v173, 1.0
	v_rcp_f32_e32 v225, v224
	s_nop 0
	v_fma_f32 v226, -v224, v225, 1.0
	v_fmac_f32_e32 v225, v226, v225
	v_div_scale_f32 v226, vcc, 1.0, v173, 1.0
	v_mul_f32_e32 v227, v226, v225
	v_fma_f32 v228, -v224, v227, v226
	v_fmac_f32_e32 v227, v228, v225
	v_fma_f32 v224, -v224, v227, v226
	v_div_fmas_f32 v224, v224, v225, v227
	v_div_fixup_f32 v173, v224, v173, 1.0
	v_lshrrev_b32_e32 v229, 4, v168
	v_lshlrev_b32_e32 v229, 6, v229
	s_add_i32 s18, s52, 0x20400
	v_add_u32_e32 v229, s18, v229
	s_mov_b64 s[62:63], exec
	s_mov_b32 exec_lo, 0x10001
	s_mov_b32 exec_hi, 0x10001
	ds_write_b64 v229, v[128:129]
	ds_write_b64 v229, v[130:131] offset:8
	ds_write_b64 v229, v[132:133] offset:16
	ds_write_b64 v229, v[134:135] offset:24
	ds_write_b64 v229, v[136:137] offset:32
	ds_write_b64 v229, v[138:139] offset:40
	ds_write_b64 v229, v[170:171] offset:48
	ds_write_b64 v229, v[172:173] offset:56
	s_mov_b64 exec, s[62:63]

; #define LAS __attribute__((address_space(3)))
; #define EPI_OPAQUE(x) asm volatile("" : "+v"(x))
;     __device__ __forceinline__ float pre(const Unit& u, int tid) const { return (tid < 256 ? sv : tv)[u.pn * BM + (tid & 255)]; }
;     __device__ __forceinline__ float pre(const Unit& u, int tid) const { return (tid < 256 ? sv : tv)[u.pn * BM + (tid & 255)]; }
;     __device__ __forceinline__ void operator()(const f32x4 (&acc)[2][2][4][2], const Unit& u, int wr, int wc, int fr, int fq, const EpiCtx& X) const {
;         ensure_tbl(PS, sid, u.pm, X);
;         LAS float* stb = (LAS float*)(X.lds + STB_OFF);
;         stb[X.tid] = X.pre;
;         asm volatile("s_waitcnt lgkmcnt(0)" ::: "memory"); __builtin_amdgcn_s_barrier(); asm volatile("" ::: "memory");
;         const bool odd = fr & 1; const int fe = fr - (fr & 1), o32 = (fr & 1) * 32;
;         constexpr int RP = BLK ? 64 : LDC;
;         char* base = BLK ? (char*)(O + (size_t)u.pm * BM * LDC + (size_t)(u.pn * 4 + wc) * (BM * 64)) : (char*)(O + (size_t)u.pm * BM * LDC + u.pn * BM);
;         unsigned lo = (unsigned)((wr * 64 + fe) * RP + (BLK ? 0 : wc * 64) + o32 + 8 * fq) * 2u; EPI_OPAQUE(lo);
;         const LAS f32x2* tbl = (const LAS f32x2*)(X.lds + TBL_OFF) + wr * 64 + fe;
;         const LAS f32x4* sp = (const LAS f32x4*)(stb + wc * 64 + o32 + 8 * fq);
;         const f32x4 sa = sp[0], sb = sp[1], ta = sp[64], tb = sp[65];
;     ...
;         EPI_PIECES({ const unsigned off = lo + (unsigned)(rl * RP) * 2u; LN_ONE(p1a, p1b, rl, off); LN_ONE(p2a, p2b, rl + 1, off + RP * 2); })
.LBB0_714:
	v_cndmask_b32_e64 v171, v127, v119, s[14:15]
	v_cndmask_b32_e64 v172, v126, v118, s[14:15]
	v_cndmask_b32_e64 v173, v125, v117, s[14:15]
	v_cndmask_b32_e64 v174, v124, v116, s[14:15]
	v_mov_b32_e32 v180, 0
	v_mov_b32_e32 v181, 0
	v_mov_b32_e32 v178, 0
	v_mov_b32_e32 v179, 0
	v_mov_b32_dpp v180, v174 quad_perm:[1,0,3,2] row_mask:0xf bank_mask:0xf
	v_mov_b32_dpp v181, v173 quad_perm:[1,0,3,2] row_mask:0xf bank_mask:0xf
	v_mov_b32_dpp v178, v172 quad_perm:[1,0,3,2] row_mask:0xf bank_mask:0xf
	v_mov_b32_dpp v179, v171 quad_perm:[1,0,3,2] row_mask:0xf bank_mask:0xf
	v_cndmask_b32_e64 v171, v123, v115, s[14:15]
	v_cndmask_b32_e64 v172, v122, v114, s[14:15]
	v_cndmask_b32_e64 v173, v121, v113, s[14:15]
	v_cndmask_b32_e64 v174, v120, v112, s[14:15]
	v_mov_b32_e32 v182, 0
	v_mov_b32_e32 v183, 0
	v_mov_b32_e32 v184, 0
	v_mov_b32_e32 v185, 0
	s_waitcnt vmcnt(16)
	ds_write_b32 v162, v169
	v_mov_b32_e32 v170, v163
	v_mov_b32_dpp v182, v174 quad_perm:[1,0,3,2] row_mask:0xf bank_mask:0xf
	v_mov_b32_dpp v183, v173 quad_perm:[1,0,3,2] row_mask:0xf bank_mask:0xf
	v_mov_b32_dpp v184, v172 quad_perm:[1,0,3,2] row_mask:0xf bank_mask:0xf
	v_mov_b32_dpp v185, v171 quad_perm:[1,0,3,2] row_mask:0xf bank_mask:0xf
	s_waitcnt lgkmcnt(0)
	s_barrier
	s_waitcnt lgkmcnt(1)
	ds_read_b128 v[132:135], v165 offset:16
	ds_read_b128 v[136:139], v165 offset:1024
	ds_read_b128 v[128:131], v165 offset:1040
	v_cndmask_b32_e64 v173, v185, v123, s[14:15]
	v_cndmask_b32_e64 v172, v184, v122, s[14:15]
	v_cndmask_b32_e64 v175, v183, v121, s[14:15]
	v_cndmask_b32_e64 v174, v182, v120, s[14:15]
	ds_read_b128 v[120:123], v165
	ds_read_b64 v[176:177], v164
	v_cndmask_b32_e64 v125, v181, v125, s[14:15]
	v_cndmask_b32_e64 v124, v180, v124, s[14:15]
	v_cndmask_b32_e64 v127, v179, v127, s[14:15]
	v_cndmask_b32_e64 v126, v178, v126, s[14:15]
	v_cndmask_b32_e64 v179, v119, v179, s[14:15]
	v_cndmask_b32_e64 v178, v118, v178, s[14:15]
	v_cndmask_b32_e64 v181, v117, v181, s[14:15]
	v_cndmask_b32_e64 v180, v116, v180, s[14:15]
	s_waitcnt lgkmcnt(0)
	v_pk_fma_f32 v[118:119], v[120:121], v[176:177], v[124:125] op_sel_hi:[1,0,1] neg_lo:[1,0,0] neg_hi:[1,0,0]
	v_xor_b32_e32 v117, 0x80000000, v123
	v_xor_b32_e32 v116, 0x80000000, v122
	v_pk_fma_f32 v[122:123], v[116:117], v[176:177], v[126:127] op_sel_hi:[1,0,1]
	v_pk_fma_f32 v[124:125], v[176:177], v[118:119], v[136:137] op_sel:[1,0,0]
	v_pk_fma_f32 v[126:127], v[132:133], v[176:177], v[174:175] op_sel_hi:[1,0,1] neg_lo:[1,0,0] neg_hi:[1,0,0]
	v_xor_b32_e32 v119, 0x80000000, v135
	v_xor_b32_e32 v118, 0x80000000, v134
	v_pk_fma_f32 v[122:123], v[176:177], v[122:123], v[138:139] op_sel:[1,0,0]
	v_pk_fma_f32 v[134:135], v[118:119], v[176:177], v[172:173] op_sel_hi:[1,0,1]
	v_pk_fma_f32 v[126:127], v[176:177], v[126:127], v[128:129] op_sel:[1,0,0]
	s_lshl_b64 s[18:19], s[60:61], 23
	v_pk_fma_f32 v[134:135], v[176:177], v[134:135], v[130:131] op_sel:[1,0,0]
	v_max_f32_e32 v124, 0, v124
	v_max_f32_e32 v126, 0, v126
	v_max_f32_e32 v125, 0, v125
	v_max_f32_e32 v127, 0, v127
	v_max_f32_e32 v122, 0, v122
	s_add_u32 s25, s45, s18
	v_mul_f32_e32 v124, v124, v124
	v_mul_f32_e32 v126, v126, v126
	v_mul_f32_e32 v125, v125, v125
	v_mul_f32_e32 v127, v127, v127
	v_max_f32_e32 v134, 0, v134
	v_mul_f32_e32 v171, v122, v122
	v_max_f32_e32 v122, 0, v123
	v_max_f32_e32 v123, 0, v135
	s_addc_u32 s27, s46, s19
	s_lshl_b32 s18, s68, 2
	v_mul_f32_e32 v134, v134, v134
	v_mul_f32_e32 v135, v122, v122
	v_mul_f32_e32 v172, v123, v123
	v_cvt_pk_bf16_f32 v122, v124, v125
	v_cvt_pk_bf16_f32 v123, v171, v135
	v_cvt_pk_bf16_f32 v124, v126, v127
	v_cvt_pk_bf16_f32 v125, v134, v172
	ds_read_b64 v[126:127], v164 offset:8
	s_or_b32 s18, s18, s41
	s_ashr_i32 s19, s18, 31
	s_lshl_b64 s[18:19], s[18:19], 15
	s_add_u32 s18, s25, s18
	v_cndmask_b32_e64 v113, v113, v183, s[14:15]
	v_cndmask_b32_e64 v112, v112, v182, s[14:15]
	s_addc_u32 s19, s27, s19
	v_cndmask_b32_e64 v115, v115, v185, s[14:15]
	v_cndmask_b32_e64 v114, v114, v184, s[14:15]
	s_waitcnt lgkmcnt(0)
	v_pk_fma_f32 v[112:113], v[132:133], v[126:127], v[112:113] op_sel_hi:[1,0,1] neg_lo:[1,0,0] neg_hi:[1,0,0]
	global_store_dwordx4 v170, v[122:125], s[18:19] nt
	v_pk_fma_f32 v[114:115], v[118:119], v[126:127], v[114:115] op_sel_hi:[1,0,1]
	v_pk_fma_f32 v[112:113], v[126:127], v[112:113], v[128:129] op_sel:[1,0,0]
	v_pk_fma_f32 v[122:123], v[120:121], v[126:127], v[180:181] op_sel_hi:[1,0,1] neg_lo:[1,0,0] neg_hi:[1,0,0]
	v_pk_fma_f32 v[124:125], v[116:117], v[126:127], v[178:179] op_sel_hi:[1,0,1]
	v_pk_fma_f32 v[122:123], v[126:127], v[122:123], v[136:137] op_sel:[1,0,0]
	v_pk_fma_f32 v[124:125], v[126:127], v[124:125], v[138:139] op_sel:[1,0,0]
	v_pk_fma_f32 v[114:115], v[126:127], v[114:115], v[130:131] op_sel:[1,0,0]
	v_max_f32_e32 v112, 0, v112
	v_max_f32_e32 v113, 0, v113
	v_max_f32_e32 v122, 0, v122
	v_mul_f32_e32 v126, v112, v112
	v_max_f32_e32 v112, 0, v123
	v_mul_f32_e32 v123, v113, v113
	v_max_f32_e32 v113, 0, v124
	v_max_f32_e32 v114, 0, v114
	v_mul_f32_e32 v122, v122, v122
	v_mul_f32_e32 v112, v112, v112
	v_mul_f32_e32 v113, v113, v113
	v_mul_f32_e32 v124, v114, v114
	v_max_f32_e32 v114, 0, v125
	v_max_f32_e32 v115, 0, v115
	v_mul_f32_e32 v114, v114, v114
	v_mul_f32_e32 v115, v115, v115
	v_cvt_pk_bf16_f32 v112, v122, v112
	v_cvt_pk_bf16_f32 v113, v113, v114
	v_add_u32_e32 v122, 0x80, v170
	v_cvt_pk_bf16_f32 v114, v126, v123
	v_cvt_pk_bf16_f32 v115, v124, v115
	global_store_dwordx4 v122, v[112:115], s[18:19] nt
	ds_read_b64 v[112:113], v164 offset:128
	v_cndmask_b32_e64 v123, v108, v100, s[14:15]
	v_mov_b32_e32 v124, 0
	v_cndmask_b32_e64 v127, v104, v96, s[14:15]
	v_mov_b32_e32 v134, 0
	v_cndmask_b32_e64 v122, v109, v101, s[14:15]
	v_mov_b32_dpp v124, v123 quad_perm:[1,0,3,2] row_mask:0xf bank_mask:0xf
	v_mov_b32_e32 v123, 0
	v_cndmask_b32_e64 v126, v105, v97, s[14:15]
	v_mov_b32_dpp v134, v127 quad_perm:[1,0,3,2] row_mask:0xf bank_mask:0xf
	v_mov_b32_e32 v127, 0
	v_cndmask_b32_e64 v115, v110, v102, s[14:15]
	v_mov_b32_dpp v123, v122 quad_perm:[1,0,3,2] row_mask:0xf bank_mask:0xf
	v_mov_b32_e32 v122, 0
	v_mov_b32_dpp v127, v126 quad_perm:[1,0,3,2] row_mask:0xf bank_mask:0xf
	v_cndmask_b32_e64 v114, v111, v103, s[14:15]
	v_mov_b32_dpp v122, v115 quad_perm:[1,0,3,2] row_mask:0xf bank_mask:0xf
	v_mov_b32_e32 v115, 0
	v_cndmask_b32_e64 v125, v106, v98, s[14:15]
	v_mov_b32_e32 v126, 0
	v_cndmask_b32_e64 v105, v127, v105, s[14:15]
	v_cndmask_b32_e64 v104, v134, v104, s[14:15]
	v_mov_b32_dpp v115, v114 quad_perm:[1,0,3,2] row_mask:0xf bank_mask:0xf
	v_cndmask_b32_e64 v114, v107, v99, s[14:15]
	v_mov_b32_dpp v126, v125 quad_perm:[1,0,3,2] row_mask:0xf bank_mask:0xf
	v_mov_b32_e32 v125, 0
	s_waitcnt lgkmcnt(0)
;     __device__ __forceinline__ void operator()(const f32x4 (&acc)[2][2][4][2], const Unit& u, int wr, int wc, int fr, int fq, const EpiCtx& X) const {
;     ...
;         EPI_PIECES({ const unsigned off = lo + (unsigned)(rl * RP) * 2u; LN_ONE(p1a, p1b, rl, off); LN_ONE(p2a, p2b, rl + 1, off + RP * 2); })
	v_pk_fma_f32 v[104:105], v[132:133], v[112:113], v[104:105] op_sel_hi:[1,0,1] neg_lo:[1,0,0] neg_hi:[1,0,0]
	v_cndmask_b32_e64 v111, v115, v111, s[14:15]
	v_mov_b32_dpp v125, v114 quad_perm:[1,0,3,2] row_mask:0xf bank_mask:0xf
	v_cndmask_b32_e64 v110, v122, v110, s[14:15]
	v_cndmask_b32_e64 v109, v123, v109, s[14:15]
	v_cndmask_b32_e64 v108, v124, v108, s[14:15]
	v_pk_fma_f32 v[104:105], v[112:113], v[104:105], v[128:129] op_sel:[1,0,0]
	v_cndmask_b32_e64 v107, v125, v107, s[14:15]
	v_cndmask_b32_e64 v106, v126, v106, s[14:15]
	v_cndmask_b32_e64 v103, v103, v115, s[14:15]
	v_cndmask_b32_e64 v115, v101, v123, s[14:15]
	v_cndmask_b32_e64 v114, v100, v124, s[14:15]
	v_pk_fma_f32 v[100:101], v[120:121], v[112:113], v[108:109] op_sel_hi:[1,0,1] neg_lo:[1,0,0] neg_hi:[1,0,0]
	v_pk_fma_f32 v[108:109], v[116:117], v[112:113], v[110:111] op_sel_hi:[1,0,1]
	v_max_f32_e32 v104, 0, v104
	v_pk_fma_f32 v[108:109], v[112:113], v[108:109], v[138:139] op_sel:[1,0,0]
	v_pk_fma_f32 v[106:107], v[118:119], v[112:113], v[106:107] op_sel_hi:[1,0,1]
	v_mul_f32_e32 v110, v104, v104
	v_max_f32_e32 v104, 0, v105
	v_pk_fma_f32 v[100:101], v[112:113], v[100:101], v[136:137] op_sel:[1,0,0]
	v_pk_fma_f32 v[106:107], v[112:113], v[106:107], v[130:131] op_sel:[1,0,0]
	v_mul_f32_e32 v111, v104, v104
	v_max_f32_e32 v104, 0, v108
	v_max_f32_e32 v100, 0, v100
	v_max_f32_e32 v101, 0, v101
	v_max_f32_e32 v105, 0, v106
	v_mul_f32_e32 v106, v104, v104
	v_max_f32_e32 v104, 0, v109
	v_mul_f32_e32 v100, v100, v100
	v_mul_f32_e32 v101, v101, v101
	v_mul_f32_e32 v108, v105, v105
	v_max_f32_e32 v105, 0, v107
	v_mul_f32_e32 v107, v104, v104
	v_mul_f32_e32 v109, v105, v105
	v_cndmask_b32_e64 v105, v99, v125, s[14:15]
	v_cndmask_b32_e64 v104, v98, v126, s[14:15]
	v_cvt_pk_bf16_f32 v98, v100, v101
	v_cvt_pk_bf16_f32 v99, v106, v107
	v_cvt_pk_bf16_f32 v100, v110, v111
	v_cvt_pk_bf16_f32 v101, v108, v109
	ds_read_b64 v[106:107], v164 offset:136
	v_cndmask_b32_e64 v97, v97, v127, s[14:15]
	v_cndmask_b32_e64 v96, v96, v134, s[14:15]
	v_cndmask_b32_e64 v102, v102, v122, s[14:15]
	v_add_u32_e32 v108, 0x800, v170
	s_waitcnt lgkmcnt(0)
	v_pk_fma_f32 v[96:97], v[132:133], v[106:107], v[96:97] op_sel_hi:[1,0,1] neg_lo:[1,0,0] neg_hi:[1,0,0]
	global_store_dwordx4 v108, v[98:101], s[18:19] nt
	v_pk_fma_f32 v[96:97], v[106:107], v[96:97], v[128:129] op_sel:[1,0,0]
	s_andn2_b64 vcc, exec, s[16:17]
	v_pk_fma_f32 v[98:99], v[120:121], v[106:107], v[114:115] op_sel_hi:[1,0,1] neg_lo:[1,0,0] neg_hi:[1,0,0]
	v_pk_fma_f32 v[100:101], v[116:117], v[106:107], v[102:103] op_sel_hi:[1,0,1]
	v_pk_fma_f32 v[102:103], v[118:119], v[106:107], v[104:105] op_sel_hi:[1,0,1]
	v_pk_fma_f32 v[100:101], v[106:107], v[100:101], v[138:139] op_sel:[1,0,0]
	v_pk_fma_f32 v[98:99], v[106:107], v[98:99], v[136:137] op_sel:[1,0,0]
	v_pk_fma_f32 v[102:103], v[106:107], v[102:103], v[130:131] op_sel:[1,0,0]
	v_max_f32_e32 v96, 0, v96
	v_max_f32_e32 v97, 0, v97
	v_max_f32_e32 v98, 0, v98
	v_mul_f32_e32 v104, v96, v96
	v_max_f32_e32 v96, 0, v99
	v_mul_f32_e32 v99, v97, v97
	v_max_f32_e32 v97, 0, v100
	v_max_f32_e32 v100, 0, v102
	v_mul_f32_e32 v98, v98, v98
	v_mul_f32_e32 v96, v96, v96
	v_mul_f32_e32 v97, v97, v97
	v_mul_f32_e32 v100, v100, v100
	v_max_f32_e32 v101, 0, v101
	v_max_f32_e32 v102, 0, v103
	v_mul_f32_e32 v101, v101, v101
	v_mul_f32_e32 v102, v102, v102
	v_cvt_pk_bf16_f32 v96, v98, v96
	v_cvt_pk_bf16_f32 v97, v97, v101
	v_cvt_pk_bf16_f32 v98, v104, v99
	v_cvt_pk_bf16_f32 v99, v100, v102
	v_add_u32_e32 v100, 0x880, v170
	global_store_dwordx4 v100, v[96:99], s[18:19] nt
	v_mov_b32_e32 v100, 0
	v_cndmask_b32_e64 v103, v88, v80, s[14:15]
	v_cndmask_b32_e64 v99, v92, v84, s[14:15]
	v_cndmask_b32_e64 v98, v93, v85, s[14:15]
	v_mov_b32_e32 v104, 0
	v_mov_b32_dpp v100, v99 quad_perm:[1,0,3,2] row_mask:0xf bank_mask:0xf
	v_mov_b32_e32 v99, 0
	v_cndmask_b32_e64 v96, v95, v87, s[14:15]
	v_cndmask_b32_e64 v97, v94, v86, s[14:15]
	v_mov_b32_dpp v99, v98 quad_perm:[1,0,3,2] row_mask:0xf bank_mask:0xf
	v_mov_b32_e32 v98, 0
	v_mov_b32_e32 v101, 0
	v_cndmask_b32_e64 v102, v89, v81, s[14:15]
	v_mov_b32_dpp v104, v103 quad_perm:[1,0,3,2] row_mask:0xf bank_mask:0xf
	v_mov_b32_e32 v103, 0
	v_mov_b32_dpp v98, v97 quad_perm:[1,0,3,2] row_mask:0xf bank_mask:0xf
	v_mov_b32_dpp v101, v96 quad_perm:[1,0,3,2] row_mask:0xf bank_mask:0xf
	v_cndmask_b32_e64 v96, v91, v83, s[14:15]
	v_cndmask_b32_e64 v97, v90, v82, s[14:15]
	v_mov_b32_dpp v103, v102 quad_perm:[1,0,3,2] row_mask:0xf bank_mask:0xf
	v_mov_b32_e32 v102, 0
	v_mov_b32_e32 v105, 0
	v_cndmask_b32_e64 v89, v103, v89, s[14:15]
	v_mov_b32_dpp v102, v97 quad_perm:[1,0,3,2] row_mask:0xf bank_mask:0xf
	v_mov_b32_dpp v105, v96 quad_perm:[1,0,3,2] row_mask:0xf bank_mask:0xf
	ds_read_b64 v[96:97], v164 offset:256
	v_cndmask_b32_e64 v88, v104, v88, s[14:15]
	v_cndmask_b32_e64 v95, v101, v95, s[14:15]
	v_cndmask_b32_e64 v94, v98, v94, s[14:15]
	v_cndmask_b32_e64 v93, v99, v93, s[14:15]
	s_waitcnt lgkmcnt(0)
;     __device__ __forceinline__ void operator()(const f32x4 (&acc)[2][2][4][2], const Unit& u, int wr, int wc, int fr, int fq, const EpiCtx& X) const {
;     ...
;         EPI_PIECES({ const unsigned off = lo + (unsigned)(rl * RP) * 2u; LN_ONE(p1a, p1b, rl, off); LN_ONE(p2a, p2b, rl + 1, off + RP * 2); })
	v_pk_fma_f32 v[88:89], v[132:133], v[96:97], v[88:89] op_sel_hi:[1,0,1] neg_lo:[1,0,0] neg_hi:[1,0,0]
	v_cndmask_b32_e64 v92, v100, v92, s[14:15]
	v_pk_fma_f32 v[88:89], v[96:97], v[88:89], v[128:129] op_sel:[1,0,0]
	v_cndmask_b32_e64 v91, v105, v91, s[14:15]
	v_cndmask_b32_e64 v90, v102, v90, s[14:15]
	v_cndmask_b32_e64 v86, v86, v98, s[14:15]
	v_cndmask_b32_e64 v99, v85, v99, s[14:15]
	v_cndmask_b32_e64 v98, v84, v100, s[14:15]
	v_pk_fma_f32 v[84:85], v[120:121], v[96:97], v[92:93] op_sel_hi:[1,0,1] neg_lo:[1,0,0] neg_hi:[1,0,0]
	v_pk_fma_f32 v[92:93], v[116:117], v[96:97], v[94:95] op_sel_hi:[1,0,1]
	v_max_f32_e32 v88, 0, v88
	v_pk_fma_f32 v[92:93], v[96:97], v[92:93], v[138:139] op_sel:[1,0,0]
	v_pk_fma_f32 v[90:91], v[118:119], v[96:97], v[90:91] op_sel_hi:[1,0,1]
	v_mul_f32_e32 v94, v88, v88
	v_max_f32_e32 v88, 0, v89
	v_pk_fma_f32 v[84:85], v[96:97], v[84:85], v[136:137] op_sel:[1,0,0]
	v_pk_fma_f32 v[90:91], v[96:97], v[90:91], v[130:131] op_sel:[1,0,0]
	v_mul_f32_e32 v95, v88, v88
	v_max_f32_e32 v88, 0, v92
	v_max_f32_e32 v84, 0, v84
	v_max_f32_e32 v85, 0, v85
	v_max_f32_e32 v89, 0, v90
	v_mul_f32_e32 v90, v88, v88
	v_max_f32_e32 v88, 0, v93
	v_mul_f32_e32 v84, v84, v84
	v_mul_f32_e32 v85, v85, v85
	v_mul_f32_e32 v92, v89, v89
	v_max_f32_e32 v89, 0, v91
	v_mul_f32_e32 v91, v88, v88
	v_mul_f32_e32 v93, v89, v89
	v_cndmask_b32_e64 v89, v83, v105, s[14:15]
	v_cndmask_b32_e64 v88, v82, v102, s[14:15]
	v_cvt_pk_bf16_f32 v82, v84, v85
	v_cvt_pk_bf16_f32 v83, v90, v91
	v_cvt_pk_bf16_f32 v84, v94, v95
	v_cvt_pk_bf16_f32 v85, v92, v93
	ds_read_b64 v[90:91], v164 offset:264
	v_cndmask_b32_e64 v81, v81, v103, s[14:15]
	v_cndmask_b32_e64 v80, v80, v104, s[14:15]
	v_cndmask_b32_e64 v87, v87, v101, s[14:15]
	v_add_u32_e32 v92, 0x1000, v170
	s_waitcnt lgkmcnt(0)
	v_pk_fma_f32 v[80:81], v[132:133], v[90:91], v[80:81] op_sel_hi:[1,0,1] neg_lo:[1,0,0] neg_hi:[1,0,0]
	global_store_dwordx4 v92, v[82:85], s[18:19] nt
	v_pk_fma_f32 v[80:81], v[90:91], v[80:81], v[128:129] op_sel:[1,0,0]
	s_mov_b64 s[16:17], -1
	v_pk_fma_f32 v[82:83], v[120:121], v[90:91], v[98:99] op_sel_hi:[1,0,1] neg_lo:[1,0,0] neg_hi:[1,0,0]
	v_pk_fma_f32 v[84:85], v[116:117], v[90:91], v[86:87] op_sel_hi:[1,0,1]
	v_pk_fma_f32 v[86:87], v[118:119], v[90:91], v[88:89] op_sel_hi:[1,0,1]
	v_pk_fma_f32 v[84:85], v[90:91], v[84:85], v[138:139] op_sel:[1,0,0]
	v_pk_fma_f32 v[82:83], v[90:91], v[82:83], v[136:137] op_sel:[1,0,0]
	v_pk_fma_f32 v[86:87], v[90:91], v[86:87], v[130:131] op_sel:[1,0,0]
	v_max_f32_e32 v80, 0, v80
	v_max_f32_e32 v81, 0, v81
	v_max_f32_e32 v82, 0, v82
	v_mul_f32_e32 v88, v80, v80
	v_max_f32_e32 v80, 0, v83
	v_mul_f32_e32 v83, v81, v81
	v_max_f32_e32 v81, 0, v84
	v_max_f32_e32 v84, 0, v86
	v_mul_f32_e32 v82, v82, v82
	v_mul_f32_e32 v80, v80, v80
	v_mul_f32_e32 v81, v81, v81
	v_mul_f32_e32 v84, v84, v84
	v_max_f32_e32 v85, 0, v85
	v_max_f32_e32 v86, 0, v87
	v_mul_f32_e32 v85, v85, v85
	v_mul_f32_e32 v86, v86, v86
	v_cvt_pk_bf16_f32 v80, v82, v80
	v_cvt_pk_bf16_f32 v81, v81, v85
	v_cvt_pk_bf16_f32 v82, v88, v83
	v_cvt_pk_bf16_f32 v83, v84, v86
	v_add_u32_e32 v84, 0x1080, v170
	global_store_dwordx4 v84, v[80:83], s[18:19] nt
	ds_read_b64 v[80:81], v164 offset:384
	v_cndmask_b32_e64 v85, v76, v68, s[14:15]
	v_mov_b32_e32 v86, 0
	v_cndmask_b32_e64 v89, v72, v64, s[14:15]
	v_mov_b32_e32 v90, 0
	v_cndmask_b32_e64 v84, v77, v69, s[14:15]
	v_mov_b32_dpp v86, v85 quad_perm:[1,0,3,2] row_mask:0xf bank_mask:0xf
	v_mov_b32_e32 v85, 0
	v_cndmask_b32_e64 v88, v73, v65, s[14:15]
	v_mov_b32_dpp v90, v89 quad_perm:[1,0,3,2] row_mask:0xf bank_mask:0xf
	v_mov_b32_e32 v89, 0
	v_cndmask_b32_e64 v83, v78, v70, s[14:15]
	v_mov_b32_dpp v85, v84 quad_perm:[1,0,3,2] row_mask:0xf bank_mask:0xf
	v_mov_b32_e32 v84, 0
	v_mov_b32_dpp v89, v88 quad_perm:[1,0,3,2] row_mask:0xf bank_mask:0xf
	v_cndmask_b32_e64 v82, v79, v71, s[14:15]
	v_mov_b32_dpp v84, v83 quad_perm:[1,0,3,2] row_mask:0xf bank_mask:0xf
	v_mov_b32_e32 v83, 0
	v_cndmask_b32_e64 v87, v74, v66, s[14:15]
	v_mov_b32_e32 v88, 0
	v_cndmask_b32_e64 v73, v89, v73, s[14:15]
	v_cndmask_b32_e64 v72, v90, v72, s[14:15]
	v_mov_b32_dpp v83, v82 quad_perm:[1,0,3,2] row_mask:0xf bank_mask:0xf
	v_cndmask_b32_e64 v82, v75, v67, s[14:15]
	v_mov_b32_dpp v88, v87 quad_perm:[1,0,3,2] row_mask:0xf bank_mask:0xf
	v_mov_b32_e32 v87, 0
	s_waitcnt lgkmcnt(0)
	v_pk_fma_f32 v[72:73], v[132:133], v[80:81], v[72:73] op_sel_hi:[1,0,1] neg_lo:[1,0,0] neg_hi:[1,0,0]
	v_cndmask_b32_e64 v79, v83, v79, s[14:15]
	v_mov_b32_dpp v87, v82 quad_perm:[1,0,3,2] row_mask:0xf bank_mask:0xf
	v_cndmask_b32_e64 v78, v84, v78, s[14:15]
	v_cndmask_b32_e64 v77, v85, v77, s[14:15]
	v_cndmask_b32_e64 v76, v86, v76, s[14:15]
	v_pk_fma_f32 v[72:73], v[80:81], v[72:73], v[128:129] op_sel:[1,0,0]
	v_cndmask_b32_e64 v75, v87, v75, s[14:15]
	v_cndmask_b32_e64 v74, v88, v74, s[14:15]
	v_cndmask_b32_e64 v71, v71, v83, s[14:15]
	v_cndmask_b32_e64 v83, v69, v85, s[14:15]
	v_cndmask_b32_e64 v82, v68, v86, s[14:15]
	v_pk_fma_f32 v[68:69], v[120:121], v[80:81], v[76:77] op_sel_hi:[1,0,1] neg_lo:[1,0,0] neg_hi:[1,0,0]
	v_pk_fma_f32 v[76:77], v[116:117], v[80:81], v[78:79] op_sel_hi:[1,0,1]
	v_max_f32_e32 v72, 0, v72
	v_pk_fma_f32 v[76:77], v[80:81], v[76:77], v[138:139] op_sel:[1,0,0]
	v_pk_fma_f32 v[74:75], v[118:119], v[80:81], v[74:75] op_sel_hi:[1,0,1]
	v_mul_f32_e32 v78, v72, v72
	v_max_f32_e32 v72, 0, v73
	v_pk_fma_f32 v[68:69], v[80:81], v[68:69], v[136:137] op_sel:[1,0,0]
	v_pk_fma_f32 v[74:75], v[80:81], v[74:75], v[130:131] op_sel:[1,0,0]
	v_mul_f32_e32 v79, v72, v72
	v_max_f32_e32 v72, 0, v76
	v_max_f32_e32 v68, 0, v68
	v_max_f32_e32 v69, 0, v69
	v_max_f32_e32 v73, 0, v74
	v_mul_f32_e32 v74, v72, v72
	v_max_f32_e32 v72, 0, v77
	v_mul_f32_e32 v68, v68, v68
	v_mul_f32_e32 v69, v69, v69
	v_mul_f32_e32 v76, v73, v73
	v_max_f32_e32 v73, 0, v75
	v_mul_f32_e32 v75, v72, v72
	v_mul_f32_e32 v77, v73, v73
	v_cndmask_b32_e64 v73, v67, v87, s[14:15]
	v_cndmask_b32_e64 v72, v66, v88, s[14:15]
	v_cvt_pk_bf16_f32 v66, v68, v69
	v_cvt_pk_bf16_f32 v67, v74, v75
	v_cvt_pk_bf16_f32 v68, v78, v79
	v_cvt_pk_bf16_f32 v69, v76, v77
	ds_read_b64 v[74:75], v164 offset:392
	v_cndmask_b32_e64 v65, v65, v89, s[14:15]
	v_cndmask_b32_e64 v64, v64, v90, s[14:15]
	v_cndmask_b32_e64 v70, v70, v84, s[14:15]
	v_add_u32_e32 v76, 0x1800, v170
	s_waitcnt lgkmcnt(0)
;     __device__ __forceinline__ void operator()(const f32x4 (&acc)[2][2][4][2], const Unit& u, int wr, int wc, int fr, int fq, const EpiCtx& X) const {
;     ...
;         EPI_PIECES({ const unsigned off = lo + (unsigned)(rl * RP) * 2u; LN_ONE(p1a, p1b, rl, off); LN_ONE(p2a, p2b, rl + 1, off + RP * 2); })
	v_pk_fma_f32 v[64:65], v[132:133], v[74:75], v[64:65] op_sel_hi:[1,0,1] neg_lo:[1,0,0] neg_hi:[1,0,0]
	global_store_dwordx4 v76, v[66:69], s[18:19] nt
	v_pk_fma_f32 v[64:65], v[74:75], v[64:65], v[128:129] op_sel:[1,0,0]
	s_nop 0
	v_pk_fma_f32 v[66:67], v[120:121], v[74:75], v[82:83] op_sel_hi:[1,0,1] neg_lo:[1,0,0] neg_hi:[1,0,0]
	v_pk_fma_f32 v[68:69], v[116:117], v[74:75], v[70:71] op_sel_hi:[1,0,1]
	v_pk_fma_f32 v[70:71], v[118:119], v[74:75], v[72:73] op_sel_hi:[1,0,1]
	v_pk_fma_f32 v[68:69], v[74:75], v[68:69], v[138:139] op_sel:[1,0,0]
	v_pk_fma_f32 v[66:67], v[74:75], v[66:67], v[136:137] op_sel:[1,0,0]
	v_pk_fma_f32 v[70:71], v[74:75], v[70:71], v[130:131] op_sel:[1,0,0]
	v_max_f32_e32 v64, 0, v64
	v_max_f32_e32 v65, 0, v65
	v_max_f32_e32 v66, 0, v66
	v_mul_f32_e32 v72, v64, v64
	v_max_f32_e32 v64, 0, v67
	v_mul_f32_e32 v67, v65, v65
	v_max_f32_e32 v65, 0, v68
	v_max_f32_e32 v68, 0, v70
	v_mul_f32_e32 v66, v66, v66
	v_mul_f32_e32 v64, v64, v64
	v_mul_f32_e32 v65, v65, v65
	v_mul_f32_e32 v68, v68, v68
	v_max_f32_e32 v69, 0, v69
	v_max_f32_e32 v70, 0, v71
	v_mul_f32_e32 v69, v69, v69
	v_mul_f32_e32 v70, v70, v70
	v_cvt_pk_bf16_f32 v64, v66, v64
	v_cvt_pk_bf16_f32 v65, v65, v69
	v_cvt_pk_bf16_f32 v66, v72, v67
	v_cvt_pk_bf16_f32 v67, v68, v70
	v_add_u32_e32 v68, 0x1880, v170
	global_store_dwordx4 v68, v[64:67], s[18:19] nt
	v_mov_b32_e32 v68, 0
	v_cndmask_b32_e64 v71, v56, v48, s[14:15]
	v_cndmask_b32_e64 v67, v60, v52, s[14:15]
	v_cndmask_b32_e64 v66, v61, v53, s[14:15]
	v_mov_b32_e32 v72, 0
	v_mov_b32_dpp v68, v67 quad_perm:[1,0,3,2] row_mask:0xf bank_mask:0xf
	v_mov_b32_e32 v67, 0
	v_cndmask_b32_e64 v64, v63, v55, s[14:15]
	v_cndmask_b32_e64 v65, v62, v54, s[14:15]
	v_mov_b32_dpp v67, v66 quad_perm:[1,0,3,2] row_mask:0xf bank_mask:0xf
	v_mov_b32_e32 v66, 0
	v_mov_b32_e32 v69, 0
	v_cndmask_b32_e64 v70, v57, v49, s[14:15]
	v_mov_b32_dpp v72, v71 quad_perm:[1,0,3,2] row_mask:0xf bank_mask:0xf
	v_mov_b32_e32 v71, 0
	v_mov_b32_dpp v66, v65 quad_perm:[1,0,3,2] row_mask:0xf bank_mask:0xf
	v_mov_b32_dpp v69, v64 quad_perm:[1,0,3,2] row_mask:0xf bank_mask:0xf
	v_cndmask_b32_e64 v64, v59, v51, s[14:15]
	v_cndmask_b32_e64 v65, v58, v50, s[14:15]
	v_mov_b32_dpp v71, v70 quad_perm:[1,0,3,2] row_mask:0xf bank_mask:0xf
	v_mov_b32_e32 v70, 0
	v_mov_b32_e32 v73, 0
	v_cndmask_b32_e64 v57, v71, v57, s[14:15]
	v_mov_b32_dpp v70, v65 quad_perm:[1,0,3,2] row_mask:0xf bank_mask:0xf
	v_mov_b32_dpp v73, v64 quad_perm:[1,0,3,2] row_mask:0xf bank_mask:0xf
	ds_read_b64 v[64:65], v164 offset:1024
	v_cndmask_b32_e64 v56, v72, v56, s[14:15]
	v_cndmask_b32_e64 v63, v69, v63, s[14:15]
	v_cndmask_b32_e64 v62, v66, v62, s[14:15]
	v_cndmask_b32_e64 v61, v67, v61, s[14:15]
	s_waitcnt lgkmcnt(0)
	v_pk_fma_f32 v[56:57], v[132:133], v[64:65], v[56:57] op_sel_hi:[1,0,1] neg_lo:[1,0,0] neg_hi:[1,0,0]
	v_cndmask_b32_e64 v60, v68, v60, s[14:15]
	v_pk_fma_f32 v[56:57], v[64:65], v[56:57], v[128:129] op_sel:[1,0,0]
	v_cndmask_b32_e64 v59, v73, v59, s[14:15]
	v_cndmask_b32_e64 v58, v70, v58, s[14:15]
	v_cndmask_b32_e64 v54, v54, v66, s[14:15]
	v_cndmask_b32_e64 v67, v53, v67, s[14:15]
	v_cndmask_b32_e64 v66, v52, v68, s[14:15]
	v_pk_fma_f32 v[52:53], v[120:121], v[64:65], v[60:61] op_sel_hi:[1,0,1] neg_lo:[1,0,0] neg_hi:[1,0,0]
	v_pk_fma_f32 v[60:61], v[116:117], v[64:65], v[62:63] op_sel_hi:[1,0,1]
	v_max_f32_e32 v56, 0, v56
	v_pk_fma_f32 v[60:61], v[64:65], v[60:61], v[138:139] op_sel:[1,0,0]
	v_pk_fma_f32 v[58:59], v[118:119], v[64:65], v[58:59] op_sel_hi:[1,0,1]
	v_mul_f32_e32 v62, v56, v56
	v_max_f32_e32 v56, 0, v57
	v_pk_fma_f32 v[52:53], v[64:65], v[52:53], v[136:137] op_sel:[1,0,0]
	v_pk_fma_f32 v[58:59], v[64:65], v[58:59], v[130:131] op_sel:[1,0,0]
	v_mul_f32_e32 v63, v56, v56
	v_max_f32_e32 v56, 0, v60
	v_max_f32_e32 v52, 0, v52
	v_max_f32_e32 v53, 0, v53
	v_max_f32_e32 v57, 0, v58
	v_mul_f32_e32 v58, v56, v56
	v_max_f32_e32 v56, 0, v61
	v_mul_f32_e32 v52, v52, v52
	v_mul_f32_e32 v53, v53, v53
	v_mul_f32_e32 v60, v57, v57
	v_max_f32_e32 v57, 0, v59
	v_mul_f32_e32 v59, v56, v56
	v_mul_f32_e32 v61, v57, v57
	v_cndmask_b32_e64 v57, v51, v73, s[14:15]
	v_cndmask_b32_e64 v56, v50, v70, s[14:15]
	v_cvt_pk_bf16_f32 v50, v52, v53
	v_cvt_pk_bf16_f32 v51, v58, v59
	v_cvt_pk_bf16_f32 v52, v62, v63
	v_cvt_pk_bf16_f32 v53, v60, v61
	ds_read_b64 v[58:59], v164 offset:1032
	v_cndmask_b32_e64 v49, v49, v71, s[14:15]
	v_cndmask_b32_e64 v48, v48, v72, s[14:15]
	v_cndmask_b32_e64 v55, v55, v69, s[14:15]
	v_add_u32_e32 v60, 0x4000, v170
	s_waitcnt lgkmcnt(0)
;     __device__ __forceinline__ void operator()(const f32x4 (&acc)[2][2][4][2], const Unit& u, int wr, int wc, int fr, int fq, const EpiCtx& X) const {
;     ...
;         EPI_PIECES({ const unsigned off = lo + (unsigned)(rl * RP) * 2u; LN_ONE(p1a, p1b, rl, off); LN_ONE(p2a, p2b, rl + 1, off + RP * 2); })
	v_pk_fma_f32 v[48:49], v[132:133], v[58:59], v[48:49] op_sel_hi:[1,0,1] neg_lo:[1,0,0] neg_hi:[1,0,0]
	global_store_dwordx4 v60, v[50:53], s[18:19] nt
	v_pk_fma_f32 v[48:49], v[58:59], v[48:49], v[128:129] op_sel:[1,0,0]
	s_nop 0
	v_pk_fma_f32 v[50:51], v[120:121], v[58:59], v[66:67] op_sel_hi:[1,0,1] neg_lo:[1,0,0] neg_hi:[1,0,0]
	v_pk_fma_f32 v[52:53], v[116:117], v[58:59], v[54:55] op_sel_hi:[1,0,1]
	v_pk_fma_f32 v[54:55], v[118:119], v[58:59], v[56:57] op_sel_hi:[1,0,1]
	v_pk_fma_f32 v[52:53], v[58:59], v[52:53], v[138:139] op_sel:[1,0,0]
	v_pk_fma_f32 v[50:51], v[58:59], v[50:51], v[136:137] op_sel:[1,0,0]
	v_pk_fma_f32 v[54:55], v[58:59], v[54:55], v[130:131] op_sel:[1,0,0]
	v_max_f32_e32 v48, 0, v48
	v_max_f32_e32 v49, 0, v49
	v_max_f32_e32 v50, 0, v50
	v_mul_f32_e32 v56, v48, v48
	v_max_f32_e32 v48, 0, v51
	v_mul_f32_e32 v51, v49, v49
	v_max_f32_e32 v49, 0, v52
	v_max_f32_e32 v52, 0, v54
	v_mul_f32_e32 v50, v50, v50
	v_mul_f32_e32 v48, v48, v48
	v_mul_f32_e32 v49, v49, v49
	v_mul_f32_e32 v52, v52, v52
	v_max_f32_e32 v53, 0, v53
	v_max_f32_e32 v54, 0, v55
	v_mul_f32_e32 v53, v53, v53
	v_mul_f32_e32 v54, v54, v54
	v_cvt_pk_bf16_f32 v48, v50, v48
	v_cvt_pk_bf16_f32 v49, v49, v53
	v_cvt_pk_bf16_f32 v50, v56, v51
	v_cvt_pk_bf16_f32 v51, v52, v54
	v_add_u32_e32 v52, 0x4080, v170
	global_store_dwordx4 v52, v[48:51], s[18:19] nt
	ds_read_b64 v[48:49], v164 offset:1152
	v_cndmask_b32_e64 v53, v44, v36, s[14:15]
	v_mov_b32_e32 v54, 0
	v_cndmask_b32_e64 v57, v40, v32, s[14:15]
	v_mov_b32_e32 v58, 0
	v_cndmask_b32_e64 v52, v45, v37, s[14:15]
	v_mov_b32_dpp v54, v53 quad_perm:[1,0,3,2] row_mask:0xf bank_mask:0xf
	v_mov_b32_e32 v53, 0
	v_cndmask_b32_e64 v56, v41, v33, s[14:15]
	v_mov_b32_dpp v58, v57 quad_perm:[1,0,3,2] row_mask:0xf bank_mask:0xf
	v_mov_b32_e32 v57, 0
	v_cndmask_b32_e64 v51, v46, v38, s[14:15]
	v_mov_b32_dpp v53, v52 quad_perm:[1,0,3,2] row_mask:0xf bank_mask:0xf
	v_mov_b32_e32 v52, 0
	v_mov_b32_dpp v57, v56 quad_perm:[1,0,3,2] row_mask:0xf bank_mask:0xf
	v_cndmask_b32_e64 v50, v47, v39, s[14:15]
	v_mov_b32_dpp v52, v51 quad_perm:[1,0,3,2] row_mask:0xf bank_mask:0xf
	v_mov_b32_e32 v51, 0
	v_cndmask_b32_e64 v55, v42, v34, s[14:15]
	v_mov_b32_e32 v56, 0
	v_cndmask_b32_e64 v41, v57, v41, s[14:15]
	v_cndmask_b32_e64 v40, v58, v40, s[14:15]
	v_mov_b32_dpp v51, v50 quad_perm:[1,0,3,2] row_mask:0xf bank_mask:0xf
	v_cndmask_b32_e64 v50, v43, v35, s[14:15]
	v_mov_b32_dpp v56, v55 quad_perm:[1,0,3,2] row_mask:0xf bank_mask:0xf
	v_mov_b32_e32 v55, 0
	s_waitcnt lgkmcnt(0)
	v_pk_fma_f32 v[40:41], v[132:133], v[48:49], v[40:41] op_sel_hi:[1,0,1] neg_lo:[1,0,0] neg_hi:[1,0,0]
	v_cndmask_b32_e64 v47, v51, v47, s[14:15]
	v_mov_b32_dpp v55, v50 quad_perm:[1,0,3,2] row_mask:0xf bank_mask:0xf
	v_cndmask_b32_e64 v46, v52, v46, s[14:15]
	v_cndmask_b32_e64 v45, v53, v45, s[14:15]
	v_cndmask_b32_e64 v44, v54, v44, s[14:15]
	v_pk_fma_f32 v[40:41], v[48:49], v[40:41], v[128:129] op_sel:[1,0,0]
	v_cndmask_b32_e64 v43, v55, v43, s[14:15]
	v_cndmask_b32_e64 v42, v56, v42, s[14:15]
	v_cndmask_b32_e64 v39, v39, v51, s[14:15]
	v_cndmask_b32_e64 v51, v37, v53, s[14:15]
	v_cndmask_b32_e64 v50, v36, v54, s[14:15]
	v_pk_fma_f32 v[36:37], v[120:121], v[48:49], v[44:45] op_sel_hi:[1,0,1] neg_lo:[1,0,0] neg_hi:[1,0,0]
	v_pk_fma_f32 v[44:45], v[116:117], v[48:49], v[46:47] op_sel_hi:[1,0,1]
	v_max_f32_e32 v40, 0, v40
	v_pk_fma_f32 v[44:45], v[48:49], v[44:45], v[138:139] op_sel:[1,0,0]
	v_pk_fma_f32 v[42:43], v[118:119], v[48:49], v[42:43] op_sel_hi:[1,0,1]
	v_mul_f32_e32 v46, v40, v40
	v_max_f32_e32 v40, 0, v41
	v_pk_fma_f32 v[36:37], v[48:49], v[36:37], v[136:137] op_sel:[1,0,0]
	v_pk_fma_f32 v[42:43], v[48:49], v[42:43], v[130:131] op_sel:[1,0,0]
	v_mul_f32_e32 v47, v40, v40
	v_max_f32_e32 v40, 0, v44
	v_max_f32_e32 v36, 0, v36
	v_max_f32_e32 v37, 0, v37
	v_max_f32_e32 v41, 0, v42
	v_mul_f32_e32 v42, v40, v40
	v_max_f32_e32 v40, 0, v45
	v_mul_f32_e32 v36, v36, v36
	v_mul_f32_e32 v37, v37, v37
	v_mul_f32_e32 v44, v41, v41
	v_max_f32_e32 v41, 0, v43
	v_mul_f32_e32 v43, v40, v40
	v_mul_f32_e32 v45, v41, v41
	v_cndmask_b32_e64 v41, v35, v55, s[14:15]
	v_cndmask_b32_e64 v40, v34, v56, s[14:15]
	v_cvt_pk_bf16_f32 v34, v36, v37
	v_cvt_pk_bf16_f32 v35, v42, v43
	v_cvt_pk_bf16_f32 v36, v46, v47
	v_cvt_pk_bf16_f32 v37, v44, v45
	ds_read_b64 v[42:43], v164 offset:1160
	v_cndmask_b32_e64 v33, v33, v57, s[14:15]
	v_cndmask_b32_e64 v32, v32, v58, s[14:15]
	v_cndmask_b32_e64 v38, v38, v52, s[14:15]
	v_add_u32_e32 v44, 0x4800, v170
	s_waitcnt lgkmcnt(0)
;     __device__ __forceinline__ void operator()(const f32x4 (&acc)[2][2][4][2], const Unit& u, int wr, int wc, int fr, int fq, const EpiCtx& X) const {
;     ...
;         EPI_PIECES({ const unsigned off = lo + (unsigned)(rl * RP) * 2u; LN_ONE(p1a, p1b, rl, off); LN_ONE(p2a, p2b, rl + 1, off + RP * 2); })
	v_pk_fma_f32 v[32:33], v[132:133], v[42:43], v[32:33] op_sel_hi:[1,0,1] neg_lo:[1,0,0] neg_hi:[1,0,0]
	global_store_dwordx4 v44, v[34:37], s[18:19] nt
	v_pk_fma_f32 v[32:33], v[42:43], v[32:33], v[128:129] op_sel:[1,0,0]
	s_nop 0
	v_pk_fma_f32 v[34:35], v[120:121], v[42:43], v[50:51] op_sel_hi:[1,0,1] neg_lo:[1,0,0] neg_hi:[1,0,0]
	v_pk_fma_f32 v[36:37], v[116:117], v[42:43], v[38:39] op_sel_hi:[1,0,1]
	v_pk_fma_f32 v[38:39], v[118:119], v[42:43], v[40:41] op_sel_hi:[1,0,1]
	v_pk_fma_f32 v[36:37], v[42:43], v[36:37], v[138:139] op_sel:[1,0,0]
	v_pk_fma_f32 v[34:35], v[42:43], v[34:35], v[136:137] op_sel:[1,0,0]
	v_pk_fma_f32 v[38:39], v[42:43], v[38:39], v[130:131] op_sel:[1,0,0]
	v_max_f32_e32 v32, 0, v32
	v_max_f32_e32 v33, 0, v33
	v_max_f32_e32 v34, 0, v34
	v_mul_f32_e32 v40, v32, v32
	v_max_f32_e32 v32, 0, v35
	v_mul_f32_e32 v35, v33, v33
	v_max_f32_e32 v33, 0, v36
	v_max_f32_e32 v36, 0, v38
	v_mul_f32_e32 v34, v34, v34
	v_mul_f32_e32 v32, v32, v32
	v_mul_f32_e32 v33, v33, v33
	v_mul_f32_e32 v36, v36, v36
	v_max_f32_e32 v37, 0, v37
	v_max_f32_e32 v38, 0, v39
	v_mul_f32_e32 v37, v37, v37
	v_mul_f32_e32 v38, v38, v38
	v_cvt_pk_bf16_f32 v32, v34, v32
	v_cvt_pk_bf16_f32 v33, v33, v37
	v_cvt_pk_bf16_f32 v34, v40, v35
	v_cvt_pk_bf16_f32 v35, v36, v38
	v_add_u32_e32 v36, 0x4880, v170
	global_store_dwordx4 v36, v[32:35], s[18:19] nt
	v_mov_b32_e32 v36, 0
	v_cndmask_b32_e64 v39, v24, v16, s[14:15]
	v_cndmask_b32_e64 v35, v28, v20, s[14:15]
	v_cndmask_b32_e64 v34, v29, v21, s[14:15]
	v_mov_b32_e32 v40, 0
	v_mov_b32_dpp v36, v35 quad_perm:[1,0,3,2] row_mask:0xf bank_mask:0xf
	v_mov_b32_e32 v35, 0
	v_cndmask_b32_e64 v32, v31, v23, s[14:15]
	v_cndmask_b32_e64 v33, v30, v22, s[14:15]
	v_mov_b32_dpp v35, v34 quad_perm:[1,0,3,2] row_mask:0xf bank_mask:0xf
	v_mov_b32_e32 v34, 0
	v_mov_b32_e32 v37, 0
	v_cndmask_b32_e64 v38, v25, v17, s[14:15]
	v_mov_b32_dpp v40, v39 quad_perm:[1,0,3,2] row_mask:0xf bank_mask:0xf
	v_mov_b32_e32 v39, 0
	v_mov_b32_dpp v34, v33 quad_perm:[1,0,3,2] row_mask:0xf bank_mask:0xf
	v_mov_b32_dpp v37, v32 quad_perm:[1,0,3,2] row_mask:0xf bank_mask:0xf
	v_cndmask_b32_e64 v32, v27, v19, s[14:15]
	v_cndmask_b32_e64 v33, v26, v18, s[14:15]
	v_mov_b32_dpp v39, v38 quad_perm:[1,0,3,2] row_mask:0xf bank_mask:0xf
	v_mov_b32_e32 v38, 0
	v_mov_b32_e32 v41, 0
	v_cndmask_b32_e64 v25, v39, v25, s[14:15]
	v_mov_b32_dpp v38, v33 quad_perm:[1,0,3,2] row_mask:0xf bank_mask:0xf
	v_mov_b32_dpp v41, v32 quad_perm:[1,0,3,2] row_mask:0xf bank_mask:0xf
	ds_read_b64 v[32:33], v164 offset:1280
	v_cndmask_b32_e64 v24, v40, v24, s[14:15]
	v_cndmask_b32_e64 v31, v37, v31, s[14:15]
	v_cndmask_b32_e64 v30, v34, v30, s[14:15]
	v_cndmask_b32_e64 v29, v35, v29, s[14:15]
	s_waitcnt lgkmcnt(0)
	v_pk_fma_f32 v[24:25], v[132:133], v[32:33], v[24:25] op_sel_hi:[1,0,1] neg_lo:[1,0,0] neg_hi:[1,0,0]
	v_cndmask_b32_e64 v28, v36, v28, s[14:15]
	v_pk_fma_f32 v[24:25], v[32:33], v[24:25], v[128:129] op_sel:[1,0,0]
	v_cndmask_b32_e64 v27, v41, v27, s[14:15]
	v_cndmask_b32_e64 v26, v38, v26, s[14:15]
	v_cndmask_b32_e64 v22, v22, v34, s[14:15]
	v_cndmask_b32_e64 v35, v21, v35, s[14:15]
	v_cndmask_b32_e64 v34, v20, v36, s[14:15]
	v_pk_fma_f32 v[20:21], v[120:121], v[32:33], v[28:29] op_sel_hi:[1,0,1] neg_lo:[1,0,0] neg_hi:[1,0,0]
	v_pk_fma_f32 v[28:29], v[116:117], v[32:33], v[30:31] op_sel_hi:[1,0,1]
	v_max_f32_e32 v24, 0, v24
	v_pk_fma_f32 v[28:29], v[32:33], v[28:29], v[138:139] op_sel:[1,0,0]
	v_pk_fma_f32 v[26:27], v[118:119], v[32:33], v[26:27] op_sel_hi:[1,0,1]
	v_mul_f32_e32 v30, v24, v24
	v_max_f32_e32 v24, 0, v25
	v_pk_fma_f32 v[20:21], v[32:33], v[20:21], v[136:137] op_sel:[1,0,0]
	v_pk_fma_f32 v[26:27], v[32:33], v[26:27], v[130:131] op_sel:[1,0,0]
	v_mul_f32_e32 v31, v24, v24
	v_max_f32_e32 v24, 0, v28
	v_max_f32_e32 v20, 0, v20
	v_max_f32_e32 v21, 0, v21
	v_max_f32_e32 v25, 0, v26
	v_mul_f32_e32 v26, v24, v24
	v_max_f32_e32 v24, 0, v29
	v_mul_f32_e32 v20, v20, v20
	v_mul_f32_e32 v21, v21, v21
	v_mul_f32_e32 v28, v25, v25
	v_max_f32_e32 v25, 0, v27
	v_mul_f32_e32 v27, v24, v24
	v_mul_f32_e32 v29, v25, v25
	v_cndmask_b32_e64 v25, v19, v41, s[14:15]
	v_cndmask_b32_e64 v24, v18, v38, s[14:15]
	v_cvt_pk_bf16_f32 v18, v20, v21
	v_cvt_pk_bf16_f32 v19, v26, v27
	v_cvt_pk_bf16_f32 v20, v30, v31
	v_cvt_pk_bf16_f32 v21, v28, v29
	ds_read_b64 v[26:27], v164 offset:1288
	v_cndmask_b32_e64 v17, v17, v39, s[14:15]
	v_cndmask_b32_e64 v16, v16, v40, s[14:15]
	v_cndmask_b32_e64 v23, v23, v37, s[14:15]
	v_add_u32_e32 v28, 0x5000, v170
	s_waitcnt lgkmcnt(0)
;     __device__ __forceinline__ void operator()(const f32x4 (&acc)[2][2][4][2], const Unit& u, int wr, int wc, int fr, int fq, const EpiCtx& X) const {
;     ...
;         EPI_PIECES({ const unsigned off = lo + (unsigned)(rl * RP) * 2u; LN_ONE(p1a, p1b, rl, off); LN_ONE(p2a, p2b, rl + 1, off + RP * 2); })
	v_pk_fma_f32 v[16:17], v[132:133], v[26:27], v[16:17] op_sel_hi:[1,0,1] neg_lo:[1,0,0] neg_hi:[1,0,0]
	global_store_dwordx4 v28, v[18:21], s[18:19] nt
	v_pk_fma_f32 v[16:17], v[26:27], v[16:17], v[128:129] op_sel:[1,0,0]
	s_nop 0
	v_pk_fma_f32 v[18:19], v[120:121], v[26:27], v[34:35] op_sel_hi:[1,0,1] neg_lo:[1,0,0] neg_hi:[1,0,0]
	v_pk_fma_f32 v[20:21], v[116:117], v[26:27], v[22:23] op_sel_hi:[1,0,1]
	v_pk_fma_f32 v[22:23], v[118:119], v[26:27], v[24:25] op_sel_hi:[1,0,1]
	v_pk_fma_f32 v[20:21], v[26:27], v[20:21], v[138:139] op_sel:[1,0,0]
	v_pk_fma_f32 v[18:19], v[26:27], v[18:19], v[136:137] op_sel:[1,0,0]
	v_pk_fma_f32 v[22:23], v[26:27], v[22:23], v[130:131] op_sel:[1,0,0]
	v_max_f32_e32 v16, 0, v16
	v_max_f32_e32 v17, 0, v17
	v_max_f32_e32 v18, 0, v18
	v_mul_f32_e32 v24, v16, v16
	v_max_f32_e32 v16, 0, v19
	v_mul_f32_e32 v19, v17, v17
	v_max_f32_e32 v17, 0, v20
	v_max_f32_e32 v20, 0, v22
	v_mul_f32_e32 v18, v18, v18
	v_mul_f32_e32 v16, v16, v16
	v_mul_f32_e32 v17, v17, v17
	v_mul_f32_e32 v20, v20, v20
	v_max_f32_e32 v21, 0, v21
	v_max_f32_e32 v22, 0, v23
	v_mul_f32_e32 v21, v21, v21
	v_mul_f32_e32 v22, v22, v22
	v_cvt_pk_bf16_f32 v16, v18, v16
	v_cvt_pk_bf16_f32 v17, v17, v21
	v_cvt_pk_bf16_f32 v18, v24, v19
	v_cvt_pk_bf16_f32 v19, v20, v22
	v_add_u32_e32 v20, 0x5080, v170
	global_store_dwordx4 v20, v[16:19], s[18:19] nt
	ds_read_b64 v[16:17], v164 offset:1408
	v_cndmask_b32_e64 v21, v12, v4, s[14:15]
	v_mov_b32_e32 v22, 0
	v_cndmask_b32_e64 v25, v8, v0, s[14:15]
	v_mov_b32_e32 v26, 0
	v_cndmask_b32_e64 v20, v13, v5, s[14:15]
	v_mov_b32_dpp v22, v21 quad_perm:[1,0,3,2] row_mask:0xf bank_mask:0xf
	v_mov_b32_e32 v21, 0
	v_cndmask_b32_e64 v24, v9, v1, s[14:15]
	v_mov_b32_dpp v26, v25 quad_perm:[1,0,3,2] row_mask:0xf bank_mask:0xf
	v_mov_b32_e32 v25, 0
	v_cndmask_b32_e64 v19, v14, v6, s[14:15]
	v_mov_b32_dpp v21, v20 quad_perm:[1,0,3,2] row_mask:0xf bank_mask:0xf
	v_mov_b32_e32 v20, 0
	v_mov_b32_dpp v25, v24 quad_perm:[1,0,3,2] row_mask:0xf bank_mask:0xf
	v_cndmask_b32_e64 v18, v15, v7, s[14:15]
	v_mov_b32_dpp v20, v19 quad_perm:[1,0,3,2] row_mask:0xf bank_mask:0xf
	v_mov_b32_e32 v19, 0
	v_cndmask_b32_e64 v23, v10, v2, s[14:15]
	v_mov_b32_e32 v24, 0
	v_cndmask_b32_e64 v9, v25, v9, s[14:15]
	v_cndmask_b32_e64 v8, v26, v8, s[14:15]
	v_mov_b32_dpp v19, v18 quad_perm:[1,0,3,2] row_mask:0xf bank_mask:0xf
	v_cndmask_b32_e64 v18, v11, v3, s[14:15]
	v_mov_b32_dpp v24, v23 quad_perm:[1,0,3,2] row_mask:0xf bank_mask:0xf
	v_mov_b32_e32 v23, 0
	s_waitcnt lgkmcnt(0)
	v_pk_fma_f32 v[8:9], v[132:133], v[16:17], v[8:9] op_sel_hi:[1,0,1] neg_lo:[1,0,0] neg_hi:[1,0,0]
	v_cndmask_b32_e64 v15, v19, v15, s[14:15]
	v_mov_b32_dpp v23, v18 quad_perm:[1,0,3,2] row_mask:0xf bank_mask:0xf
	v_cndmask_b32_e64 v14, v20, v14, s[14:15]
	v_cndmask_b32_e64 v13, v21, v13, s[14:15]
	v_cndmask_b32_e64 v12, v22, v12, s[14:15]
	v_pk_fma_f32 v[8:9], v[16:17], v[8:9], v[128:129] op_sel:[1,0,0]
	v_cndmask_b32_e64 v11, v23, v11, s[14:15]
	v_cndmask_b32_e64 v10, v24, v10, s[14:15]
	v_cndmask_b32_e64 v7, v7, v19, s[14:15]
	v_cndmask_b32_e64 v19, v5, v21, s[14:15]
	v_cndmask_b32_e64 v18, v4, v22, s[14:15]
	v_pk_fma_f32 v[4:5], v[120:121], v[16:17], v[12:13] op_sel_hi:[1,0,1] neg_lo:[1,0,0] neg_hi:[1,0,0]
	v_pk_fma_f32 v[12:13], v[116:117], v[16:17], v[14:15] op_sel_hi:[1,0,1]
	v_max_f32_e32 v8, 0, v8
	v_pk_fma_f32 v[12:13], v[16:17], v[12:13], v[138:139] op_sel:[1,0,0]
	v_pk_fma_f32 v[10:11], v[118:119], v[16:17], v[10:11] op_sel_hi:[1,0,1]
	v_mul_f32_e32 v14, v8, v8
	v_max_f32_e32 v8, 0, v9
	v_pk_fma_f32 v[4:5], v[16:17], v[4:5], v[136:137] op_sel:[1,0,0]
	v_pk_fma_f32 v[10:11], v[16:17], v[10:11], v[130:131] op_sel:[1,0,0]
	v_mul_f32_e32 v15, v8, v8
	v_max_f32_e32 v8, 0, v12
	v_max_f32_e32 v4, 0, v4
	v_max_f32_e32 v5, 0, v5
	v_max_f32_e32 v9, 0, v10
	v_mul_f32_e32 v10, v8, v8
	v_max_f32_e32 v8, 0, v13
	v_mul_f32_e32 v4, v4, v4
	v_mul_f32_e32 v5, v5, v5
	v_mul_f32_e32 v12, v9, v9
	v_max_f32_e32 v9, 0, v11
	v_mul_f32_e32 v11, v8, v8
	v_mul_f32_e32 v13, v9, v9
	v_cndmask_b32_e64 v9, v3, v23, s[14:15]
	v_cndmask_b32_e64 v8, v2, v24, s[14:15]
	v_cvt_pk_bf16_f32 v2, v4, v5
	v_cvt_pk_bf16_f32 v3, v10, v11
	v_cvt_pk_bf16_f32 v4, v14, v15
	v_cvt_pk_bf16_f32 v5, v12, v13
	ds_read_b64 v[10:11], v164 offset:1416
	v_cndmask_b32_e64 v1, v1, v25, s[14:15]
	v_cndmask_b32_e64 v0, v0, v26, s[14:15]
	v_cndmask_b32_e64 v6, v6, v20, s[14:15]
	v_add_u32_e32 v12, 0x5800, v170
	s_waitcnt lgkmcnt(0)
	v_pk_fma_f32 v[0:1], v[132:133], v[10:11], v[0:1] op_sel_hi:[1,0,1] neg_lo:[1,0,0] neg_hi:[1,0,0]
	global_store_dwordx4 v12, v[2:5], s[18:19] nt
	v_pk_fma_f32 v[0:1], v[10:11], v[0:1], v[128:129] op_sel:[1,0,0]
	s_nop 0
	v_pk_fma_f32 v[2:3], v[120:121], v[10:11], v[18:19] op_sel_hi:[1,0,1] neg_lo:[1,0,0] neg_hi:[1,0,0]
	v_pk_fma_f32 v[4:5], v[116:117], v[10:11], v[6:7] op_sel_hi:[1,0,1]
	v_pk_fma_f32 v[6:7], v[118:119], v[10:11], v[8:9] op_sel_hi:[1,0,1]
	v_pk_fma_f32 v[4:5], v[10:11], v[4:5], v[138:139] op_sel:[1,0,0]
	v_pk_fma_f32 v[2:3], v[10:11], v[2:3], v[136:137] op_sel:[1,0,0]
	v_pk_fma_f32 v[6:7], v[10:11], v[6:7], v[130:131] op_sel:[1,0,0]
	v_max_f32_e32 v0, 0, v0
	v_max_f32_e32 v1, 0, v1
	v_max_f32_e32 v2, 0, v2
	v_mul_f32_e32 v8, v0, v0
	v_max_f32_e32 v0, 0, v3
	v_mul_f32_e32 v3, v1, v1
	v_max_f32_e32 v1, 0, v4
	v_max_f32_e32 v4, 0, v6
	v_mul_f32_e32 v2, v2, v2
	v_mul_f32_e32 v0, v0, v0
	v_mul_f32_e32 v1, v1, v1
	v_mul_f32_e32 v4, v4, v4
	v_max_f32_e32 v5, 0, v5
	v_max_f32_e32 v6, 0, v7
	v_mul_f32_e32 v5, v5, v5
	v_mul_f32_e32 v6, v6, v6
	v_cvt_pk_bf16_f32 v0, v2, v0
	v_cvt_pk_bf16_f32 v1, v1, v5
	v_cvt_pk_bf16_f32 v2, v8, v3
	v_cvt_pk_bf16_f32 v3, v4, v6
	v_add_u32_e32 v4, 0x5880, v170
	global_store_dwordx4 v4, v[0:3], s[18:19] nt
	s_cbranch_vccnz .LBB0_679
	s_and_b64 vcc, exec, s[8:9]
	s_cbranch_vccnz .LBB0_678
	s_barrier
	s_branch .LBB0_678

; #define LAS __attribute__((address_space(3)))
; __device__ __forceinline__ void build_tbl(const f32x2* PS, int pm, LAS unsigned char* lds, int wid, int lane) {
;     LAS f32x2* tbl = (LAS f32x2*)(lds + TBL_OFF);
;     const f32x2* p = PS + ((size_t)pm * BM + wid * 32) * 64 + lane;
; #pragma unroll 8
;     for (int i = 0; i < 32; ++i) {
;         const f32x2 v = p[(size_t)i * 64];
;         const float a = wave_sum(v.x), b = wave_sum(v.y);
;         if (lane == 0) { const float mu = a * (1.f / DM), var = fmaxf(b * (1.f / DM) - mu * mu, 0.f); tbl[wid * 32 + i] = (f32x2){mu, 1.f / sqrtf(var + LN_EPS)}; }
;     }
; }
; __device__ __forceinline__ void ensure_tbl(const f32x2* PS, int sid, int pm, const EpiCtx& X) {
;     volatile LAS unsigned* keyw = (volatile LAS unsigned*)(X.lds + MISC_OFF) + KEY_WORD;
;     const unsigned key = (unsigned)(sid * 64 + pm + 1);
;     if ((unsigned)__builtin_amdgcn_readfirstlane((int)keyw[0]) != key) {
;         build_tbl(PS, pm, X.lds, X.wid, X.lane);
;         asm volatile("s_waitcnt lgkmcnt(0)" ::: "memory"); __builtin_amdgcn_s_barrier(); asm volatile("" ::: "memory");
;         if (X.tid == 0) keyw[0] = key;
;     }
; }
.LBB0_928:
	s_waitcnt lgkmcnt(0)
	v_readfirstlane_b32 s5, v182
	s_cmp_eq_u32 s5, s4
	s_cbranch_scc1 .LBB0_950
	s_ashr_i32 s65, s64, 31
	s_lshl_b64 s[18:19], s[64:65], 17
	v_lshl_add_u64 v[232:233], v[162:163], 0, s[18:19]
	s_mov_b64 s[18:19], 0x1000
	global_load_dwordx2 v[128:129], v[232:233], off offset:-2048
	global_load_dwordx2 v[130:131], v[232:233], off offset:-1536
	global_load_dwordx2 v[132:133], v[232:233], off offset:-1024
	global_load_dwordx2 v[134:135], v[232:233], off offset:-512
	global_load_dwordx2 v[136:137], v[232:233], off
	global_load_dwordx2 v[138:139], v[232:233], off offset:512
	global_load_dwordx2 v[140:141], v[232:233], off offset:1024
	global_load_dwordx2 v[142:143], v[232:233], off offset:1536
	v_lshl_add_u64 v[232:233], v[232:233], 0, s[18:19]
	global_load_dwordx2 v[184:185], v[232:233], off offset:-2048
	global_load_dwordx2 v[186:187], v[232:233], off offset:-1536
	global_load_dwordx2 v[188:189], v[232:233], off offset:-1024
	global_load_dwordx2 v[190:191], v[232:233], off offset:-512
	global_load_dwordx2 v[192:193], v[232:233], off
	global_load_dwordx2 v[194:195], v[232:233], off offset:512
	global_load_dwordx2 v[196:197], v[232:233], off offset:1024
	global_load_dwordx2 v[198:199], v[232:233], off offset:1536
	v_lshl_add_u64 v[232:233], v[232:233], 0, s[18:19]
	global_load_dwordx2 v[200:201], v[232:233], off offset:-2048
	global_load_dwordx2 v[202:203], v[232:233], off offset:-1536
	global_load_dwordx2 v[204:205], v[232:233], off offset:-1024
	global_load_dwordx2 v[206:207], v[232:233], off offset:-512
	global_load_dwordx2 v[208:209], v[232:233], off
	global_load_dwordx2 v[210:211], v[232:233], off offset:512
	global_load_dwordx2 v[212:213], v[232:233], off offset:1024
	global_load_dwordx2 v[214:215], v[232:233], off offset:1536
	v_lshl_add_u64 v[232:233], v[232:233], 0, s[18:19]
	global_load_dwordx2 v[216:217], v[232:233], off offset:-2048
	global_load_dwordx2 v[218:219], v[232:233], off offset:-1536
	global_load_dwordx2 v[220:221], v[232:233], off offset:-1024
	global_load_dwordx2 v[222:223], v[232:233], off offset:-512
	global_load_dwordx2 v[224:225], v[232:233], off
	global_load_dwordx2 v[226:227], v[232:233], off offset:512
	global_load_dwordx2 v[228:229], v[232:233], off offset:1024
	global_load_dwordx2 v[230:231], v[232:233], off offset:1536
	s_waitcnt vmcnt(0)
	v_permlane32_swap_b32_e32 v128, v200
	v_permlane32_swap_b32_e32 v129, v201
	v_permlane32_swap_b32_e32 v130, v202
	v_permlane32_swap_b32_e32 v131, v203
	v_permlane32_swap_b32_e32 v132, v204
	v_permlane32_swap_b32_e32 v133, v205
	v_permlane32_swap_b32_e32 v134, v206
	v_permlane32_swap_b32_e32 v135, v207
	v_permlane32_swap_b32_e32 v136, v208
	v_permlane32_swap_b32_e32 v137, v209
	v_permlane32_swap_b32_e32 v138, v210
	v_permlane32_swap_b32_e32 v139, v211
	v_permlane32_swap_b32_e32 v140, v212
	v_permlane32_swap_b32_e32 v141, v213
	v_permlane32_swap_b32_e32 v142, v214
	v_permlane32_swap_b32_e32 v143, v215
	v_permlane32_swap_b32_e32 v184, v216
	v_permlane32_swap_b32_e32 v185, v217
	v_permlane32_swap_b32_e32 v186, v218
	v_permlane32_swap_b32_e32 v187, v219
	v_permlane32_swap_b32_e32 v188, v220
	v_permlane32_swap_b32_e32 v189, v221
	v_permlane32_swap_b32_e32 v190, v222
	v_permlane32_swap_b32_e32 v191, v223
	v_permlane32_swap_b32_e32 v192, v224
	v_permlane32_swap_b32_e32 v193, v225
	v_permlane32_swap_b32_e32 v194, v226
	v_permlane32_swap_b32_e32 v195, v227
	v_permlane32_swap_b32_e32 v196, v228
	v_permlane32_swap_b32_e32 v197, v229
	v_permlane32_swap_b32_e32 v198, v230
	v_permlane32_swap_b32_e32 v199, v231
	v_pk_add_f32 v[128:129], v[128:129], v[200:201]
	v_pk_add_f32 v[130:131], v[130:131], v[202:203]
	v_pk_add_f32 v[132:133], v[132:133], v[204:205]
	v_pk_add_f32 v[134:135], v[134:135], v[206:207]
	v_pk_add_f32 v[136:137], v[136:137], v[208:209]
	v_pk_add_f32 v[138:139], v[138:139], v[210:211]
	v_pk_add_f32 v[140:141], v[140:141], v[212:213]
	v_pk_add_f32 v[142:143], v[142:143], v[214:215]
	v_pk_add_f32 v[184:185], v[184:185], v[216:217]
	v_pk_add_f32 v[186:187], v[186:187], v[218:219]
	v_pk_add_f32 v[188:189], v[188:189], v[220:221]
	v_pk_add_f32 v[190:191], v[190:191], v[222:223]
	v_pk_add_f32 v[192:193], v[192:193], v[224:225]
	v_pk_add_f32 v[194:195], v[194:195], v[226:227]
	v_pk_add_f32 v[196:197], v[196:197], v[228:229]
	v_pk_add_f32 v[198:199], v[198:199], v[230:231]
	s_nop 1
	v_permlane16_swap_b32_e32 v128, v184
	v_permlane16_swap_b32_e32 v129, v185
	v_permlane16_swap_b32_e32 v130, v186
	v_permlane16_swap_b32_e32 v131, v187
	v_permlane16_swap_b32_e32 v132, v188
	v_permlane16_swap_b32_e32 v133, v189
	v_permlane16_swap_b32_e32 v134, v190
	v_permlane16_swap_b32_e32 v135, v191
	v_permlane16_swap_b32_e32 v136, v192
	v_permlane16_swap_b32_e32 v137, v193
	v_permlane16_swap_b32_e32 v138, v194
	v_permlane16_swap_b32_e32 v139, v195
	v_permlane16_swap_b32_e32 v140, v196
	v_permlane16_swap_b32_e32 v141, v197
	v_permlane16_swap_b32_e32 v142, v198
	v_permlane16_swap_b32_e32 v143, v199
	v_pk_add_f32 v[128:129], v[128:129], v[184:185]
	v_pk_add_f32 v[130:131], v[130:131], v[186:187]
	v_pk_add_f32 v[132:133], v[132:133], v[188:189]
	v_pk_add_f32 v[134:135], v[134:135], v[190:191]
	v_pk_add_f32 v[136:137], v[136:137], v[192:193]
	v_pk_add_f32 v[138:139], v[138:139], v[194:195]
	v_pk_add_f32 v[140:141], v[140:141], v[196:197]
	v_pk_add_f32 v[142:143], v[142:143], v[198:199]
	s_nop 1
	v_add_f32_dpp v128, v128, v128 row_ror:8 row_mask:0xf bank_mask:0xf
	v_add_f32_dpp v129, v129, v129 row_ror:8 row_mask:0xf bank_mask:0xf
	v_add_f32_dpp v130, v130, v130 row_ror:8 row_mask:0xf bank_mask:0xf
	v_add_f32_dpp v131, v131, v131 row_ror:8 row_mask:0xf bank_mask:0xf
; #define LAS __attribute__((address_space(3)))
; __device__ __forceinline__ void build_tbl(const f32x2* PS, int pm, LAS unsigned char* lds, int wid, int lane) {
;     LAS f32x2* tbl = (LAS f32x2*)(lds + TBL_OFF);
;     const f32x2* p = PS + ((size_t)pm * BM + wid * 32) * 64 + lane;
; #pragma unroll 8
;     for (int i = 0; i < 32; ++i) {
;         const f32x2 v = p[(size_t)i * 64];
;         const float a = wave_sum(v.x), b = wave_sum(v.y);
;         if (lane == 0) { const float mu = a * (1.f / DM), var = fmaxf(b * (1.f / DM) - mu * mu, 0.f); tbl[wid * 32 + i] = (f32x2){mu, 1.f / sqrtf(var + LN_EPS)}; }
;     }
; }
	v_add_f32_dpp v132, v132, v132 row_ror:8 row_mask:0xf bank_mask:0xf
	v_add_f32_dpp v133, v133, v133 row_ror:8 row_mask:0xf bank_mask:0xf
	v_add_f32_dpp v134, v134, v134 row_ror:8 row_mask:0xf bank_mask:0xf
	v_add_f32_dpp v135, v135, v135 row_ror:8 row_mask:0xf bank_mask:0xf
	v_add_f32_dpp v136, v136, v136 row_ror:8 row_mask:0xf bank_mask:0xf
	v_add_f32_dpp v137, v137, v137 row_ror:8 row_mask:0xf bank_mask:0xf
	v_add_f32_dpp v138, v138, v138 row_ror:8 row_mask:0xf bank_mask:0xf
	v_add_f32_dpp v139, v139, v139 row_ror:8 row_mask:0xf bank_mask:0xf
	v_add_f32_dpp v140, v140, v140 row_ror:8 row_mask:0xf bank_mask:0xf
	v_add_f32_dpp v141, v141, v141 row_ror:8 row_mask:0xf bank_mask:0xf
	v_add_f32_dpp v142, v142, v142 row_ror:8 row_mask:0xf bank_mask:0xf
	v_add_f32_dpp v143, v143, v143 row_ror:8 row_mask:0xf bank_mask:0xf
	v_add_f32_dpp v128, v128, v128 row_ror:4 row_mask:0xf bank_mask:0xf
	v_add_f32_dpp v129, v129, v129 row_ror:4 row_mask:0xf bank_mask:0xf
	v_add_f32_dpp v130, v130, v130 row_ror:4 row_mask:0xf bank_mask:0xf
	v_add_f32_dpp v131, v131, v131 row_ror:4 row_mask:0xf bank_mask:0xf
	v_add_f32_dpp v132, v132, v132 row_ror:4 row_mask:0xf bank_mask:0xf
	v_add_f32_dpp v133, v133, v133 row_ror:4 row_mask:0xf bank_mask:0xf
	v_add_f32_dpp v134, v134, v134 row_ror:4 row_mask:0xf bank_mask:0xf
	v_add_f32_dpp v135, v135, v135 row_ror:4 row_mask:0xf bank_mask:0xf
	v_add_f32_dpp v136, v136, v136 row_ror:4 row_mask:0xf bank_mask:0xf
	v_add_f32_dpp v137, v137, v137 row_ror:4 row_mask:0xf bank_mask:0xf
	v_add_f32_dpp v138, v138, v138 row_ror:4 row_mask:0xf bank_mask:0xf
	v_add_f32_dpp v139, v139, v139 row_ror:4 row_mask:0xf bank_mask:0xf
	v_add_f32_dpp v140, v140, v140 row_ror:4 row_mask:0xf bank_mask:0xf
	v_add_f32_dpp v141, v141, v141 row_ror:4 row_mask:0xf bank_mask:0xf
	v_add_f32_dpp v142, v142, v142 row_ror:4 row_mask:0xf bank_mask:0xf
	v_add_f32_dpp v143, v143, v143 row_ror:4 row_mask:0xf bank_mask:0xf
	v_add_f32_dpp v128, v128, v128 row_ror:2 row_mask:0xf bank_mask:0xf
	v_add_f32_dpp v129, v129, v129 row_ror:2 row_mask:0xf bank_mask:0xf
	v_add_f32_dpp v130, v130, v130 row_ror:2 row_mask:0xf bank_mask:0xf
	v_add_f32_dpp v131, v131, v131 row_ror:2 row_mask:0xf bank_mask:0xf
	v_add_f32_dpp v132, v132, v132 row_ror:2 row_mask:0xf bank_mask:0xf
	v_add_f32_dpp v133, v133, v133 row_ror:2 row_mask:0xf bank_mask:0xf
	v_add_f32_dpp v134, v134, v134 row_ror:2 row_mask:0xf bank_mask:0xf
	v_add_f32_dpp v135, v135, v135 row_ror:2 row_mask:0xf bank_mask:0xf
	v_add_f32_dpp v136, v136, v136 row_ror:2 row_mask:0xf bank_mask:0xf
	v_add_f32_dpp v137, v137, v137 row_ror:2 row_mask:0xf bank_mask:0xf
	v_add_f32_dpp v138, v138, v138 row_ror:2 row_mask:0xf bank_mask:0xf
	v_add_f32_dpp v139, v139, v139 row_ror:2 row_mask:0xf bank_mask:0xf
	v_add_f32_dpp v140, v140, v140 row_ror:2 row_mask:0xf bank_mask:0xf
	v_add_f32_dpp v141, v141, v141 row_ror:2 row_mask:0xf bank_mask:0xf
	v_add_f32_dpp v142, v142, v142 row_ror:2 row_mask:0xf bank_mask:0xf
	v_add_f32_dpp v143, v143, v143 row_ror:2 row_mask:0xf bank_mask:0xf
	v_add_f32_dpp v128, v128, v128 row_ror:1 row_mask:0xf bank_mask:0xf
	v_add_f32_dpp v129, v129, v129 row_ror:1 row_mask:0xf bank_mask:0xf
	v_add_f32_dpp v130, v130, v130 row_ror:1 row_mask:0xf bank_mask:0xf
	v_add_f32_dpp v131, v131, v131 row_ror:1 row_mask:0xf bank_mask:0xf
	v_add_f32_dpp v132, v132, v132 row_ror:1 row_mask:0xf bank_mask:0xf
	v_add_f32_dpp v133, v133, v133 row_ror:1 row_mask:0xf bank_mask:0xf
	v_add_f32_dpp v134, v134, v134 row_ror:1 row_mask:0xf bank_mask:0xf
	v_add_f32_dpp v135, v135, v135 row_ror:1 row_mask:0xf bank_mask:0xf
	v_add_f32_dpp v136, v136, v136 row_ror:1 row_mask:0xf bank_mask:0xf
	v_add_f32_dpp v137, v137, v137 row_ror:1 row_mask:0xf bank_mask:0xf
	v_add_f32_dpp v138, v138, v138 row_ror:1 row_mask:0xf bank_mask:0xf
	v_add_f32_dpp v139, v139, v139 row_ror:1 row_mask:0xf bank_mask:0xf
	v_add_f32_dpp v140, v140, v140 row_ror:1 row_mask:0xf bank_mask:0xf
	v_add_f32_dpp v141, v141, v141 row_ror:1 row_mask:0xf bank_mask:0xf
	v_add_f32_dpp v142, v142, v142 row_ror:1 row_mask:0xf bank_mask:0xf
	v_add_f32_dpp v143, v143, v143 row_ror:1 row_mask:0xf bank_mask:0xf
	s_nop 1
	v_mul_f32_e32 v128, s26, v128
	v_mul_f32_e32 v129, s26, v129
	v_fma_f32 v129, -v128, v128, v129
	v_max_f32_e32 v129, 0, v129
	v_add_f32_e32 v129, 0x3727c5ac, v129
	v_mul_f32_e32 v234, 0x4f800000, v129
	v_cmp_gt_f32_e32 vcc, s93, v129
	s_nop 1
	v_cndmask_b32_e32 v129, v129, v234, vcc
	v_sqrt_f32_e32 v234, v129
	s_nop 0
	v_add_u32_e32 v235, -1, v234
	v_fma_f32 v237, -v235, v234, v129
	v_add_u32_e32 v236, 1, v234
	v_cmp_ge_f32_e64 s[18:19], 0, v237
	s_nop 1
	v_cndmask_b32_e64 v235, v234, v235, s[18:19]
	v_fma_f32 v234, -v236, v234, v129
	v_cmp_lt_f32_e64 s[18:19], 0, v234
	s_nop 1
	v_cndmask_b32_e64 v234, v235, v236, s[18:19]
	v_mul_f32_e32 v235, 0x37800000, v234
	v_cndmask_b32_e32 v234, v234, v235, vcc
	v_cmp_class_f32_e32 vcc, v129, v178
	s_nop 1
	v_cndmask_b32_e32 v129, v234, v129, vcc
	v_div_scale_f32 v234, s[18:19], v129, v129, 1.0
	v_rcp_f32_e32 v235, v234
	s_nop 0
	v_fma_f32 v236, -v234, v235, 1.0
	v_fmac_f32_e32 v235, v236, v235
	v_div_scale_f32 v236, vcc, 1.0, v129, 1.0
	v_mul_f32_e32 v237, v236, v235
	v_fma_f32 v238, -v234, v237, v236
	v_fmac_f32_e32 v237, v238, v235
	v_fma_f32 v234, -v234, v237, v236
	v_div_fmas_f32 v234, v234, v235, v237
	v_div_fixup_f32 v129, v234, v129, 1.0
	v_mul_f32_e32 v130, s26, v130
	v_mul_f32_e32 v131, s26, v131
	v_fma_f32 v131, -v130, v130, v131
	v_max_f32_e32 v131, 0, v131
	v_add_f32_e32 v131, 0x3727c5ac, v131
	v_mul_f32_e32 v234, 0x4f800000, v131
	v_cmp_gt_f32_e32 vcc, s93, v131
	s_nop 1
	v_cndmask_b32_e32 v131, v131, v234, vcc
; __device__ __forceinline__ void build_tbl(const f32x2* PS, int pm, LAS unsigned char* lds, int wid, int lane) {
;     ...
;         if (lane == 0) { const float mu = a * (1.f / DM), var = fmaxf(b * (1.f / DM) - mu * mu, 0.f); tbl[wid * 32 + i] = (f32x2){mu, 1.f / sqrtf(var + LN_EPS)}; }
	v_sqrt_f32_e32 v234, v131
	s_nop 0
	v_add_u32_e32 v235, -1, v234
	v_fma_f32 v237, -v235, v234, v131
	v_add_u32_e32 v236, 1, v234
	v_cmp_ge_f32_e64 s[18:19], 0, v237
	s_nop 1
	v_cndmask_b32_e64 v235, v234, v235, s[18:19]
	v_fma_f32 v234, -v236, v234, v131
	v_cmp_lt_f32_e64 s[18:19], 0, v234
	s_nop 1
	v_cndmask_b32_e64 v234, v235, v236, s[18:19]
	v_mul_f32_e32 v235, 0x37800000, v234
	v_cndmask_b32_e32 v234, v234, v235, vcc
	v_cmp_class_f32_e32 vcc, v131, v178
	s_nop 1
	v_cndmask_b32_e32 v131, v234, v131, vcc
	v_div_scale_f32 v234, s[18:19], v131, v131, 1.0
	v_rcp_f32_e32 v235, v234
	s_nop 0
	v_fma_f32 v236, -v234, v235, 1.0
	v_fmac_f32_e32 v235, v236, v235
	v_div_scale_f32 v236, vcc, 1.0, v131, 1.0
	v_mul_f32_e32 v237, v236, v235
	v_fma_f32 v238, -v234, v237, v236
	v_fmac_f32_e32 v237, v238, v235
	v_fma_f32 v234, -v234, v237, v236
	v_div_fmas_f32 v234, v234, v235, v237
	v_div_fixup_f32 v131, v234, v131, 1.0
	v_mul_f32_e32 v132, s26, v132
	v_mul_f32_e32 v133, s26, v133
	v_fma_f32 v133, -v132, v132, v133
	v_max_f32_e32 v133, 0, v133
	v_add_f32_e32 v133, 0x3727c5ac, v133
	v_mul_f32_e32 v234, 0x4f800000, v133
	v_cmp_gt_f32_e32 vcc, s93, v133
	s_nop 1
	v_cndmask_b32_e32 v133, v133, v234, vcc
	v_sqrt_f32_e32 v234, v133
	s_nop 0
	v_add_u32_e32 v235, -1, v234
	v_fma_f32 v237, -v235, v234, v133
	v_add_u32_e32 v236, 1, v234
	v_cmp_ge_f32_e64 s[18:19], 0, v237
	s_nop 1
	v_cndmask_b32_e64 v235, v234, v235, s[18:19]
	v_fma_f32 v234, -v236, v234, v133
	v_cmp_lt_f32_e64 s[18:19], 0, v234
	s_nop 1
	v_cndmask_b32_e64 v234, v235, v236, s[18:19]
	v_mul_f32_e32 v235, 0x37800000, v234
	v_cndmask_b32_e32 v234, v234, v235, vcc
	v_cmp_class_f32_e32 vcc, v133, v178
	s_nop 1
	v_cndmask_b32_e32 v133, v234, v133, vcc
	v_div_scale_f32 v234, s[18:19], v133, v133, 1.0
	v_rcp_f32_e32 v235, v234
	s_nop 0
	v_fma_f32 v236, -v234, v235, 1.0
	v_fmac_f32_e32 v235, v236, v235
	v_div_scale_f32 v236, vcc, 1.0, v133, 1.0
	v_mul_f32_e32 v237, v236, v235
	v_fma_f32 v238, -v234, v237, v236
	v_fmac_f32_e32 v237, v238, v235
	v_fma_f32 v234, -v234, v237, v236
	v_div_fmas_f32 v234, v234, v235, v237
	v_div_fixup_f32 v133, v234, v133, 1.0
	v_mul_f32_e32 v134, s26, v134
	v_mul_f32_e32 v135, s26, v135
	v_fma_f32 v135, -v134, v134, v135
	v_max_f32_e32 v135, 0, v135
	v_add_f32_e32 v135, 0x3727c5ac, v135
	v_mul_f32_e32 v234, 0x4f800000, v135
	v_cmp_gt_f32_e32 vcc, s93, v135
	s_nop 1
	v_cndmask_b32_e32 v135, v135, v234, vcc
	v_sqrt_f32_e32 v234, v135
	s_nop 0
	v_add_u32_e32 v235, -1, v234
	v_fma_f32 v237, -v235, v234, v135
	v_add_u32_e32 v236, 1, v234
	v_cmp_ge_f32_e64 s[18:19], 0, v237
	s_nop 1
	v_cndmask_b32_e64 v235, v234, v235, s[18:19]
	v_fma_f32 v234, -v236, v234, v135
	v_cmp_lt_f32_e64 s[18:19], 0, v234
	s_nop 1
	v_cndmask_b32_e64 v234, v235, v236, s[18:19]
	v_mul_f32_e32 v235, 0x37800000, v234
	v_cndmask_b32_e32 v234, v234, v235, vcc
	v_cmp_class_f32_e32 vcc, v135, v178
	s_nop 1
	v_cndmask_b32_e32 v135, v234, v135, vcc
	v_div_scale_f32 v234, s[18:19], v135, v135, 1.0
	v_rcp_f32_e32 v235, v234
	s_nop 0
	v_fma_f32 v236, -v234, v235, 1.0
	v_fmac_f32_e32 v235, v236, v235
	v_div_scale_f32 v236, vcc, 1.0, v135, 1.0
	v_mul_f32_e32 v237, v236, v235
	v_fma_f32 v238, -v234, v237, v236
	v_fmac_f32_e32 v237, v238, v235
	v_fma_f32 v234, -v234, v237, v236
	v_div_fmas_f32 v234, v234, v235, v237
	v_div_fixup_f32 v135, v234, v135, 1.0
	v_mul_f32_e32 v136, s26, v136
	v_mul_f32_e32 v137, s26, v137
	v_fma_f32 v137, -v136, v136, v137
	v_max_f32_e32 v137, 0, v137
	v_add_f32_e32 v137, 0x3727c5ac, v137
	v_mul_f32_e32 v234, 0x4f800000, v137
	v_cmp_gt_f32_e32 vcc, s93, v137
	s_nop 1
	v_cndmask_b32_e32 v137, v137, v234, vcc
	v_sqrt_f32_e32 v234, v137
	s_nop 0
	v_add_u32_e32 v235, -1, v234
	v_fma_f32 v237, -v235, v234, v137
	v_add_u32_e32 v236, 1, v234
	v_cmp_ge_f32_e64 s[18:19], 0, v237
	s_nop 1
	v_cndmask_b32_e64 v235, v234, v235, s[18:19]
	v_fma_f32 v234, -v236, v234, v137
	v_cmp_lt_f32_e64 s[18:19], 0, v234
	s_nop 1
	v_cndmask_b32_e64 v234, v235, v236, s[18:19]
	v_mul_f32_e32 v235, 0x37800000, v234
	v_cndmask_b32_e32 v234, v234, v235, vcc
	v_cmp_class_f32_e32 vcc, v137, v178
	s_nop 1
	v_cndmask_b32_e32 v137, v234, v137, vcc
	v_div_scale_f32 v234, s[18:19], v137, v137, 1.0
	v_rcp_f32_e32 v235, v234
	s_nop 0
	v_fma_f32 v236, -v234, v235, 1.0
	v_fmac_f32_e32 v235, v236, v235
	v_div_scale_f32 v236, vcc, 1.0, v137, 1.0
	v_mul_f32_e32 v237, v236, v235
; __device__ __forceinline__ void build_tbl(const f32x2* PS, int pm, LAS unsigned char* lds, int wid, int lane) {
;     ...
;         if (lane == 0) { const float mu = a * (1.f / DM), var = fmaxf(b * (1.f / DM) - mu * mu, 0.f); tbl[wid * 32 + i] = (f32x2){mu, 1.f / sqrtf(var + LN_EPS)}; }
	v_fma_f32 v238, -v234, v237, v236
	v_fmac_f32_e32 v237, v238, v235
	v_fma_f32 v234, -v234, v237, v236
	v_div_fmas_f32 v234, v234, v235, v237
	v_div_fixup_f32 v137, v234, v137, 1.0
	v_mul_f32_e32 v138, s26, v138
	v_mul_f32_e32 v139, s26, v139
	v_fma_f32 v139, -v138, v138, v139
	v_max_f32_e32 v139, 0, v139
	v_add_f32_e32 v139, 0x3727c5ac, v139
	v_mul_f32_e32 v234, 0x4f800000, v139
	v_cmp_gt_f32_e32 vcc, s93, v139
	s_nop 1
	v_cndmask_b32_e32 v139, v139, v234, vcc
	v_sqrt_f32_e32 v234, v139
	s_nop 0
	v_add_u32_e32 v235, -1, v234
	v_fma_f32 v237, -v235, v234, v139
	v_add_u32_e32 v236, 1, v234
	v_cmp_ge_f32_e64 s[18:19], 0, v237
	s_nop 1
	v_cndmask_b32_e64 v235, v234, v235, s[18:19]
	v_fma_f32 v234, -v236, v234, v139
	v_cmp_lt_f32_e64 s[18:19], 0, v234
	s_nop 1
	v_cndmask_b32_e64 v234, v235, v236, s[18:19]
	v_mul_f32_e32 v235, 0x37800000, v234
	v_cndmask_b32_e32 v234, v234, v235, vcc
	v_cmp_class_f32_e32 vcc, v139, v178
	s_nop 1
	v_cndmask_b32_e32 v139, v234, v139, vcc
	v_div_scale_f32 v234, s[18:19], v139, v139, 1.0
	v_rcp_f32_e32 v235, v234
	s_nop 0
	v_fma_f32 v236, -v234, v235, 1.0
	v_fmac_f32_e32 v235, v236, v235
	v_div_scale_f32 v236, vcc, 1.0, v139, 1.0
	v_mul_f32_e32 v237, v236, v235
	v_fma_f32 v238, -v234, v237, v236
	v_fmac_f32_e32 v237, v238, v235
	v_fma_f32 v234, -v234, v237, v236
	v_div_fmas_f32 v234, v234, v235, v237
	v_div_fixup_f32 v139, v234, v139, 1.0
	v_mul_f32_e32 v140, s26, v140
	v_mul_f32_e32 v141, s26, v141
	v_fma_f32 v141, -v140, v140, v141
	v_max_f32_e32 v141, 0, v141
	v_add_f32_e32 v141, 0x3727c5ac, v141
	v_mul_f32_e32 v234, 0x4f800000, v141
	v_cmp_gt_f32_e32 vcc, s93, v141
	s_nop 1
	v_cndmask_b32_e32 v141, v141, v234, vcc
	v_sqrt_f32_e32 v234, v141
	s_nop 0
	v_add_u32_e32 v235, -1, v234
	v_fma_f32 v237, -v235, v234, v141
	v_add_u32_e32 v236, 1, v234
	v_cmp_ge_f32_e64 s[18:19], 0, v237
	s_nop 1
	v_cndmask_b32_e64 v235, v234, v235, s[18:19]
	v_fma_f32 v234, -v236, v234, v141
	v_cmp_lt_f32_e64 s[18:19], 0, v234
	s_nop 1
	v_cndmask_b32_e64 v234, v235, v236, s[18:19]
	v_mul_f32_e32 v235, 0x37800000, v234
	v_cndmask_b32_e32 v234, v234, v235, vcc
	v_cmp_class_f32_e32 vcc, v141, v178
	s_nop 1
	v_cndmask_b32_e32 v141, v234, v141, vcc
	v_div_scale_f32 v234, s[18:19], v141, v141, 1.0
	v_rcp_f32_e32 v235, v234
	s_nop 0
	v_fma_f32 v236, -v234, v235, 1.0
	v_fmac_f32_e32 v235, v236, v235
	v_div_scale_f32 v236, vcc, 1.0, v141, 1.0
	v_mul_f32_e32 v237, v236, v235
	v_fma_f32 v238, -v234, v237, v236
	v_fmac_f32_e32 v237, v238, v235
	v_fma_f32 v234, -v234, v237, v236
	v_div_fmas_f32 v234, v234, v235, v237
	v_div_fixup_f32 v141, v234, v141, 1.0
	v_mul_f32_e32 v142, s26, v142
	v_mul_f32_e32 v143, s26, v143
	v_fma_f32 v143, -v142, v142, v143
	v_max_f32_e32 v143, 0, v143
	v_add_f32_e32 v143, 0x3727c5ac, v143
	v_mul_f32_e32 v234, 0x4f800000, v143
	v_cmp_gt_f32_e32 vcc, s93, v143
	s_nop 1
	v_cndmask_b32_e32 v143, v143, v234, vcc
	v_sqrt_f32_e32 v234, v143
	s_nop 0
	v_add_u32_e32 v235, -1, v234
	v_fma_f32 v237, -v235, v234, v143
	v_add_u32_e32 v236, 1, v234
	v_cmp_ge_f32_e64 s[18:19], 0, v237
	s_nop 1
	v_cndmask_b32_e64 v235, v234, v235, s[18:19]
	v_fma_f32 v234, -v236, v234, v143
	v_cmp_lt_f32_e64 s[18:19], 0, v234
	s_nop 1
	v_cndmask_b32_e64 v234, v235, v236, s[18:19]
	v_mul_f32_e32 v235, 0x37800000, v234
	v_cndmask_b32_e32 v234, v234, v235, vcc
	v_cmp_class_f32_e32 vcc, v143, v178
	s_nop 1
	v_cndmask_b32_e32 v143, v234, v143, vcc
	v_div_scale_f32 v234, s[18:19], v143, v143, 1.0
	v_rcp_f32_e32 v235, v234
	s_nop 0
	v_fma_f32 v236, -v234, v235, 1.0
	v_fmac_f32_e32 v235, v236, v235
	v_div_scale_f32 v236, vcc, 1.0, v143, 1.0
	v_mul_f32_e32 v237, v236, v235
	v_fma_f32 v238, -v234, v237, v236
	v_fmac_f32_e32 v237, v238, v235
	v_fma_f32 v234, -v234, v237, v236
	v_div_fmas_f32 v234, v234, v235, v237
	v_div_fixup_f32 v143, v234, v143, 1.0
	v_lshrrev_b32_e32 v239, 4, v179
	v_lshlrev_b32_e32 v239, 6, v239
	s_add_i32 s18, s87, 0x20400
	v_add_u32_e32 v239, s18, v239
	s_mov_b64 s[68:69], exec
	s_mov_b32 exec_lo, 0x10001
	s_mov_b32 exec_hi, 0x10001
	ds_write_b64 v239, v[128:129]
	ds_write_b64 v239, v[130:131] offset:8
	ds_write_b64 v239, v[132:133] offset:16
	ds_write_b64 v239, v[134:135] offset:24
	ds_write_b64 v239, v[136:137] offset:32
	ds_write_b64 v239, v[138:139] offset:40
	ds_write_b64 v239, v[140:141] offset:48
	ds_write_b64 v239, v[142:143] offset:56
	s_mov_b64 exec, s[68:69]

; #define LAS __attribute__((address_space(3)))
;     __device__ __forceinline__ float pre(const Unit& u, int tid) const { return (tid < 256 ? sv : tv)[u.pn * BM + (tid & 255)]; }
;     __device__ __forceinline__ float pre(const Unit& u, int tid) const { return (tid < 256 ? sv : tv)[u.pn * BM + (tid & 255)]; }
;     __device__ __forceinline__ void operator()(const f32x4 (&acc)[2][2][4][2], const Unit& u, int wr, int wc, int fr, int fq, const EpiCtx& X) const {
;     ...
;             LAS float* stb = (LAS float*)(X.lds + STB_OFF);
;             stb[X.tid] = X.pre;
;             asm volatile("s_waitcnt lgkmcnt(0)" ::: "memory"); __builtin_amdgcn_s_barrier(); asm volatile("" ::: "memory");
.LBB0_950:
	s_waitcnt vmcnt(16)
	ds_write_b32 v171, v181
	s_waitcnt lgkmcnt(0)
	s_barrier
	s_andn2_b64 vcc, exec, s[24:25]
	s_cbranch_vccz .LBB0_952
	s_branch .LBB0_927

; #define LAS __attribute__((address_space(3)))
; #define EPI_OPAQUE(x) asm volatile("" : "+v"(x))
;     __device__ __forceinline__ float pre(const Unit& u, int tid) const { return (tid < 256 ? sv : tv)[u.pn * BM + (tid & 255)]; }
;     __device__ __forceinline__ float pre(const Unit& u, int tid) const { return (tid < 256 ? sv : tv)[u.pn * BM + (tid & 255)]; }
;     __device__ __forceinline__ void operator()(const f32x4 (&acc)[2][2][4][2], const Unit& u, int wr, int wc, int fr, int fq, const EpiCtx& X) const {
;     ...
;         LAS float* stb = (LAS float*)(X.lds + STB_OFF);
;         stb[X.tid] = X.pre;
;         asm volatile("s_waitcnt lgkmcnt(0)" ::: "memory"); __builtin_amdgcn_s_barrier(); asm volatile("" ::: "memory");
;         const bool odd = fr & 1; const int fe = fr - (fr & 1), o32 = (fr & 1) * 32;
;         constexpr int RP = BLK ? 64 : LDC;
;         char* base = BLK ? (char*)(O + (size_t)u.pm * BM * LDC + (size_t)(u.pn * 4 + wc) * (BM * 64)) : (char*)(O + (size_t)u.pm * BM * LDC + u.pn * BM);
;         unsigned lo = (unsigned)((wr * 64 + fe) * RP + (BLK ? 0 : wc * 64) + o32 + 8 * fq) * 2u; EPI_OPAQUE(lo);
;         const LAS f32x2* tbl = (const LAS f32x2*)(X.lds + TBL_OFF) + wr * 64 + fe;
;         const LAS f32x4* sp = (const LAS f32x4*)(stb + wc * 64 + o32 + 8 * fq);
;         const f32x4 sa = sp[0], sb = sp[1], ta = sp[64], tb = sp[65];
;     ...
;         EPI_PIECES({ const unsigned off = lo + (unsigned)(rl * RP) * 2u; LN_ONE(p1a, p1b, rl, off); LN_ONE(p2a, p2b, rl + 1, off + RP * 2); })
.LBB0_975:
	v_cndmask_b32_e64 v185, v124, v116, s[14:15]
	v_mov_b32_e32 v186, 0
	v_cndmask_b32_e64 v184, v125, v117, s[14:15]
	v_cndmask_b32_e64 v189, v120, v112, s[14:15]
	v_mov_b32_dpp v186, v185 quad_perm:[1,0,3,2] row_mask:0xf bank_mask:0xf
	v_mov_b32_e32 v185, 0
	v_mov_b32_e32 v190, 0
	v_cndmask_b32_e64 v183, v126, v118, s[14:15]
	v_mov_b32_dpp v185, v184 quad_perm:[1,0,3,2] row_mask:0xf bank_mask:0xf
	v_mov_b32_e32 v184, 0
	v_cndmask_b32_e64 v188, v121, v113, s[14:15]
	v_mov_b32_dpp v190, v189 quad_perm:[1,0,3,2] row_mask:0xf bank_mask:0xf
	v_mov_b32_e32 v189, 0
	v_cndmask_b32_e64 v182, v127, v119, s[14:15]
	v_mov_b32_dpp v184, v183 quad_perm:[1,0,3,2] row_mask:0xf bank_mask:0xf
	v_mov_b32_e32 v183, 0
	v_cndmask_b32_e64 v187, v122, v114, s[14:15]
	v_mov_b32_dpp v189, v188 quad_perm:[1,0,3,2] row_mask:0xf bank_mask:0xf
	v_mov_b32_e32 v188, 0
	s_waitcnt vmcnt(16)
	ds_write_b32 v171, v181
	v_mov_b32_e32 v152, v174
	v_mov_b32_dpp v183, v182 quad_perm:[1,0,3,2] row_mask:0xf bank_mask:0xf
	v_cndmask_b32_e64 v182, v123, v115, s[14:15]
	v_mov_b32_dpp v188, v187 quad_perm:[1,0,3,2] row_mask:0xf bank_mask:0xf
	v_mov_b32_e32 v187, 0
	s_waitcnt lgkmcnt(0)
	s_barrier
	ds_read_b128 v[136:139], v176
	s_waitcnt lgkmcnt(2)
	ds_read_b128 v[132:135], v176 offset:16
	ds_read_b128 v[140:143], v176 offset:1024
	ds_read_b128 v[128:131], v176 offset:1040
	v_mov_b32_dpp v187, v182 quad_perm:[1,0,3,2] row_mask:0xf bank_mask:0xf
	v_cndmask_b32_e64 v126, v184, v126, s[14:15]
	v_cndmask_b32_e64 v125, v185, v125, s[14:15]
	v_cndmask_b32_e64 v182, v118, v184, s[14:15]
	v_cndmask_b32_e64 v185, v117, v185, s[14:15]
	v_cndmask_b32_e64 v184, v116, v186, s[14:15]
	ds_read_b64 v[116:117], v175
	s_mul_i32 s5, s64, 0x600000
	s_mul_hi_i32 s4, s64, 0x600000
	s_add_u32 s18, s77, s5
	v_cndmask_b32_e64 v124, v186, v124, s[14:15]
	s_addc_u32 s19, s78, s4
	s_ashr_i32 s67, s66, 31
	v_cndmask_b32_e64 v123, v187, v123, s[14:15]
	v_cndmask_b32_e64 v187, v115, v187, s[14:15]
	v_cndmask_b32_e64 v186, v114, v188, s[14:15]
	s_waitcnt lgkmcnt(0)
	v_pk_fma_f32 v[114:115], v[136:137], v[116:117], v[124:125] op_sel_hi:[1,0,1] neg_lo:[1,0,0] neg_hi:[1,0,0]
	s_lshl_b64 s[4:5], s[66:67], 1
	v_cndmask_b32_e64 v127, v183, v127, s[14:15]
	v_cndmask_b32_e64 v122, v188, v122, s[14:15]
	v_cndmask_b32_e64 v121, v189, v121, s[14:15]
	v_cndmask_b32_e64 v120, v190, v120, s[14:15]
	v_cndmask_b32_e64 v189, v113, v189, s[14:15]
	v_cndmask_b32_e64 v188, v112, v190, s[14:15]
	v_xor_b32_e32 v113, 0x80000000, v139
	v_xor_b32_e32 v112, 0x80000000, v138
	v_pk_fma_f32 v[124:125], v[116:117], v[114:115], v[140:141] op_sel:[1,0,0]
	v_xor_b32_e32 v115, 0x80000000, v135
	v_xor_b32_e32 v114, 0x80000000, v134
	s_add_u32 s18, s18, s4
	v_cndmask_b32_e64 v183, v119, v183, s[14:15]
	v_pk_fma_f32 v[118:119], v[112:113], v[116:117], v[126:127] op_sel_hi:[1,0,1]
	v_pk_fma_f32 v[120:121], v[132:133], v[116:117], v[120:121] op_sel_hi:[1,0,1] neg_lo:[1,0,0] neg_hi:[1,0,0]
	v_pk_fma_f32 v[122:123], v[114:115], v[116:117], v[122:123] op_sel_hi:[1,0,1]
	s_addc_u32 s19, s19, s5
	v_pk_fma_f32 v[118:119], v[116:117], v[118:119], v[142:143] op_sel:[1,0,0]
	v_pk_fma_f32 v[122:123], v[116:117], v[122:123], v[130:131] op_sel:[1,0,0]
	v_pk_fma_f32 v[120:121], v[116:117], v[120:121], v[128:129] op_sel:[1,0,0]
	v_cvt_pk_bf16_f32 v116, v124, v125
	v_cvt_pk_bf16_f32 v117, v118, v119
	v_mov_b32_e32 v126, 0
	v_cvt_pk_bf16_f32 v118, v120, v121
	v_cvt_pk_bf16_f32 v119, v122, v123
	global_store_dwordx4 v152, v[116:119], s[18:19]
	ds_read_b64 v[116:117], v175 offset:8
	s_waitcnt lgkmcnt(0)
	v_pk_fma_f32 v[120:121], v[112:113], v[116:117], v[182:183] op_sel_hi:[1,0,1]
	v_pk_fma_f32 v[118:119], v[136:137], v[116:117], v[184:185] op_sel_hi:[1,0,1] neg_lo:[1,0,0] neg_hi:[1,0,0]
	v_pk_fma_f32 v[120:121], v[116:117], v[120:121], v[142:143] op_sel:[1,0,0]
	v_pk_fma_f32 v[122:123], v[132:133], v[116:117], v[188:189] op_sel_hi:[1,0,1] neg_lo:[1,0,0] neg_hi:[1,0,0]
	v_pk_fma_f32 v[124:125], v[114:115], v[116:117], v[186:187] op_sel_hi:[1,0,1]
	v_pk_fma_f32 v[118:119], v[116:117], v[118:119], v[140:141] op_sel:[1,0,0]
	v_pk_fma_f32 v[124:125], v[116:117], v[124:125], v[130:131] op_sel:[1,0,0]
	v_pk_fma_f32 v[122:123], v[116:117], v[122:123], v[128:129] op_sel:[1,0,0]
	v_cvt_pk_bf16_f32 v116, v118, v119
	v_cvt_pk_bf16_f32 v117, v120, v121
	v_add_u32_e32 v120, 0x6000, v152
	v_cvt_pk_bf16_f32 v118, v122, v123
	v_cvt_pk_bf16_f32 v119, v124, v125
	global_store_dwordx4 v120, v[116:119], s[18:19]
	ds_read_b64 v[116:117], v175 offset:128
	v_cndmask_b32_e64 v121, v108, v100, s[14:15]
	v_mov_b32_e32 v122, 0
	v_cndmask_b32_e64 v120, v109, v101, s[14:15]
	v_cndmask_b32_e64 v125, v104, v96, s[14:15]
	v_mov_b32_dpp v122, v121 quad_perm:[1,0,3,2] row_mask:0xf bank_mask:0xf
	v_mov_b32_e32 v121, 0
	v_cndmask_b32_e64 v119, v110, v102, s[14:15]
	v_cndmask_b32_e64 v124, v105, v97, s[14:15]
	v_mov_b32_dpp v121, v120 quad_perm:[1,0,3,2] row_mask:0xf bank_mask:0xf
	v_mov_b32_e32 v120, 0
	v_mov_b32_dpp v126, v125 quad_perm:[1,0,3,2] row_mask:0xf bank_mask:0xf
	v_mov_b32_e32 v125, 0
	v_cndmask_b32_e64 v118, v111, v103, s[14:15]
	v_mov_b32_dpp v120, v119 quad_perm:[1,0,3,2] row_mask:0xf bank_mask:0xf
	v_mov_b32_e32 v119, 0
	v_cndmask_b32_e64 v123, v106, v98, s[14:15]
	v_mov_b32_dpp v125, v124 quad_perm:[1,0,3,2] row_mask:0xf bank_mask:0xf
	v_mov_b32_e32 v124, 0
	v_mov_b32_dpp v119, v118 quad_perm:[1,0,3,2] row_mask:0xf bank_mask:0xf
	v_cndmask_b32_e64 v118, v107, v99, s[14:15]
	v_mov_b32_dpp v124, v123 quad_perm:[1,0,3,2] row_mask:0xf bank_mask:0xf
	v_mov_b32_e32 v123, 0
	v_cndmask_b32_e64 v109, v121, v109, s[14:15]
	v_cndmask_b32_e64 v108, v122, v108, s[14:15]
	v_mov_b32_dpp v123, v118 quad_perm:[1,0,3,2] row_mask:0xf bank_mask:0xf
	v_cndmask_b32_e64 v111, v119, v111, s[14:15]
	v_cndmask_b32_e64 v110, v120, v110, s[14:15]
	v_cndmask_b32_e64 v102, v102, v120, s[14:15]
	v_cndmask_b32_e64 v101, v101, v121, s[14:15]
	v_cndmask_b32_e64 v121, v97, v125, s[14:15]
	v_cndmask_b32_e64 v120, v96, v126, s[14:15]
	s_waitcnt lgkmcnt(0)
;     __device__ __forceinline__ void operator()(const f32x4 (&acc)[2][2][4][2], const Unit& u, int wr, int wc, int fr, int fq, const EpiCtx& X) const {
;     ...
;         EPI_PIECES({ const unsigned off = lo + (unsigned)(rl * RP) * 2u; LN_ONE(p1a, p1b, rl, off); LN_ONE(p2a, p2b, rl + 1, off + RP * 2); })
	v_pk_fma_f32 v[96:97], v[136:137], v[116:117], v[108:109] op_sel_hi:[1,0,1] neg_lo:[1,0,0] neg_hi:[1,0,0]
	v_cndmask_b32_e64 v107, v123, v107, s[14:15]
	v_cndmask_b32_e64 v106, v124, v106, s[14:15]
	v_cndmask_b32_e64 v105, v125, v105, s[14:15]
	v_cndmask_b32_e64 v104, v126, v104, s[14:15]
	v_cndmask_b32_e64 v103, v103, v119, s[14:15]
	v_cndmask_b32_e64 v119, v99, v123, s[14:15]
	v_cndmask_b32_e64 v118, v98, v124, s[14:15]
	v_pk_fma_f32 v[98:99], v[112:113], v[116:117], v[110:111] op_sel_hi:[1,0,1]
	v_pk_fma_f32 v[96:97], v[116:117], v[96:97], v[140:141] op_sel:[1,0,0]
	v_cndmask_b32_e64 v100, v100, v122, s[14:15]
	v_add_u32_e32 v122, 0x60000, v152
	v_pk_fma_f32 v[98:99], v[116:117], v[98:99], v[142:143] op_sel:[1,0,0]
	v_pk_fma_f32 v[104:105], v[132:133], v[116:117], v[104:105] op_sel_hi:[1,0,1] neg_lo:[1,0,0] neg_hi:[1,0,0]
	v_pk_fma_f32 v[106:107], v[114:115], v[116:117], v[106:107] op_sel_hi:[1,0,1]
	v_cvt_pk_bf16_f32 v96, v96, v97
	v_cvt_pk_bf16_f32 v97, v98, v99
	v_pk_fma_f32 v[104:105], v[116:117], v[104:105], v[128:129] op_sel:[1,0,0]
	v_pk_fma_f32 v[106:107], v[116:117], v[106:107], v[130:131] op_sel:[1,0,0]
	v_cvt_pk_bf16_f32 v98, v104, v105
	s_nop 0
	v_cvt_pk_bf16_f32 v99, v106, v107
	global_store_dwordx4 v122, v[96:99], s[18:19]
	ds_read_b64 v[96:97], v175 offset:136
	s_waitcnt lgkmcnt(0)
	v_pk_fma_f32 v[104:105], v[114:115], v[96:97], v[118:119] op_sel_hi:[1,0,1]
	v_pk_fma_f32 v[98:99], v[136:137], v[96:97], v[100:101] op_sel_hi:[1,0,1] neg_lo:[1,0,0] neg_hi:[1,0,0]
	v_pk_fma_f32 v[100:101], v[112:113], v[96:97], v[102:103] op_sel_hi:[1,0,1]
	v_pk_fma_f32 v[98:99], v[96:97], v[98:99], v[140:141] op_sel:[1,0,0]
	v_pk_fma_f32 v[100:101], v[96:97], v[100:101], v[142:143] op_sel:[1,0,0]
	v_pk_fma_f32 v[102:103], v[132:133], v[96:97], v[120:121] op_sel_hi:[1,0,1] neg_lo:[1,0,0] neg_hi:[1,0,0]
	v_pk_fma_f32 v[104:105], v[96:97], v[104:105], v[130:131] op_sel:[1,0,0]
	v_pk_fma_f32 v[102:103], v[96:97], v[102:103], v[128:129] op_sel:[1,0,0]
	v_cvt_pk_bf16_f32 v96, v98, v99
	v_cvt_pk_bf16_f32 v97, v100, v101
	v_add_u32_e32 v100, 0x66000, v152
	v_cvt_pk_bf16_f32 v98, v102, v103
	v_cvt_pk_bf16_f32 v99, v104, v105
	global_store_dwordx4 v100, v[96:99], s[18:19]
	v_mov_b32_e32 v100, 0
	v_cndmask_b32_e64 v103, v88, v80, s[14:15]
	v_cndmask_b32_e64 v99, v92, v84, s[14:15]
	v_cndmask_b32_e64 v98, v93, v85, s[14:15]
	v_mov_b32_e32 v104, 0
	v_mov_b32_dpp v100, v99 quad_perm:[1,0,3,2] row_mask:0xf bank_mask:0xf
	v_mov_b32_e32 v99, 0
	v_cndmask_b32_e64 v97, v94, v86, s[14:15]
	v_cndmask_b32_e64 v102, v89, v81, s[14:15]
	v_mov_b32_dpp v99, v98 quad_perm:[1,0,3,2] row_mask:0xf bank_mask:0xf
	v_mov_b32_e32 v98, 0
	v_mov_b32_dpp v104, v103 quad_perm:[1,0,3,2] row_mask:0xf bank_mask:0xf
	v_mov_b32_e32 v103, 0
	v_mov_b32_dpp v98, v97 quad_perm:[1,0,3,2] row_mask:0xf bank_mask:0xf
	v_cndmask_b32_e64 v94, v98, v94, s[14:15]
	v_mov_b32_dpp v103, v102 quad_perm:[1,0,3,2] row_mask:0xf bank_mask:0xf
	v_cndmask_b32_e64 v93, v99, v93, s[14:15]
	v_cndmask_b32_e64 v86, v86, v98, s[14:15]
	v_cndmask_b32_e64 v85, v85, v99, s[14:15]
	v_cndmask_b32_e64 v99, v81, v103, s[14:15]
	v_cndmask_b32_e64 v98, v80, v104, s[14:15]
	ds_read_b64 v[80:81], v175 offset:256
	v_cndmask_b32_e64 v96, v95, v87, s[14:15]
	v_mov_b32_e32 v97, 0
	v_cndmask_b32_e64 v101, v90, v82, s[14:15]
	v_mov_b32_e32 v102, 0
	v_mov_b32_dpp v97, v96 quad_perm:[1,0,3,2] row_mask:0xf bank_mask:0xf
	v_cndmask_b32_e64 v96, v91, v83, s[14:15]
	v_mov_b32_dpp v102, v101 quad_perm:[1,0,3,2] row_mask:0xf bank_mask:0xf
	v_mov_b32_e32 v101, 0
	v_cndmask_b32_e64 v95, v97, v95, s[14:15]
	v_cndmask_b32_e64 v92, v100, v92, s[14:15]
	v_mov_b32_dpp v101, v96 quad_perm:[1,0,3,2] row_mask:0xf bank_mask:0xf
	v_cndmask_b32_e64 v91, v101, v91, s[14:15]
	v_cndmask_b32_e64 v90, v102, v90, s[14:15]
	v_cndmask_b32_e64 v89, v103, v89, s[14:15]
	v_cndmask_b32_e64 v88, v104, v88, s[14:15]
	v_cndmask_b32_e64 v87, v87, v97, s[14:15]
	v_cndmask_b32_e64 v97, v83, v101, s[14:15]
	v_cndmask_b32_e64 v96, v82, v102, s[14:15]
	s_waitcnt lgkmcnt(0)
	v_pk_fma_f32 v[82:83], v[136:137], v[80:81], v[92:93] op_sel_hi:[1,0,1] neg_lo:[1,0,0] neg_hi:[1,0,0]
	v_pk_fma_f32 v[92:93], v[112:113], v[80:81], v[94:95] op_sel_hi:[1,0,1]
	v_pk_fma_f32 v[88:89], v[132:133], v[80:81], v[88:89] op_sel_hi:[1,0,1] neg_lo:[1,0,0] neg_hi:[1,0,0]
	v_pk_fma_f32 v[90:91], v[114:115], v[80:81], v[90:91] op_sel_hi:[1,0,1]
	v_cndmask_b32_e64 v84, v84, v100, s[14:15]
	v_add_u32_e32 v100, 0xc0000, v152
	v_pk_fma_f32 v[92:93], v[80:81], v[92:93], v[142:143] op_sel:[1,0,0]
	v_pk_fma_f32 v[82:83], v[80:81], v[82:83], v[140:141] op_sel:[1,0,0]
	v_pk_fma_f32 v[90:91], v[80:81], v[90:91], v[130:131] op_sel:[1,0,0]
	v_pk_fma_f32 v[88:89], v[80:81], v[88:89], v[128:129] op_sel:[1,0,0]
	v_cvt_pk_bf16_f32 v80, v82, v83
	v_cvt_pk_bf16_f32 v81, v92, v93
	s_nop 0
	v_cvt_pk_bf16_f32 v82, v88, v89
	v_cvt_pk_bf16_f32 v83, v90, v91
	global_store_dwordx4 v100, v[80:83], s[18:19]
	ds_read_b64 v[80:81], v175 offset:264
	v_mov_b32_e32 v90, 0
	s_waitcnt lgkmcnt(0)
;     __device__ __forceinline__ void operator()(const f32x4 (&acc)[2][2][4][2], const Unit& u, int wr, int wc, int fr, int fq, const EpiCtx& X) const {
;     ...
;         EPI_PIECES({ const unsigned off = lo + (unsigned)(rl * RP) * 2u; LN_ONE(p1a, p1b, rl, off); LN_ONE(p2a, p2b, rl + 1, off + RP * 2); })
	v_pk_fma_f32 v[82:83], v[136:137], v[80:81], v[84:85] op_sel_hi:[1,0,1] neg_lo:[1,0,0] neg_hi:[1,0,0]
	v_pk_fma_f32 v[84:85], v[112:113], v[80:81], v[86:87] op_sel_hi:[1,0,1]
	v_pk_fma_f32 v[86:87], v[132:133], v[80:81], v[98:99] op_sel_hi:[1,0,1] neg_lo:[1,0,0] neg_hi:[1,0,0]
	v_pk_fma_f32 v[84:85], v[80:81], v[84:85], v[142:143] op_sel:[1,0,0]
	v_pk_fma_f32 v[88:89], v[114:115], v[80:81], v[96:97] op_sel_hi:[1,0,1]
	v_pk_fma_f32 v[82:83], v[80:81], v[82:83], v[140:141] op_sel:[1,0,0]
	v_pk_fma_f32 v[88:89], v[80:81], v[88:89], v[130:131] op_sel:[1,0,0]
	v_pk_fma_f32 v[86:87], v[80:81], v[86:87], v[128:129] op_sel:[1,0,0]
	v_cvt_pk_bf16_f32 v80, v82, v83
	v_cvt_pk_bf16_f32 v81, v84, v85
	v_add_u32_e32 v84, 0xc6000, v152
	v_cvt_pk_bf16_f32 v82, v86, v87
	v_cvt_pk_bf16_f32 v83, v88, v89
	global_store_dwordx4 v84, v[80:83], s[18:19]
	ds_read_b64 v[80:81], v175 offset:384
	v_cndmask_b32_e64 v85, v76, v68, s[14:15]
	v_mov_b32_e32 v86, 0
	v_cndmask_b32_e64 v84, v77, v69, s[14:15]
	v_cndmask_b32_e64 v89, v72, v64, s[14:15]
	v_mov_b32_dpp v86, v85 quad_perm:[1,0,3,2] row_mask:0xf bank_mask:0xf
	v_mov_b32_e32 v85, 0
	v_cndmask_b32_e64 v83, v78, v70, s[14:15]
	v_cndmask_b32_e64 v88, v73, v65, s[14:15]
	v_mov_b32_dpp v85, v84 quad_perm:[1,0,3,2] row_mask:0xf bank_mask:0xf
	v_mov_b32_e32 v84, 0
	v_mov_b32_dpp v90, v89 quad_perm:[1,0,3,2] row_mask:0xf bank_mask:0xf
	v_mov_b32_e32 v89, 0
	v_cndmask_b32_e64 v82, v79, v71, s[14:15]
	v_mov_b32_dpp v84, v83 quad_perm:[1,0,3,2] row_mask:0xf bank_mask:0xf
	v_mov_b32_e32 v83, 0
	v_cndmask_b32_e64 v87, v74, v66, s[14:15]
	v_mov_b32_dpp v89, v88 quad_perm:[1,0,3,2] row_mask:0xf bank_mask:0xf
	v_mov_b32_e32 v88, 0
	v_mov_b32_dpp v83, v82 quad_perm:[1,0,3,2] row_mask:0xf bank_mask:0xf
	v_cndmask_b32_e64 v82, v75, v67, s[14:15]
	v_mov_b32_dpp v88, v87 quad_perm:[1,0,3,2] row_mask:0xf bank_mask:0xf
	v_mov_b32_e32 v87, 0
	v_cndmask_b32_e64 v77, v85, v77, s[14:15]
	v_cndmask_b32_e64 v76, v86, v76, s[14:15]
	v_mov_b32_dpp v87, v82 quad_perm:[1,0,3,2] row_mask:0xf bank_mask:0xf
	v_cndmask_b32_e64 v79, v83, v79, s[14:15]
	v_cndmask_b32_e64 v78, v84, v78, s[14:15]
	v_cndmask_b32_e64 v70, v70, v84, s[14:15]
	v_cndmask_b32_e64 v69, v69, v85, s[14:15]
	v_cndmask_b32_e64 v85, v65, v89, s[14:15]
	v_cndmask_b32_e64 v84, v64, v90, s[14:15]
	s_waitcnt lgkmcnt(0)
	v_pk_fma_f32 v[64:65], v[136:137], v[80:81], v[76:77] op_sel_hi:[1,0,1] neg_lo:[1,0,0] neg_hi:[1,0,0]
	v_cndmask_b32_e64 v75, v87, v75, s[14:15]
	v_cndmask_b32_e64 v74, v88, v74, s[14:15]
	v_cndmask_b32_e64 v73, v89, v73, s[14:15]
	v_cndmask_b32_e64 v72, v90, v72, s[14:15]
	v_cndmask_b32_e64 v71, v71, v83, s[14:15]
	v_cndmask_b32_e64 v83, v67, v87, s[14:15]
	v_cndmask_b32_e64 v82, v66, v88, s[14:15]
	v_pk_fma_f32 v[66:67], v[112:113], v[80:81], v[78:79] op_sel_hi:[1,0,1]
	v_pk_fma_f32 v[64:65], v[80:81], v[64:65], v[140:141] op_sel:[1,0,0]
	v_cndmask_b32_e64 v68, v68, v86, s[14:15]
	v_add_u32_e32 v86, 0x120000, v152
	v_pk_fma_f32 v[66:67], v[80:81], v[66:67], v[142:143] op_sel:[1,0,0]
	v_pk_fma_f32 v[72:73], v[132:133], v[80:81], v[72:73] op_sel_hi:[1,0,1] neg_lo:[1,0,0] neg_hi:[1,0,0]
	v_pk_fma_f32 v[74:75], v[114:115], v[80:81], v[74:75] op_sel_hi:[1,0,1]
	v_cvt_pk_bf16_f32 v64, v64, v65
	v_cvt_pk_bf16_f32 v65, v66, v67
	v_pk_fma_f32 v[72:73], v[80:81], v[72:73], v[128:129] op_sel:[1,0,0]
	v_pk_fma_f32 v[74:75], v[80:81], v[74:75], v[130:131] op_sel:[1,0,0]
	v_cvt_pk_bf16_f32 v66, v72, v73
	s_nop 0
	v_cvt_pk_bf16_f32 v67, v74, v75
	global_store_dwordx4 v86, v[64:67], s[18:19]
	ds_read_b64 v[64:65], v175 offset:392
	s_waitcnt lgkmcnt(0)
	v_pk_fma_f32 v[72:73], v[114:115], v[64:65], v[82:83] op_sel_hi:[1,0,1]
	v_pk_fma_f32 v[66:67], v[136:137], v[64:65], v[68:69] op_sel_hi:[1,0,1] neg_lo:[1,0,0] neg_hi:[1,0,0]
	v_pk_fma_f32 v[68:69], v[112:113], v[64:65], v[70:71] op_sel_hi:[1,0,1]
	v_pk_fma_f32 v[66:67], v[64:65], v[66:67], v[140:141] op_sel:[1,0,0]
	v_pk_fma_f32 v[68:69], v[64:65], v[68:69], v[142:143] op_sel:[1,0,0]
	v_pk_fma_f32 v[70:71], v[132:133], v[64:65], v[84:85] op_sel_hi:[1,0,1] neg_lo:[1,0,0] neg_hi:[1,0,0]
	v_pk_fma_f32 v[72:73], v[64:65], v[72:73], v[130:131] op_sel:[1,0,0]
	v_pk_fma_f32 v[70:71], v[64:65], v[70:71], v[128:129] op_sel:[1,0,0]
	v_cvt_pk_bf16_f32 v64, v66, v67
	v_cvt_pk_bf16_f32 v65, v68, v69
	v_add_u32_e32 v68, 0x126000, v152
	v_cvt_pk_bf16_f32 v66, v70, v71
	v_cvt_pk_bf16_f32 v67, v72, v73
	global_store_dwordx4 v68, v[64:67], s[18:19]
	v_mov_b32_e32 v68, 0
	v_cndmask_b32_e64 v71, v56, v48, s[14:15]
	v_cndmask_b32_e64 v67, v60, v52, s[14:15]
	v_cndmask_b32_e64 v66, v61, v53, s[14:15]
	v_mov_b32_e32 v72, 0
	v_mov_b32_dpp v68, v67 quad_perm:[1,0,3,2] row_mask:0xf bank_mask:0xf
	v_mov_b32_e32 v67, 0
	v_cndmask_b32_e64 v65, v62, v54, s[14:15]
	v_cndmask_b32_e64 v70, v57, v49, s[14:15]
	v_mov_b32_dpp v67, v66 quad_perm:[1,0,3,2] row_mask:0xf bank_mask:0xf
	v_mov_b32_e32 v66, 0
	v_mov_b32_dpp v72, v71 quad_perm:[1,0,3,2] row_mask:0xf bank_mask:0xf
	v_mov_b32_e32 v71, 0
	v_mov_b32_dpp v66, v65 quad_perm:[1,0,3,2] row_mask:0xf bank_mask:0xf
	v_cndmask_b32_e64 v62, v66, v62, s[14:15]
	v_mov_b32_dpp v71, v70 quad_perm:[1,0,3,2] row_mask:0xf bank_mask:0xf
	v_cndmask_b32_e64 v61, v67, v61, s[14:15]
	v_cndmask_b32_e64 v54, v54, v66, s[14:15]
	v_cndmask_b32_e64 v53, v53, v67, s[14:15]
	v_cndmask_b32_e64 v67, v49, v71, s[14:15]
	v_cndmask_b32_e64 v66, v48, v72, s[14:15]
	ds_read_b64 v[48:49], v175 offset:1024
	v_cndmask_b32_e64 v64, v63, v55, s[14:15]
	v_mov_b32_e32 v65, 0
	v_cndmask_b32_e64 v69, v58, v50, s[14:15]
	v_mov_b32_e32 v70, 0
	v_mov_b32_dpp v65, v64 quad_perm:[1,0,3,2] row_mask:0xf bank_mask:0xf
	v_cndmask_b32_e64 v64, v59, v51, s[14:15]
	v_mov_b32_dpp v70, v69 quad_perm:[1,0,3,2] row_mask:0xf bank_mask:0xf
	v_mov_b32_e32 v69, 0
	v_cndmask_b32_e64 v63, v65, v63, s[14:15]
	v_cndmask_b32_e64 v60, v68, v60, s[14:15]
	v_mov_b32_dpp v69, v64 quad_perm:[1,0,3,2] row_mask:0xf bank_mask:0xf
	v_cndmask_b32_e64 v59, v69, v59, s[14:15]
	v_cndmask_b32_e64 v58, v70, v58, s[14:15]
	v_cndmask_b32_e64 v57, v71, v57, s[14:15]
	v_cndmask_b32_e64 v56, v72, v56, s[14:15]
	v_cndmask_b32_e64 v55, v55, v65, s[14:15]
	v_cndmask_b32_e64 v65, v51, v69, s[14:15]
	v_cndmask_b32_e64 v64, v50, v70, s[14:15]
	s_waitcnt lgkmcnt(0)
;     __device__ __forceinline__ void operator()(const f32x4 (&acc)[2][2][4][2], const Unit& u, int wr, int wc, int fr, int fq, const EpiCtx& X) const {
;     ...
;         EPI_PIECES({ const unsigned off = lo + (unsigned)(rl * RP) * 2u; LN_ONE(p1a, p1b, rl, off); LN_ONE(p2a, p2b, rl + 1, off + RP * 2); })
	v_pk_fma_f32 v[50:51], v[136:137], v[48:49], v[60:61] op_sel_hi:[1,0,1] neg_lo:[1,0,0] neg_hi:[1,0,0]
	v_pk_fma_f32 v[60:61], v[112:113], v[48:49], v[62:63] op_sel_hi:[1,0,1]
	v_pk_fma_f32 v[56:57], v[132:133], v[48:49], v[56:57] op_sel_hi:[1,0,1] neg_lo:[1,0,0] neg_hi:[1,0,0]
	v_pk_fma_f32 v[58:59], v[114:115], v[48:49], v[58:59] op_sel_hi:[1,0,1]
	v_cndmask_b32_e64 v52, v52, v68, s[14:15]
	v_add_u32_e32 v68, 0x300000, v152
	v_pk_fma_f32 v[60:61], v[48:49], v[60:61], v[142:143] op_sel:[1,0,0]
	v_pk_fma_f32 v[50:51], v[48:49], v[50:51], v[140:141] op_sel:[1,0,0]
	v_pk_fma_f32 v[58:59], v[48:49], v[58:59], v[130:131] op_sel:[1,0,0]
	v_pk_fma_f32 v[56:57], v[48:49], v[56:57], v[128:129] op_sel:[1,0,0]
	v_cvt_pk_bf16_f32 v48, v50, v51
	v_cvt_pk_bf16_f32 v49, v60, v61
	s_nop 0
	v_cvt_pk_bf16_f32 v50, v56, v57
	v_cvt_pk_bf16_f32 v51, v58, v59
	global_store_dwordx4 v68, v[48:51], s[18:19]
	ds_read_b64 v[48:49], v175 offset:1032
	v_mov_b32_e32 v58, 0
	s_waitcnt lgkmcnt(0)
	v_pk_fma_f32 v[50:51], v[136:137], v[48:49], v[52:53] op_sel_hi:[1,0,1] neg_lo:[1,0,0] neg_hi:[1,0,0]
	v_pk_fma_f32 v[52:53], v[112:113], v[48:49], v[54:55] op_sel_hi:[1,0,1]
	v_pk_fma_f32 v[54:55], v[132:133], v[48:49], v[66:67] op_sel_hi:[1,0,1] neg_lo:[1,0,0] neg_hi:[1,0,0]
	v_pk_fma_f32 v[52:53], v[48:49], v[52:53], v[142:143] op_sel:[1,0,0]
	v_pk_fma_f32 v[56:57], v[114:115], v[48:49], v[64:65] op_sel_hi:[1,0,1]
	v_pk_fma_f32 v[50:51], v[48:49], v[50:51], v[140:141] op_sel:[1,0,0]
	v_pk_fma_f32 v[56:57], v[48:49], v[56:57], v[130:131] op_sel:[1,0,0]
	v_pk_fma_f32 v[54:55], v[48:49], v[54:55], v[128:129] op_sel:[1,0,0]
	v_cvt_pk_bf16_f32 v48, v50, v51
	v_cvt_pk_bf16_f32 v49, v52, v53
	v_add_u32_e32 v52, 0x306000, v152
	v_cvt_pk_bf16_f32 v50, v54, v55
	v_cvt_pk_bf16_f32 v51, v56, v57
	global_store_dwordx4 v52, v[48:51], s[18:19]
	ds_read_b64 v[48:49], v175 offset:1152
	v_cndmask_b32_e64 v53, v44, v36, s[14:15]
	v_mov_b32_e32 v54, 0
	v_cndmask_b32_e64 v52, v45, v37, s[14:15]
	v_cndmask_b32_e64 v57, v40, v32, s[14:15]
	v_mov_b32_dpp v54, v53 quad_perm:[1,0,3,2] row_mask:0xf bank_mask:0xf
	v_mov_b32_e32 v53, 0
	v_cndmask_b32_e64 v51, v46, v38, s[14:15]
	v_cndmask_b32_e64 v56, v41, v33, s[14:15]
	v_mov_b32_dpp v53, v52 quad_perm:[1,0,3,2] row_mask:0xf bank_mask:0xf
	v_mov_b32_e32 v52, 0
	v_mov_b32_dpp v58, v57 quad_perm:[1,0,3,2] row_mask:0xf bank_mask:0xf
	v_mov_b32_e32 v57, 0
	v_cndmask_b32_e64 v50, v47, v39, s[14:15]
	v_mov_b32_dpp v52, v51 quad_perm:[1,0,3,2] row_mask:0xf bank_mask:0xf
	v_mov_b32_e32 v51, 0
	v_cndmask_b32_e64 v55, v42, v34, s[14:15]
	v_mov_b32_dpp v57, v56 quad_perm:[1,0,3,2] row_mask:0xf bank_mask:0xf
	v_mov_b32_e32 v56, 0
	v_mov_b32_dpp v51, v50 quad_perm:[1,0,3,2] row_mask:0xf bank_mask:0xf
	v_cndmask_b32_e64 v50, v43, v35, s[14:15]
	v_mov_b32_dpp v56, v55 quad_perm:[1,0,3,2] row_mask:0xf bank_mask:0xf
	v_mov_b32_e32 v55, 0
	v_cndmask_b32_e64 v45, v53, v45, s[14:15]
	v_cndmask_b32_e64 v44, v54, v44, s[14:15]
	v_mov_b32_dpp v55, v50 quad_perm:[1,0,3,2] row_mask:0xf bank_mask:0xf
	v_cndmask_b32_e64 v47, v51, v47, s[14:15]
	v_cndmask_b32_e64 v46, v52, v46, s[14:15]
	v_cndmask_b32_e64 v38, v38, v52, s[14:15]
	v_cndmask_b32_e64 v37, v37, v53, s[14:15]
	v_cndmask_b32_e64 v53, v33, v57, s[14:15]
	v_cndmask_b32_e64 v52, v32, v58, s[14:15]
	s_waitcnt lgkmcnt(0)
	v_pk_fma_f32 v[32:33], v[136:137], v[48:49], v[44:45] op_sel_hi:[1,0,1] neg_lo:[1,0,0] neg_hi:[1,0,0]
	v_cndmask_b32_e64 v43, v55, v43, s[14:15]
	v_cndmask_b32_e64 v42, v56, v42, s[14:15]
	v_cndmask_b32_e64 v41, v57, v41, s[14:15]
	v_cndmask_b32_e64 v40, v58, v40, s[14:15]
	v_cndmask_b32_e64 v39, v39, v51, s[14:15]
	v_cndmask_b32_e64 v51, v35, v55, s[14:15]
	v_cndmask_b32_e64 v50, v34, v56, s[14:15]
	v_pk_fma_f32 v[34:35], v[112:113], v[48:49], v[46:47] op_sel_hi:[1,0,1]
	v_pk_fma_f32 v[32:33], v[48:49], v[32:33], v[140:141] op_sel:[1,0,0]
	v_cndmask_b32_e64 v36, v36, v54, s[14:15]
	v_add_u32_e32 v54, 0x360000, v152
	v_pk_fma_f32 v[34:35], v[48:49], v[34:35], v[142:143] op_sel:[1,0,0]
	v_pk_fma_f32 v[40:41], v[132:133], v[48:49], v[40:41] op_sel_hi:[1,0,1] neg_lo:[1,0,0] neg_hi:[1,0,0]
	v_pk_fma_f32 v[42:43], v[114:115], v[48:49], v[42:43] op_sel_hi:[1,0,1]
	v_cvt_pk_bf16_f32 v32, v32, v33
	v_cvt_pk_bf16_f32 v33, v34, v35
	v_pk_fma_f32 v[40:41], v[48:49], v[40:41], v[128:129] op_sel:[1,0,0]
	v_pk_fma_f32 v[42:43], v[48:49], v[42:43], v[130:131] op_sel:[1,0,0]
	v_cvt_pk_bf16_f32 v34, v40, v41
	s_nop 0
	v_cvt_pk_bf16_f32 v35, v42, v43
	global_store_dwordx4 v54, v[32:35], s[18:19]
	ds_read_b64 v[32:33], v175 offset:1160
	s_waitcnt lgkmcnt(0)
;     __device__ __forceinline__ void operator()(const f32x4 (&acc)[2][2][4][2], const Unit& u, int wr, int wc, int fr, int fq, const EpiCtx& X) const {
;     ...
;         EPI_PIECES({ const unsigned off = lo + (unsigned)(rl * RP) * 2u; LN_ONE(p1a, p1b, rl, off); LN_ONE(p2a, p2b, rl + 1, off + RP * 2); })
	v_pk_fma_f32 v[40:41], v[114:115], v[32:33], v[50:51] op_sel_hi:[1,0,1]
	v_pk_fma_f32 v[34:35], v[136:137], v[32:33], v[36:37] op_sel_hi:[1,0,1] neg_lo:[1,0,0] neg_hi:[1,0,0]
	v_pk_fma_f32 v[36:37], v[112:113], v[32:33], v[38:39] op_sel_hi:[1,0,1]
	v_pk_fma_f32 v[34:35], v[32:33], v[34:35], v[140:141] op_sel:[1,0,0]
	v_pk_fma_f32 v[36:37], v[32:33], v[36:37], v[142:143] op_sel:[1,0,0]
	v_pk_fma_f32 v[38:39], v[132:133], v[32:33], v[52:53] op_sel_hi:[1,0,1] neg_lo:[1,0,0] neg_hi:[1,0,0]
	v_pk_fma_f32 v[40:41], v[32:33], v[40:41], v[130:131] op_sel:[1,0,0]
	v_pk_fma_f32 v[38:39], v[32:33], v[38:39], v[128:129] op_sel:[1,0,0]
	v_cvt_pk_bf16_f32 v32, v34, v35
	v_cvt_pk_bf16_f32 v33, v36, v37
	v_add_u32_e32 v36, 0x366000, v152
	v_cvt_pk_bf16_f32 v34, v38, v39
	v_cvt_pk_bf16_f32 v35, v40, v41
	global_store_dwordx4 v36, v[32:35], s[18:19]
	v_mov_b32_e32 v36, 0
	v_cndmask_b32_e64 v39, v24, v16, s[14:15]
	v_cndmask_b32_e64 v35, v28, v20, s[14:15]
	v_cndmask_b32_e64 v34, v29, v21, s[14:15]
	v_mov_b32_e32 v40, 0
	v_mov_b32_dpp v36, v35 quad_perm:[1,0,3,2] row_mask:0xf bank_mask:0xf
	v_mov_b32_e32 v35, 0
	v_cndmask_b32_e64 v33, v30, v22, s[14:15]
	v_cndmask_b32_e64 v38, v25, v17, s[14:15]
	v_mov_b32_dpp v35, v34 quad_perm:[1,0,3,2] row_mask:0xf bank_mask:0xf
	v_mov_b32_e32 v34, 0
	v_mov_b32_dpp v40, v39 quad_perm:[1,0,3,2] row_mask:0xf bank_mask:0xf
	v_mov_b32_e32 v39, 0
	v_mov_b32_dpp v34, v33 quad_perm:[1,0,3,2] row_mask:0xf bank_mask:0xf
	v_cndmask_b32_e64 v30, v34, v30, s[14:15]
	v_mov_b32_dpp v39, v38 quad_perm:[1,0,3,2] row_mask:0xf bank_mask:0xf
	v_cndmask_b32_e64 v29, v35, v29, s[14:15]
	v_cndmask_b32_e64 v22, v22, v34, s[14:15]
	v_cndmask_b32_e64 v21, v21, v35, s[14:15]
	v_cndmask_b32_e64 v35, v17, v39, s[14:15]
	v_cndmask_b32_e64 v34, v16, v40, s[14:15]
	ds_read_b64 v[16:17], v175 offset:1280
	v_cndmask_b32_e64 v32, v31, v23, s[14:15]
	v_mov_b32_e32 v33, 0
	v_cndmask_b32_e64 v37, v26, v18, s[14:15]
	v_mov_b32_e32 v38, 0
	v_mov_b32_dpp v33, v32 quad_perm:[1,0,3,2] row_mask:0xf bank_mask:0xf
	v_cndmask_b32_e64 v32, v27, v19, s[14:15]
	v_mov_b32_dpp v38, v37 quad_perm:[1,0,3,2] row_mask:0xf bank_mask:0xf
	v_mov_b32_e32 v37, 0
	v_cndmask_b32_e64 v31, v33, v31, s[14:15]
	v_cndmask_b32_e64 v28, v36, v28, s[14:15]
	v_mov_b32_dpp v37, v32 quad_perm:[1,0,3,2] row_mask:0xf bank_mask:0xf
	v_cndmask_b32_e64 v27, v37, v27, s[14:15]
	v_cndmask_b32_e64 v26, v38, v26, s[14:15]
	v_cndmask_b32_e64 v25, v39, v25, s[14:15]
	v_cndmask_b32_e64 v24, v40, v24, s[14:15]
	v_cndmask_b32_e64 v23, v23, v33, s[14:15]
	v_cndmask_b32_e64 v33, v19, v37, s[14:15]
	v_cndmask_b32_e64 v32, v18, v38, s[14:15]
	s_waitcnt lgkmcnt(0)
	v_pk_fma_f32 v[18:19], v[136:137], v[16:17], v[28:29] op_sel_hi:[1,0,1] neg_lo:[1,0,0] neg_hi:[1,0,0]
	v_pk_fma_f32 v[28:29], v[112:113], v[16:17], v[30:31] op_sel_hi:[1,0,1]
	v_pk_fma_f32 v[24:25], v[132:133], v[16:17], v[24:25] op_sel_hi:[1,0,1] neg_lo:[1,0,0] neg_hi:[1,0,0]
	v_pk_fma_f32 v[26:27], v[114:115], v[16:17], v[26:27] op_sel_hi:[1,0,1]
	v_cndmask_b32_e64 v20, v20, v36, s[14:15]
	v_add_u32_e32 v36, 0x3c0000, v152
	v_pk_fma_f32 v[28:29], v[16:17], v[28:29], v[142:143] op_sel:[1,0,0]
	v_pk_fma_f32 v[18:19], v[16:17], v[18:19], v[140:141] op_sel:[1,0,0]
	v_pk_fma_f32 v[26:27], v[16:17], v[26:27], v[130:131] op_sel:[1,0,0]
	v_pk_fma_f32 v[24:25], v[16:17], v[24:25], v[128:129] op_sel:[1,0,0]
	v_cvt_pk_bf16_f32 v16, v18, v19
	v_cvt_pk_bf16_f32 v17, v28, v29
	s_nop 0
	v_cvt_pk_bf16_f32 v18, v24, v25
	v_cvt_pk_bf16_f32 v19, v26, v27
	global_store_dwordx4 v36, v[16:19], s[18:19]
	ds_read_b64 v[16:17], v175 offset:1288
	v_mov_b32_e32 v26, 0
	s_waitcnt lgkmcnt(0)
; #define PG8_BAR __builtin_amdgcn_s_barrier()
; template <class Epi, class Sched, bool ALIGN_EPI>
; __device__ __forceinline__ void gemm_phase(LAS unsigned char* lds, const Gemm g, const Sched& S, const Epi& E, const int wid) {
;     ...
;         if (!has_next) break;
; #pragma unroll
;         for (int a = 0; a < 2; ++a)
; #pragma unroll
;             for (int b = 0; b < 2; ++b)
; #pragma unroll
;                 for (int m = 0; m < 4; ++m)
; #pragma unroll
;                     for (int n = 0; n < 2; ++n) acc[a][b][m][n] = (f32x4){0.f, 0.f, 0.f, 0.f};
;         cur = nxt; cA = nA; cB = nB; ++ui;
;         if constexpr (ALIGN_EPI) { if (wr == 1) PG8_BAR; }
;     }
;     __device__ __forceinline__ void operator()(const f32x4 (&acc)[2][2][4][2], const Unit& u, int wr, int wc, int fr, int fq, const EpiCtx& X) const {
;     ...
;         EPI_PIECES({ const unsigned off = lo + (unsigned)(rl * RP) * 2u; LN_ONE(p1a, p1b, rl, off); LN_ONE(p2a, p2b, rl + 1, off + RP * 2); })
	v_pk_fma_f32 v[18:19], v[136:137], v[16:17], v[20:21] op_sel_hi:[1,0,1] neg_lo:[1,0,0] neg_hi:[1,0,0]
	v_pk_fma_f32 v[20:21], v[112:113], v[16:17], v[22:23] op_sel_hi:[1,0,1]
	v_pk_fma_f32 v[22:23], v[132:133], v[16:17], v[34:35] op_sel_hi:[1,0,1] neg_lo:[1,0,0] neg_hi:[1,0,0]
	v_pk_fma_f32 v[20:21], v[16:17], v[20:21], v[142:143] op_sel:[1,0,0]
	v_pk_fma_f32 v[24:25], v[114:115], v[16:17], v[32:33] op_sel_hi:[1,0,1]
	v_pk_fma_f32 v[18:19], v[16:17], v[18:19], v[140:141] op_sel:[1,0,0]
	v_pk_fma_f32 v[24:25], v[16:17], v[24:25], v[130:131] op_sel:[1,0,0]
	v_pk_fma_f32 v[22:23], v[16:17], v[22:23], v[128:129] op_sel:[1,0,0]
	v_cvt_pk_bf16_f32 v16, v18, v19
	v_cvt_pk_bf16_f32 v17, v20, v21
	v_add_u32_e32 v20, 0x3c6000, v152
	v_cvt_pk_bf16_f32 v18, v22, v23
	v_cvt_pk_bf16_f32 v19, v24, v25
	global_store_dwordx4 v20, v[16:19], s[18:19]
	ds_read_b64 v[16:17], v175 offset:1408
	v_cndmask_b32_e64 v21, v12, v4, s[14:15]
	v_mov_b32_e32 v22, 0
	v_cndmask_b32_e64 v20, v13, v5, s[14:15]
	v_cndmask_b32_e64 v25, v8, v0, s[14:15]
	v_mov_b32_dpp v22, v21 quad_perm:[1,0,3,2] row_mask:0xf bank_mask:0xf
	v_mov_b32_e32 v21, 0
	v_cndmask_b32_e64 v19, v14, v6, s[14:15]
	v_cndmask_b32_e64 v24, v9, v1, s[14:15]
	v_mov_b32_dpp v21, v20 quad_perm:[1,0,3,2] row_mask:0xf bank_mask:0xf
	v_mov_b32_e32 v20, 0
	v_mov_b32_dpp v26, v25 quad_perm:[1,0,3,2] row_mask:0xf bank_mask:0xf
	v_mov_b32_e32 v25, 0
	v_cndmask_b32_e64 v18, v15, v7, s[14:15]
	v_mov_b32_dpp v20, v19 quad_perm:[1,0,3,2] row_mask:0xf bank_mask:0xf
	v_mov_b32_e32 v19, 0
	v_cndmask_b32_e64 v23, v10, v2, s[14:15]
	v_mov_b32_dpp v25, v24 quad_perm:[1,0,3,2] row_mask:0xf bank_mask:0xf
	v_mov_b32_e32 v24, 0
	v_mov_b32_dpp v19, v18 quad_perm:[1,0,3,2] row_mask:0xf bank_mask:0xf
	v_cndmask_b32_e64 v18, v11, v3, s[14:15]
	v_mov_b32_dpp v24, v23 quad_perm:[1,0,3,2] row_mask:0xf bank_mask:0xf
	v_mov_b32_e32 v23, 0
	v_cndmask_b32_e64 v13, v21, v13, s[14:15]
	v_cndmask_b32_e64 v12, v22, v12, s[14:15]
	v_mov_b32_dpp v23, v18 quad_perm:[1,0,3,2] row_mask:0xf bank_mask:0xf
	v_cndmask_b32_e64 v15, v19, v15, s[14:15]
	v_cndmask_b32_e64 v14, v20, v14, s[14:15]
	v_cndmask_b32_e64 v6, v6, v20, s[14:15]
	v_cndmask_b32_e64 v5, v5, v21, s[14:15]
	v_cndmask_b32_e64 v21, v1, v25, s[14:15]
	v_cndmask_b32_e64 v20, v0, v26, s[14:15]
	s_waitcnt lgkmcnt(0)
	v_pk_fma_f32 v[0:1], v[136:137], v[16:17], v[12:13] op_sel_hi:[1,0,1] neg_lo:[1,0,0] neg_hi:[1,0,0]
	v_cndmask_b32_e64 v11, v23, v11, s[14:15]
	v_cndmask_b32_e64 v10, v24, v10, s[14:15]
	v_cndmask_b32_e64 v9, v25, v9, s[14:15]
	v_cndmask_b32_e64 v8, v26, v8, s[14:15]
	v_cndmask_b32_e64 v7, v7, v19, s[14:15]
	v_cndmask_b32_e64 v19, v3, v23, s[14:15]
	v_cndmask_b32_e64 v18, v2, v24, s[14:15]
	v_pk_fma_f32 v[2:3], v[112:113], v[16:17], v[14:15] op_sel_hi:[1,0,1]
	v_pk_fma_f32 v[0:1], v[16:17], v[0:1], v[140:141] op_sel:[1,0,0]
	v_cndmask_b32_e64 v4, v4, v22, s[14:15]
	v_add_u32_e32 v22, 0x420000, v152
	v_pk_fma_f32 v[2:3], v[16:17], v[2:3], v[142:143] op_sel:[1,0,0]
	v_pk_fma_f32 v[8:9], v[132:133], v[16:17], v[8:9] op_sel_hi:[1,0,1] neg_lo:[1,0,0] neg_hi:[1,0,0]
	v_pk_fma_f32 v[10:11], v[114:115], v[16:17], v[10:11] op_sel_hi:[1,0,1]
	v_cvt_pk_bf16_f32 v0, v0, v1
	v_cvt_pk_bf16_f32 v1, v2, v3
	v_pk_fma_f32 v[8:9], v[16:17], v[8:9], v[128:129] op_sel:[1,0,0]
	v_pk_fma_f32 v[10:11], v[16:17], v[10:11], v[130:131] op_sel:[1,0,0]
	v_cvt_pk_bf16_f32 v2, v8, v9
	s_nop 0
	v_cvt_pk_bf16_f32 v3, v10, v11
	global_store_dwordx4 v22, v[0:3], s[18:19]
	ds_read_b64 v[0:1], v175 offset:1416
	s_waitcnt lgkmcnt(0)
	v_pk_fma_f32 v[8:9], v[114:115], v[0:1], v[18:19] op_sel_hi:[1,0,1]
	v_pk_fma_f32 v[2:3], v[136:137], v[0:1], v[4:5] op_sel_hi:[1,0,1] neg_lo:[1,0,0] neg_hi:[1,0,0]
	v_pk_fma_f32 v[4:5], v[112:113], v[0:1], v[6:7] op_sel_hi:[1,0,1]
	v_pk_fma_f32 v[6:7], v[132:133], v[0:1], v[20:21] op_sel_hi:[1,0,1] neg_lo:[1,0,0] neg_hi:[1,0,0]
	v_pk_fma_f32 v[4:5], v[0:1], v[4:5], v[142:143] op_sel:[1,0,0]
	v_pk_fma_f32 v[2:3], v[0:1], v[2:3], v[140:141] op_sel:[1,0,0]
	v_pk_fma_f32 v[8:9], v[0:1], v[8:9], v[130:131] op_sel:[1,0,0]
	v_pk_fma_f32 v[6:7], v[0:1], v[6:7], v[128:129] op_sel:[1,0,0]
	v_cvt_pk_bf16_f32 v0, v2, v3
	v_cvt_pk_bf16_f32 v1, v4, v5
	v_add_u32_e32 v4, 0x426000, v152
	v_cvt_pk_bf16_f32 v2, v6, v7
	v_cvt_pk_bf16_f32 v3, v8, v9
	global_store_dwordx4 v4, v[0:3], s[18:19]
	s_andn2_b64 vcc, exec, s[16:17]
	s_mov_b64 s[16:17], -1
	s_cbranch_vccnz .LBB0_916

; #define LAS __attribute__((address_space(3)))
; __device__ __forceinline__ void build_tbl(const f32x2* PS, int pm, LAS unsigned char* lds, int wid, int lane) {
;     LAS f32x2* tbl = (LAS f32x2*)(lds + TBL_OFF);
;     const f32x2* p = PS + ((size_t)pm * BM + wid * 32) * 64 + lane;
; #pragma unroll 8
;     for (int i = 0; i < 32; ++i) {
;         const f32x2 v = p[(size_t)i * 64];
;         const float a = wave_sum(v.x), b = wave_sum(v.y);
;         if (lane == 0) { const float mu = a * (1.f / DM), var = fmaxf(b * (1.f / DM) - mu * mu, 0.f); tbl[wid * 32 + i] = (f32x2){mu, 1.f / sqrtf(var + LN_EPS)}; }
;     }
; }
; __device__ __forceinline__ void ensure_tbl(const f32x2* PS, int sid, int pm, const EpiCtx& X) {
;     volatile LAS unsigned* keyw = (volatile LAS unsigned*)(X.lds + MISC_OFF) + KEY_WORD;
;     const unsigned key = (unsigned)(sid * 64 + pm + 1);
;     if ((unsigned)__builtin_amdgcn_readfirstlane((int)keyw[0]) != key) {
;         build_tbl(PS, pm, X.lds, X.wid, X.lane);
;         asm volatile("s_waitcnt lgkmcnt(0)" ::: "memory"); __builtin_amdgcn_s_barrier(); asm volatile("" ::: "memory");
;         if (X.tid == 0) keyw[0] = key;
;     }
; }
.LBB0_1573:
	v_mov_b32_e32 v128, s65
	ds_read_b32 v128, v128
	s_add_i32 s25, s52, 0x81
	s_ashr_i32 s53, s52, 31
	s_waitcnt lgkmcnt(0)
	v_readfirstlane_b32 s16, v128
	s_cmp_eq_u32 s16, s25
	s_cbranch_scc1 .LBB0_1595
	s_ashr_i32 s53, s52, 31
	s_lshl_b64 s[16:17], s[52:53], 17
	v_lshl_add_u64 v[222:223], v[154:155], 0, s[16:17]
	s_mov_b64 s[16:17], 0x1000
	global_load_dwordx2 v[128:129], v[222:223], off offset:-2048
	global_load_dwordx2 v[130:131], v[222:223], off offset:-1536
	global_load_dwordx2 v[132:133], v[222:223], off offset:-1024
	global_load_dwordx2 v[134:135], v[222:223], off offset:-512
	global_load_dwordx2 v[136:137], v[222:223], off
	global_load_dwordx2 v[138:139], v[222:223], off offset:512
	global_load_dwordx2 v[170:171], v[222:223], off offset:1024
	global_load_dwordx2 v[172:173], v[222:223], off offset:1536
	v_lshl_add_u64 v[222:223], v[222:223], 0, s[16:17]
	global_load_dwordx2 v[174:175], v[222:223], off offset:-2048
	global_load_dwordx2 v[176:177], v[222:223], off offset:-1536
	global_load_dwordx2 v[178:179], v[222:223], off offset:-1024
	global_load_dwordx2 v[180:181], v[222:223], off offset:-512
	global_load_dwordx2 v[182:183], v[222:223], off
	global_load_dwordx2 v[184:185], v[222:223], off offset:512
	global_load_dwordx2 v[186:187], v[222:223], off offset:1024
	global_load_dwordx2 v[188:189], v[222:223], off offset:1536
	v_lshl_add_u64 v[222:223], v[222:223], 0, s[16:17]
	global_load_dwordx2 v[190:191], v[222:223], off offset:-2048
	global_load_dwordx2 v[192:193], v[222:223], off offset:-1536
	global_load_dwordx2 v[194:195], v[222:223], off offset:-1024
	global_load_dwordx2 v[196:197], v[222:223], off offset:-512
	global_load_dwordx2 v[198:199], v[222:223], off
	global_load_dwordx2 v[200:201], v[222:223], off offset:512
	global_load_dwordx2 v[202:203], v[222:223], off offset:1024
	global_load_dwordx2 v[204:205], v[222:223], off offset:1536
	v_lshl_add_u64 v[222:223], v[222:223], 0, s[16:17]
	global_load_dwordx2 v[206:207], v[222:223], off offset:-2048
	global_load_dwordx2 v[208:209], v[222:223], off offset:-1536
	global_load_dwordx2 v[210:211], v[222:223], off offset:-1024
	global_load_dwordx2 v[212:213], v[222:223], off offset:-512
	global_load_dwordx2 v[214:215], v[222:223], off
	global_load_dwordx2 v[216:217], v[222:223], off offset:512
	global_load_dwordx2 v[218:219], v[222:223], off offset:1024
	global_load_dwordx2 v[220:221], v[222:223], off offset:1536
	s_waitcnt vmcnt(0)
	v_permlane32_swap_b32_e32 v128, v190
	v_permlane32_swap_b32_e32 v129, v191
	v_permlane32_swap_b32_e32 v130, v192
	v_permlane32_swap_b32_e32 v131, v193
	v_permlane32_swap_b32_e32 v132, v194
	v_permlane32_swap_b32_e32 v133, v195
	v_permlane32_swap_b32_e32 v134, v196
	v_permlane32_swap_b32_e32 v135, v197
	v_permlane32_swap_b32_e32 v136, v198
	v_permlane32_swap_b32_e32 v137, v199
	v_permlane32_swap_b32_e32 v138, v200
	v_permlane32_swap_b32_e32 v139, v201
	v_permlane32_swap_b32_e32 v170, v202
	v_permlane32_swap_b32_e32 v171, v203
	v_permlane32_swap_b32_e32 v172, v204
	v_permlane32_swap_b32_e32 v173, v205
	v_permlane32_swap_b32_e32 v174, v206
	v_permlane32_swap_b32_e32 v175, v207
	v_permlane32_swap_b32_e32 v176, v208
	v_permlane32_swap_b32_e32 v177, v209
	v_permlane32_swap_b32_e32 v178, v210
	v_permlane32_swap_b32_e32 v179, v211
	v_permlane32_swap_b32_e32 v180, v212
	v_permlane32_swap_b32_e32 v181, v213
	v_permlane32_swap_b32_e32 v182, v214
	v_permlane32_swap_b32_e32 v183, v215
	v_permlane32_swap_b32_e32 v184, v216
	v_permlane32_swap_b32_e32 v185, v217
	v_permlane32_swap_b32_e32 v186, v218
	v_permlane32_swap_b32_e32 v187, v219
	v_permlane32_swap_b32_e32 v188, v220
	v_permlane32_swap_b32_e32 v189, v221
	v_pk_add_f32 v[128:129], v[128:129], v[190:191]
	v_pk_add_f32 v[130:131], v[130:131], v[192:193]
	v_pk_add_f32 v[132:133], v[132:133], v[194:195]
	v_pk_add_f32 v[134:135], v[134:135], v[196:197]
	v_pk_add_f32 v[136:137], v[136:137], v[198:199]
	v_pk_add_f32 v[138:139], v[138:139], v[200:201]
	v_pk_add_f32 v[170:171], v[170:171], v[202:203]
	v_pk_add_f32 v[172:173], v[172:173], v[204:205]
	v_pk_add_f32 v[174:175], v[174:175], v[206:207]
	v_pk_add_f32 v[176:177], v[176:177], v[208:209]
	v_pk_add_f32 v[178:179], v[178:179], v[210:211]
	v_pk_add_f32 v[180:181], v[180:181], v[212:213]
	v_pk_add_f32 v[182:183], v[182:183], v[214:215]
	v_pk_add_f32 v[184:185], v[184:185], v[216:217]
	v_pk_add_f32 v[186:187], v[186:187], v[218:219]
	v_pk_add_f32 v[188:189], v[188:189], v[220:221]
	s_nop 1
	v_permlane16_swap_b32_e32 v128, v174
	v_permlane16_swap_b32_e32 v129, v175
	v_permlane16_swap_b32_e32 v130, v176
	v_permlane16_swap_b32_e32 v131, v177
	v_permlane16_swap_b32_e32 v132, v178
	v_permlane16_swap_b32_e32 v133, v179
	v_permlane16_swap_b32_e32 v134, v180
	v_permlane16_swap_b32_e32 v135, v181
	v_permlane16_swap_b32_e32 v136, v182
	v_permlane16_swap_b32_e32 v137, v183
	v_permlane16_swap_b32_e32 v138, v184
	v_permlane16_swap_b32_e32 v139, v185
	v_permlane16_swap_b32_e32 v170, v186
	v_permlane16_swap_b32_e32 v171, v187
	v_permlane16_swap_b32_e32 v172, v188
	v_permlane16_swap_b32_e32 v173, v189
	v_pk_add_f32 v[128:129], v[128:129], v[174:175]
	v_pk_add_f32 v[130:131], v[130:131], v[176:177]
	v_pk_add_f32 v[132:133], v[132:133], v[178:179]
	v_pk_add_f32 v[134:135], v[134:135], v[180:181]
	v_pk_add_f32 v[136:137], v[136:137], v[182:183]
	v_pk_add_f32 v[138:139], v[138:139], v[184:185]
	v_pk_add_f32 v[170:171], v[170:171], v[186:187]
	v_pk_add_f32 v[172:173], v[172:173], v[188:189]
	s_nop 1
	v_add_f32_dpp v128, v128, v128 row_ror:8 row_mask:0xf bank_mask:0xf
	v_add_f32_dpp v129, v129, v129 row_ror:8 row_mask:0xf bank_mask:0xf
	v_add_f32_dpp v130, v130, v130 row_ror:8 row_mask:0xf bank_mask:0xf
; #define LAS __attribute__((address_space(3)))
; __device__ __forceinline__ void build_tbl(const f32x2* PS, int pm, LAS unsigned char* lds, int wid, int lane) {
;     LAS f32x2* tbl = (LAS f32x2*)(lds + TBL_OFF);
;     const f32x2* p = PS + ((size_t)pm * BM + wid * 32) * 64 + lane;
; #pragma unroll 8
;     for (int i = 0; i < 32; ++i) {
;         const f32x2 v = p[(size_t)i * 64];
;         const float a = wave_sum(v.x), b = wave_sum(v.y);
;         if (lane == 0) { const float mu = a * (1.f / DM), var = fmaxf(b * (1.f / DM) - mu * mu, 0.f); tbl[wid * 32 + i] = (f32x2){mu, 1.f / sqrtf(var + LN_EPS)}; }
;     }
; }
	v_add_f32_dpp v131, v131, v131 row_ror:8 row_mask:0xf bank_mask:0xf
	v_add_f32_dpp v132, v132, v132 row_ror:8 row_mask:0xf bank_mask:0xf
	v_add_f32_dpp v133, v133, v133 row_ror:8 row_mask:0xf bank_mask:0xf
	v_add_f32_dpp v134, v134, v134 row_ror:8 row_mask:0xf bank_mask:0xf
	v_add_f32_dpp v135, v135, v135 row_ror:8 row_mask:0xf bank_mask:0xf
	v_add_f32_dpp v136, v136, v136 row_ror:8 row_mask:0xf bank_mask:0xf
	v_add_f32_dpp v137, v137, v137 row_ror:8 row_mask:0xf bank_mask:0xf
	v_add_f32_dpp v138, v138, v138 row_ror:8 row_mask:0xf bank_mask:0xf
	v_add_f32_dpp v139, v139, v139 row_ror:8 row_mask:0xf bank_mask:0xf
	v_add_f32_dpp v170, v170, v170 row_ror:8 row_mask:0xf bank_mask:0xf
	v_add_f32_dpp v171, v171, v171 row_ror:8 row_mask:0xf bank_mask:0xf
	v_add_f32_dpp v172, v172, v172 row_ror:8 row_mask:0xf bank_mask:0xf
	v_add_f32_dpp v173, v173, v173 row_ror:8 row_mask:0xf bank_mask:0xf
	v_add_f32_dpp v128, v128, v128 row_ror:4 row_mask:0xf bank_mask:0xf
	v_add_f32_dpp v129, v129, v129 row_ror:4 row_mask:0xf bank_mask:0xf
	v_add_f32_dpp v130, v130, v130 row_ror:4 row_mask:0xf bank_mask:0xf
	v_add_f32_dpp v131, v131, v131 row_ror:4 row_mask:0xf bank_mask:0xf
	v_add_f32_dpp v132, v132, v132 row_ror:4 row_mask:0xf bank_mask:0xf
	v_add_f32_dpp v133, v133, v133 row_ror:4 row_mask:0xf bank_mask:0xf
	v_add_f32_dpp v134, v134, v134 row_ror:4 row_mask:0xf bank_mask:0xf
	v_add_f32_dpp v135, v135, v135 row_ror:4 row_mask:0xf bank_mask:0xf
	v_add_f32_dpp v136, v136, v136 row_ror:4 row_mask:0xf bank_mask:0xf
	v_add_f32_dpp v137, v137, v137 row_ror:4 row_mask:0xf bank_mask:0xf
	v_add_f32_dpp v138, v138, v138 row_ror:4 row_mask:0xf bank_mask:0xf
	v_add_f32_dpp v139, v139, v139 row_ror:4 row_mask:0xf bank_mask:0xf
	v_add_f32_dpp v170, v170, v170 row_ror:4 row_mask:0xf bank_mask:0xf
	v_add_f32_dpp v171, v171, v171 row_ror:4 row_mask:0xf bank_mask:0xf
	v_add_f32_dpp v172, v172, v172 row_ror:4 row_mask:0xf bank_mask:0xf
	v_add_f32_dpp v173, v173, v173 row_ror:4 row_mask:0xf bank_mask:0xf
	v_add_f32_dpp v128, v128, v128 row_ror:2 row_mask:0xf bank_mask:0xf
	v_add_f32_dpp v129, v129, v129 row_ror:2 row_mask:0xf bank_mask:0xf
	v_add_f32_dpp v130, v130, v130 row_ror:2 row_mask:0xf bank_mask:0xf
	v_add_f32_dpp v131, v131, v131 row_ror:2 row_mask:0xf bank_mask:0xf
	v_add_f32_dpp v132, v132, v132 row_ror:2 row_mask:0xf bank_mask:0xf
	v_add_f32_dpp v133, v133, v133 row_ror:2 row_mask:0xf bank_mask:0xf
	v_add_f32_dpp v134, v134, v134 row_ror:2 row_mask:0xf bank_mask:0xf
	v_add_f32_dpp v135, v135, v135 row_ror:2 row_mask:0xf bank_mask:0xf
	v_add_f32_dpp v136, v136, v136 row_ror:2 row_mask:0xf bank_mask:0xf
	v_add_f32_dpp v137, v137, v137 row_ror:2 row_mask:0xf bank_mask:0xf
	v_add_f32_dpp v138, v138, v138 row_ror:2 row_mask:0xf bank_mask:0xf
	v_add_f32_dpp v139, v139, v139 row_ror:2 row_mask:0xf bank_mask:0xf
	v_add_f32_dpp v170, v170, v170 row_ror:2 row_mask:0xf bank_mask:0xf
	v_add_f32_dpp v171, v171, v171 row_ror:2 row_mask:0xf bank_mask:0xf
	v_add_f32_dpp v172, v172, v172 row_ror:2 row_mask:0xf bank_mask:0xf
	v_add_f32_dpp v173, v173, v173 row_ror:2 row_mask:0xf bank_mask:0xf
	v_add_f32_dpp v128, v128, v128 row_ror:1 row_mask:0xf bank_mask:0xf
	v_add_f32_dpp v129, v129, v129 row_ror:1 row_mask:0xf bank_mask:0xf
	v_add_f32_dpp v130, v130, v130 row_ror:1 row_mask:0xf bank_mask:0xf
	v_add_f32_dpp v131, v131, v131 row_ror:1 row_mask:0xf bank_mask:0xf
	v_add_f32_dpp v132, v132, v132 row_ror:1 row_mask:0xf bank_mask:0xf
	v_add_f32_dpp v133, v133, v133 row_ror:1 row_mask:0xf bank_mask:0xf
	v_add_f32_dpp v134, v134, v134 row_ror:1 row_mask:0xf bank_mask:0xf
	v_add_f32_dpp v135, v135, v135 row_ror:1 row_mask:0xf bank_mask:0xf
	v_add_f32_dpp v136, v136, v136 row_ror:1 row_mask:0xf bank_mask:0xf
	v_add_f32_dpp v137, v137, v137 row_ror:1 row_mask:0xf bank_mask:0xf
	v_add_f32_dpp v138, v138, v138 row_ror:1 row_mask:0xf bank_mask:0xf
	v_add_f32_dpp v139, v139, v139 row_ror:1 row_mask:0xf bank_mask:0xf
	v_add_f32_dpp v170, v170, v170 row_ror:1 row_mask:0xf bank_mask:0xf
	v_add_f32_dpp v171, v171, v171 row_ror:1 row_mask:0xf bank_mask:0xf
	v_add_f32_dpp v172, v172, v172 row_ror:1 row_mask:0xf bank_mask:0xf
	v_add_f32_dpp v173, v173, v173 row_ror:1 row_mask:0xf bank_mask:0xf
	s_nop 1
	v_mul_f32_e32 v128, s22, v128
	v_mul_f32_e32 v129, s22, v129
	v_fma_f32 v129, -v128, v128, v129
	v_max_f32_e32 v129, 0, v129
	v_add_f32_e32 v129, 0x3727c5ac, v129
	v_mul_f32_e32 v224, 0x4f800000, v129
	v_cmp_gt_f32_e32 vcc, s66, v129
	s_nop 1
	v_cndmask_b32_e32 v129, v129, v224, vcc
	v_sqrt_f32_e32 v224, v129
	s_nop 0
	v_add_u32_e32 v225, -1, v224
	v_fma_f32 v227, -v225, v224, v129
	v_add_u32_e32 v226, 1, v224
	v_cmp_ge_f32_e64 s[16:17], 0, v227
	s_nop 1
	v_cndmask_b32_e64 v225, v224, v225, s[16:17]
	v_fma_f32 v224, -v226, v224, v129
	v_cmp_lt_f32_e64 s[16:17], 0, v224
	s_nop 1
	v_cndmask_b32_e64 v224, v225, v226, s[16:17]
	v_mul_f32_e32 v225, 0x37800000, v224
	v_cndmask_b32_e32 v224, v224, v225, vcc
	v_cmp_class_f32_e32 vcc, v129, v167
	s_nop 1
	v_cndmask_b32_e32 v129, v224, v129, vcc
	v_div_scale_f32 v224, s[16:17], v129, v129, 1.0
	v_rcp_f32_e32 v225, v224
	s_nop 0
	v_fma_f32 v226, -v224, v225, 1.0
	v_fmac_f32_e32 v225, v226, v225
	v_div_scale_f32 v226, vcc, 1.0, v129, 1.0
	v_mul_f32_e32 v227, v226, v225
	v_fma_f32 v228, -v224, v227, v226
	v_fmac_f32_e32 v227, v228, v225
	v_fma_f32 v224, -v224, v227, v226
	v_div_fmas_f32 v224, v224, v225, v227
	v_div_fixup_f32 v129, v224, v129, 1.0
	v_mul_f32_e32 v130, s22, v130
	v_mul_f32_e32 v131, s22, v131
	v_fma_f32 v131, -v130, v130, v131
	v_max_f32_e32 v131, 0, v131
	v_add_f32_e32 v131, 0x3727c5ac, v131
	v_mul_f32_e32 v224, 0x4f800000, v131
; __device__ __forceinline__ void build_tbl(const f32x2* PS, int pm, LAS unsigned char* lds, int wid, int lane) {
;     ...
;         if (lane == 0) { const float mu = a * (1.f / DM), var = fmaxf(b * (1.f / DM) - mu * mu, 0.f); tbl[wid * 32 + i] = (f32x2){mu, 1.f / sqrtf(var + LN_EPS)}; }
	v_cmp_gt_f32_e32 vcc, s66, v131
	s_nop 1
	v_cndmask_b32_e32 v131, v131, v224, vcc
	v_sqrt_f32_e32 v224, v131
	s_nop 0
	v_add_u32_e32 v225, -1, v224
	v_fma_f32 v227, -v225, v224, v131
	v_add_u32_e32 v226, 1, v224
	v_cmp_ge_f32_e64 s[16:17], 0, v227
	s_nop 1
	v_cndmask_b32_e64 v225, v224, v225, s[16:17]
	v_fma_f32 v224, -v226, v224, v131
	v_cmp_lt_f32_e64 s[16:17], 0, v224
	s_nop 1
	v_cndmask_b32_e64 v224, v225, v226, s[16:17]
	v_mul_f32_e32 v225, 0x37800000, v224
	v_cndmask_b32_e32 v224, v224, v225, vcc
	v_cmp_class_f32_e32 vcc, v131, v167
	s_nop 1
	v_cndmask_b32_e32 v131, v224, v131, vcc
	v_div_scale_f32 v224, s[16:17], v131, v131, 1.0
	v_rcp_f32_e32 v225, v224
	s_nop 0
	v_fma_f32 v226, -v224, v225, 1.0
	v_fmac_f32_e32 v225, v226, v225
	v_div_scale_f32 v226, vcc, 1.0, v131, 1.0
	v_mul_f32_e32 v227, v226, v225
	v_fma_f32 v228, -v224, v227, v226
	v_fmac_f32_e32 v227, v228, v225
	v_fma_f32 v224, -v224, v227, v226
	v_div_fmas_f32 v224, v224, v225, v227
	v_div_fixup_f32 v131, v224, v131, 1.0
	v_mul_f32_e32 v132, s22, v132
	v_mul_f32_e32 v133, s22, v133
	v_fma_f32 v133, -v132, v132, v133
	v_max_f32_e32 v133, 0, v133
	v_add_f32_e32 v133, 0x3727c5ac, v133
	v_mul_f32_e32 v224, 0x4f800000, v133
	v_cmp_gt_f32_e32 vcc, s66, v133
	s_nop 1
	v_cndmask_b32_e32 v133, v133, v224, vcc
	v_sqrt_f32_e32 v224, v133
	s_nop 0
	v_add_u32_e32 v225, -1, v224
	v_fma_f32 v227, -v225, v224, v133
	v_add_u32_e32 v226, 1, v224
	v_cmp_ge_f32_e64 s[16:17], 0, v227
	s_nop 1
	v_cndmask_b32_e64 v225, v224, v225, s[16:17]
	v_fma_f32 v224, -v226, v224, v133
	v_cmp_lt_f32_e64 s[16:17], 0, v224
	s_nop 1
	v_cndmask_b32_e64 v224, v225, v226, s[16:17]
	v_mul_f32_e32 v225, 0x37800000, v224
	v_cndmask_b32_e32 v224, v224, v225, vcc
	v_cmp_class_f32_e32 vcc, v133, v167
	s_nop 1
	v_cndmask_b32_e32 v133, v224, v133, vcc
	v_div_scale_f32 v224, s[16:17], v133, v133, 1.0
	v_rcp_f32_e32 v225, v224
	s_nop 0
	v_fma_f32 v226, -v224, v225, 1.0
	v_fmac_f32_e32 v225, v226, v225
	v_div_scale_f32 v226, vcc, 1.0, v133, 1.0
	v_mul_f32_e32 v227, v226, v225
	v_fma_f32 v228, -v224, v227, v226
	v_fmac_f32_e32 v227, v228, v225
	v_fma_f32 v224, -v224, v227, v226
	v_div_fmas_f32 v224, v224, v225, v227
	v_div_fixup_f32 v133, v224, v133, 1.0
	v_mul_f32_e32 v134, s22, v134
	v_mul_f32_e32 v135, s22, v135
	v_fma_f32 v135, -v134, v134, v135
	v_max_f32_e32 v135, 0, v135
	v_add_f32_e32 v135, 0x3727c5ac, v135
	v_mul_f32_e32 v224, 0x4f800000, v135
	v_cmp_gt_f32_e32 vcc, s66, v135
	s_nop 1
	v_cndmask_b32_e32 v135, v135, v224, vcc
	v_sqrt_f32_e32 v224, v135
	s_nop 0
	v_add_u32_e32 v225, -1, v224
	v_fma_f32 v227, -v225, v224, v135
	v_add_u32_e32 v226, 1, v224
	v_cmp_ge_f32_e64 s[16:17], 0, v227
	s_nop 1
	v_cndmask_b32_e64 v225, v224, v225, s[16:17]
	v_fma_f32 v224, -v226, v224, v135
	v_cmp_lt_f32_e64 s[16:17], 0, v224
	s_nop 1
	v_cndmask_b32_e64 v224, v225, v226, s[16:17]
	v_mul_f32_e32 v225, 0x37800000, v224
	v_cndmask_b32_e32 v224, v224, v225, vcc
	v_cmp_class_f32_e32 vcc, v135, v167
	s_nop 1
	v_cndmask_b32_e32 v135, v224, v135, vcc
	v_div_scale_f32 v224, s[16:17], v135, v135, 1.0
	v_rcp_f32_e32 v225, v224
	s_nop 0
	v_fma_f32 v226, -v224, v225, 1.0
	v_fmac_f32_e32 v225, v226, v225
	v_div_scale_f32 v226, vcc, 1.0, v135, 1.0
	v_mul_f32_e32 v227, v226, v225
	v_fma_f32 v228, -v224, v227, v226
	v_fmac_f32_e32 v227, v228, v225
	v_fma_f32 v224, -v224, v227, v226
	v_div_fmas_f32 v224, v224, v225, v227
	v_div_fixup_f32 v135, v224, v135, 1.0
	v_mul_f32_e32 v136, s22, v136
	v_mul_f32_e32 v137, s22, v137
	v_fma_f32 v137, -v136, v136, v137
	v_max_f32_e32 v137, 0, v137
	v_add_f32_e32 v137, 0x3727c5ac, v137
	v_mul_f32_e32 v224, 0x4f800000, v137
	v_cmp_gt_f32_e32 vcc, s66, v137
	s_nop 1
	v_cndmask_b32_e32 v137, v137, v224, vcc
	v_sqrt_f32_e32 v224, v137
	s_nop 0
	v_add_u32_e32 v225, -1, v224
	v_fma_f32 v227, -v225, v224, v137
	v_add_u32_e32 v226, 1, v224
	v_cmp_ge_f32_e64 s[16:17], 0, v227
	s_nop 1
	v_cndmask_b32_e64 v225, v224, v225, s[16:17]
	v_fma_f32 v224, -v226, v224, v137
	v_cmp_lt_f32_e64 s[16:17], 0, v224
	s_nop 1
	v_cndmask_b32_e64 v224, v225, v226, s[16:17]
	v_mul_f32_e32 v225, 0x37800000, v224
	v_cndmask_b32_e32 v224, v224, v225, vcc
	v_cmp_class_f32_e32 vcc, v137, v167
	s_nop 1
	v_cndmask_b32_e32 v137, v224, v137, vcc
	v_div_scale_f32 v224, s[16:17], v137, v137, 1.0
	v_rcp_f32_e32 v225, v224
	s_nop 0
	v_fma_f32 v226, -v224, v225, 1.0
	v_fmac_f32_e32 v225, v226, v225
	v_div_scale_f32 v226, vcc, 1.0, v137, 1.0
; __device__ __forceinline__ void build_tbl(const f32x2* PS, int pm, LAS unsigned char* lds, int wid, int lane) {
;     ...
;         if (lane == 0) { const float mu = a * (1.f / DM), var = fmaxf(b * (1.f / DM) - mu * mu, 0.f); tbl[wid * 32 + i] = (f32x2){mu, 1.f / sqrtf(var + LN_EPS)}; }
	v_mul_f32_e32 v227, v226, v225
	v_fma_f32 v228, -v224, v227, v226
	v_fmac_f32_e32 v227, v228, v225
	v_fma_f32 v224, -v224, v227, v226
	v_div_fmas_f32 v224, v224, v225, v227
	v_div_fixup_f32 v137, v224, v137, 1.0
	v_mul_f32_e32 v138, s22, v138
	v_mul_f32_e32 v139, s22, v139
	v_fma_f32 v139, -v138, v138, v139
	v_max_f32_e32 v139, 0, v139
	v_add_f32_e32 v139, 0x3727c5ac, v139
	v_mul_f32_e32 v224, 0x4f800000, v139
	v_cmp_gt_f32_e32 vcc, s66, v139
	s_nop 1
	v_cndmask_b32_e32 v139, v139, v224, vcc
	v_sqrt_f32_e32 v224, v139
	s_nop 0
	v_add_u32_e32 v225, -1, v224
	v_fma_f32 v227, -v225, v224, v139
	v_add_u32_e32 v226, 1, v224
	v_cmp_ge_f32_e64 s[16:17], 0, v227
	s_nop 1
	v_cndmask_b32_e64 v225, v224, v225, s[16:17]
	v_fma_f32 v224, -v226, v224, v139
	v_cmp_lt_f32_e64 s[16:17], 0, v224
	s_nop 1
	v_cndmask_b32_e64 v224, v225, v226, s[16:17]
	v_mul_f32_e32 v225, 0x37800000, v224
	v_cndmask_b32_e32 v224, v224, v225, vcc
	v_cmp_class_f32_e32 vcc, v139, v167
	s_nop 1
	v_cndmask_b32_e32 v139, v224, v139, vcc
	v_div_scale_f32 v224, s[16:17], v139, v139, 1.0
	v_rcp_f32_e32 v225, v224
	s_nop 0
	v_fma_f32 v226, -v224, v225, 1.0
	v_fmac_f32_e32 v225, v226, v225
	v_div_scale_f32 v226, vcc, 1.0, v139, 1.0
	v_mul_f32_e32 v227, v226, v225
	v_fma_f32 v228, -v224, v227, v226
	v_fmac_f32_e32 v227, v228, v225
	v_fma_f32 v224, -v224, v227, v226
	v_div_fmas_f32 v224, v224, v225, v227
	v_div_fixup_f32 v139, v224, v139, 1.0
	v_mul_f32_e32 v170, s22, v170
	v_mul_f32_e32 v171, s22, v171
	v_fma_f32 v171, -v170, v170, v171
	v_max_f32_e32 v171, 0, v171
	v_add_f32_e32 v171, 0x3727c5ac, v171
	v_mul_f32_e32 v224, 0x4f800000, v171
	v_cmp_gt_f32_e32 vcc, s66, v171
	s_nop 1
	v_cndmask_b32_e32 v171, v171, v224, vcc
	v_sqrt_f32_e32 v224, v171
	s_nop 0
	v_add_u32_e32 v225, -1, v224
	v_fma_f32 v227, -v225, v224, v171
	v_add_u32_e32 v226, 1, v224
	v_cmp_ge_f32_e64 s[16:17], 0, v227
	s_nop 1
	v_cndmask_b32_e64 v225, v224, v225, s[16:17]
	v_fma_f32 v224, -v226, v224, v171
	v_cmp_lt_f32_e64 s[16:17], 0, v224
	s_nop 1
	v_cndmask_b32_e64 v224, v225, v226, s[16:17]
	v_mul_f32_e32 v225, 0x37800000, v224
	v_cndmask_b32_e32 v224, v224, v225, vcc
	v_cmp_class_f32_e32 vcc, v171, v167
	s_nop 1
	v_cndmask_b32_e32 v171, v224, v171, vcc
	v_div_scale_f32 v224, s[16:17], v171, v171, 1.0
	v_rcp_f32_e32 v225, v224
	s_nop 0
	v_fma_f32 v226, -v224, v225, 1.0
	v_fmac_f32_e32 v225, v226, v225
	v_div_scale_f32 v226, vcc, 1.0, v171, 1.0
	v_mul_f32_e32 v227, v226, v225
	v_fma_f32 v228, -v224, v227, v226
	v_fmac_f32_e32 v227, v228, v225
	v_fma_f32 v224, -v224, v227, v226
	v_div_fmas_f32 v224, v224, v225, v227
	v_div_fixup_f32 v171, v224, v171, 1.0
	v_mul_f32_e32 v172, s22, v172
	v_mul_f32_e32 v173, s22, v173
	v_fma_f32 v173, -v172, v172, v173
	v_max_f32_e32 v173, 0, v173
	v_add_f32_e32 v173, 0x3727c5ac, v173
	v_mul_f32_e32 v224, 0x4f800000, v173
	v_cmp_gt_f32_e32 vcc, s66, v173
	s_nop 1
	v_cndmask_b32_e32 v173, v173, v224, vcc
	v_sqrt_f32_e32 v224, v173
	s_nop 0
	v_add_u32_e32 v225, -1, v224
	v_fma_f32 v227, -v225, v224, v173
	v_add_u32_e32 v226, 1, v224
	v_cmp_ge_f32_e64 s[16:17], 0, v227
	s_nop 1
	v_cndmask_b32_e64 v225, v224, v225, s[16:17]
	v_fma_f32 v224, -v226, v224, v173
	v_cmp_lt_f32_e64 s[16:17], 0, v224
	s_nop 1
	v_cndmask_b32_e64 v224, v225, v226, s[16:17]
	v_mul_f32_e32 v225, 0x37800000, v224
	v_cndmask_b32_e32 v224, v224, v225, vcc
	v_cmp_class_f32_e32 vcc, v173, v167
	s_nop 1
	v_cndmask_b32_e32 v173, v224, v173, vcc
	v_div_scale_f32 v224, s[16:17], v173, v173, 1.0
	v_rcp_f32_e32 v225, v224
	s_nop 0
	v_fma_f32 v226, -v224, v225, 1.0
	v_fmac_f32_e32 v225, v226, v225
	v_div_scale_f32 v226, vcc, 1.0, v173, 1.0
	v_mul_f32_e32 v227, v226, v225
	v_fma_f32 v228, -v224, v227, v226
	v_fmac_f32_e32 v227, v228, v225
	v_fma_f32 v224, -v224, v227, v226
	v_div_fmas_f32 v224, v224, v225, v227
	v_div_fixup_f32 v173, v224, v173, 1.0
	v_lshrrev_b32_e32 v229, 4, v168
	v_lshlrev_b32_e32 v229, 6, v229
	s_add_i32 s16, s62, 0x20400
	v_add_u32_e32 v229, s16, v229
	s_mov_b64 s[56:57], exec
	s_mov_b32 exec_lo, 0x10001
	s_mov_b32 exec_hi, 0x10001
	ds_write_b64 v229, v[128:129]
	ds_write_b64 v229, v[130:131] offset:8
	ds_write_b64 v229, v[132:133] offset:16
	ds_write_b64 v229, v[134:135] offset:24
	ds_write_b64 v229, v[136:137] offset:32
	ds_write_b64 v229, v[138:139] offset:40
	ds_write_b64 v229, v[170:171] offset:48
	ds_write_b64 v229, v[172:173] offset:56
	s_mov_b64 exec, s[56:57]

; #define LAS __attribute__((address_space(3)))
; #define EPI_OPAQUE(x) asm volatile("" : "+v"(x))
;     __device__ __forceinline__ float pre(const Unit& u, int tid) const { return (tid < 256 ? sv : tv)[u.pn * BM + (tid & 255)]; }
;     __device__ __forceinline__ float pre(const Unit& u, int tid) const { return (tid < 256 ? sv : tv)[u.pn * BM + (tid & 255)]; }
;     __device__ __forceinline__ void operator()(const f32x4 (&acc)[2][2][4][2], const Unit& u, int wr, int wc, int fr, int fq, const EpiCtx& X) const {
;     ...
;         LAS float* stb = (LAS float*)(X.lds + STB_OFF);
;         stb[X.tid] = X.pre;
;         asm volatile("s_waitcnt lgkmcnt(0)" ::: "memory"); __builtin_amdgcn_s_barrier(); asm volatile("" ::: "memory");
;         const bool odd = fr & 1; const int fe = fr - (fr & 1), o32 = (fr & 1) * 32;
;         constexpr int RP = BLK ? 64 : LDC;
;         char* base = BLK ? (char*)(O + (size_t)u.pm * BM * LDC + (size_t)(u.pn * 4 + wc) * (BM * 64)) : (char*)(O + (size_t)u.pm * BM * LDC + u.pn * BM);
;         unsigned lo = (unsigned)((wr * 64 + fe) * RP + (BLK ? 0 : wc * 64) + o32 + 8 * fq) * 2u; EPI_OPAQUE(lo);
;         const LAS f32x2* tbl = (const LAS f32x2*)(X.lds + TBL_OFF) + wr * 64 + fe;
;         const LAS f32x4* sp = (const LAS f32x4*)(stb + wc * 64 + o32 + 8 * fq);
;         const f32x4 sa = sp[0], sb = sp[1], ta = sp[64], tb = sp[65];
;     ...
;         EPI_PIECES({ const unsigned off = lo + (unsigned)(rl * RP) * 2u; LN_ONE(p1a, p1b, rl, off); LN_ONE(p2a, p2b, rl + 1, off + RP * 2); })
.LBB0_1595:
	v_cndmask_b32_e64 v171, v127, v119, s[12:13]
	v_cndmask_b32_e64 v172, v126, v118, s[12:13]
	v_cndmask_b32_e64 v173, v125, v117, s[12:13]
	v_cndmask_b32_e64 v174, v124, v116, s[12:13]
	v_mov_b32_e32 v180, 0
	v_mov_b32_e32 v181, 0
	v_mov_b32_e32 v178, 0
	v_mov_b32_e32 v179, 0
	v_mov_b32_dpp v180, v174 quad_perm:[1,0,3,2] row_mask:0xf bank_mask:0xf
	v_mov_b32_dpp v181, v173 quad_perm:[1,0,3,2] row_mask:0xf bank_mask:0xf
	v_mov_b32_dpp v178, v172 quad_perm:[1,0,3,2] row_mask:0xf bank_mask:0xf
	v_mov_b32_dpp v179, v171 quad_perm:[1,0,3,2] row_mask:0xf bank_mask:0xf
	v_cndmask_b32_e64 v171, v123, v115, s[12:13]
	v_cndmask_b32_e64 v172, v122, v114, s[12:13]
	v_cndmask_b32_e64 v173, v121, v113, s[12:13]
	v_cndmask_b32_e64 v174, v120, v112, s[12:13]
	v_mov_b32_e32 v182, 0
	v_mov_b32_e32 v183, 0
	v_mov_b32_e32 v184, 0
	v_mov_b32_e32 v185, 0
	s_waitcnt vmcnt(16)
	ds_write_b32 v162, v169
	v_mov_b32_e32 v170, v163
	v_mov_b32_dpp v182, v174 quad_perm:[1,0,3,2] row_mask:0xf bank_mask:0xf
	v_mov_b32_dpp v183, v173 quad_perm:[1,0,3,2] row_mask:0xf bank_mask:0xf
	v_mov_b32_dpp v184, v172 quad_perm:[1,0,3,2] row_mask:0xf bank_mask:0xf
	v_mov_b32_dpp v185, v171 quad_perm:[1,0,3,2] row_mask:0xf bank_mask:0xf
	s_waitcnt lgkmcnt(0)
	s_barrier
	s_waitcnt lgkmcnt(1)
	ds_read_b128 v[132:135], v165 offset:16
	ds_read_b128 v[136:139], v165 offset:1024
	ds_read_b128 v[128:131], v165 offset:1040
	v_cndmask_b32_e64 v173, v185, v123, s[12:13]
	v_cndmask_b32_e64 v172, v184, v122, s[12:13]
	v_cndmask_b32_e64 v175, v183, v121, s[12:13]
	v_cndmask_b32_e64 v174, v182, v120, s[12:13]
	ds_read_b128 v[120:123], v165
	ds_read_b64 v[176:177], v164
	v_cndmask_b32_e64 v125, v181, v125, s[12:13]
	v_cndmask_b32_e64 v124, v180, v124, s[12:13]
	v_cndmask_b32_e64 v127, v179, v127, s[12:13]
	v_cndmask_b32_e64 v126, v178, v126, s[12:13]
	v_cndmask_b32_e64 v179, v119, v179, s[12:13]
	v_cndmask_b32_e64 v178, v118, v178, s[12:13]
	v_cndmask_b32_e64 v181, v117, v181, s[12:13]
	v_cndmask_b32_e64 v180, v116, v180, s[12:13]
	s_waitcnt lgkmcnt(0)
	v_pk_fma_f32 v[118:119], v[120:121], v[176:177], v[124:125] op_sel_hi:[1,0,1] neg_lo:[1,0,0] neg_hi:[1,0,0]
	v_xor_b32_e32 v117, 0x80000000, v123
	v_xor_b32_e32 v116, 0x80000000, v122
	v_pk_fma_f32 v[122:123], v[116:117], v[176:177], v[126:127] op_sel_hi:[1,0,1]
	v_pk_fma_f32 v[124:125], v[176:177], v[118:119], v[136:137] op_sel:[1,0,0]
	v_pk_fma_f32 v[126:127], v[132:133], v[176:177], v[174:175] op_sel_hi:[1,0,1] neg_lo:[1,0,0] neg_hi:[1,0,0]
	v_xor_b32_e32 v119, 0x80000000, v135
	v_xor_b32_e32 v118, 0x80000000, v134
	v_pk_fma_f32 v[122:123], v[176:177], v[122:123], v[138:139] op_sel:[1,0,0]
	v_pk_fma_f32 v[134:135], v[118:119], v[176:177], v[172:173] op_sel_hi:[1,0,1]
	v_pk_fma_f32 v[126:127], v[176:177], v[126:127], v[128:129] op_sel:[1,0,0]
	s_lshl_b64 s[16:17], s[52:53], 23
	v_pk_fma_f32 v[134:135], v[176:177], v[134:135], v[130:131] op_sel:[1,0,0]
	v_max_f32_e32 v124, 0, v124
	v_max_f32_e32 v126, 0, v126
	v_max_f32_e32 v125, 0, v125
	v_max_f32_e32 v127, 0, v127
	v_max_f32_e32 v122, 0, v122
	s_add_u32 s25, s46, s16
	v_mul_f32_e32 v124, v124, v124
	v_mul_f32_e32 v126, v126, v126
	v_mul_f32_e32 v125, v125, v125
	v_mul_f32_e32 v127, v127, v127
	v_max_f32_e32 v134, 0, v134
	v_mul_f32_e32 v171, v122, v122
	v_max_f32_e32 v122, 0, v123
	v_max_f32_e32 v123, 0, v135
	s_addc_u32 s27, s47, s17
	s_lshl_b32 s16, s67, 2
	v_mul_f32_e32 v134, v134, v134
	v_mul_f32_e32 v135, v122, v122
	v_mul_f32_e32 v172, v123, v123
	v_cvt_pk_bf16_f32 v122, v124, v125
	v_cvt_pk_bf16_f32 v123, v171, v135
	v_cvt_pk_bf16_f32 v124, v126, v127
	v_cvt_pk_bf16_f32 v125, v134, v172
	ds_read_b64 v[126:127], v164 offset:8
	s_or_b32 s16, s16, s41
	s_ashr_i32 s17, s16, 31
	s_lshl_b64 s[16:17], s[16:17], 15
	s_add_u32 s16, s25, s16
	v_cndmask_b32_e64 v113, v113, v183, s[12:13]
	v_cndmask_b32_e64 v112, v112, v182, s[12:13]
	s_addc_u32 s17, s27, s17
	v_cndmask_b32_e64 v115, v115, v185, s[12:13]
	v_cndmask_b32_e64 v114, v114, v184, s[12:13]
	s_waitcnt lgkmcnt(0)
	v_pk_fma_f32 v[112:113], v[132:133], v[126:127], v[112:113] op_sel_hi:[1,0,1] neg_lo:[1,0,0] neg_hi:[1,0,0]
	global_store_dwordx4 v170, v[122:125], s[16:17] nt
	v_pk_fma_f32 v[114:115], v[118:119], v[126:127], v[114:115] op_sel_hi:[1,0,1]
	v_pk_fma_f32 v[112:113], v[126:127], v[112:113], v[128:129] op_sel:[1,0,0]
	v_pk_fma_f32 v[122:123], v[120:121], v[126:127], v[180:181] op_sel_hi:[1,0,1] neg_lo:[1,0,0] neg_hi:[1,0,0]
	v_pk_fma_f32 v[124:125], v[116:117], v[126:127], v[178:179] op_sel_hi:[1,0,1]
	v_pk_fma_f32 v[122:123], v[126:127], v[122:123], v[136:137] op_sel:[1,0,0]
	v_pk_fma_f32 v[124:125], v[126:127], v[124:125], v[138:139] op_sel:[1,0,0]
	v_pk_fma_f32 v[114:115], v[126:127], v[114:115], v[130:131] op_sel:[1,0,0]
	v_max_f32_e32 v112, 0, v112
	v_max_f32_e32 v113, 0, v113
	v_max_f32_e32 v122, 0, v122
	v_mul_f32_e32 v126, v112, v112
	v_max_f32_e32 v112, 0, v123
	v_mul_f32_e32 v123, v113, v113
	v_max_f32_e32 v113, 0, v124
	v_max_f32_e32 v114, 0, v114
	v_mul_f32_e32 v122, v122, v122
	v_mul_f32_e32 v112, v112, v112
	v_mul_f32_e32 v113, v113, v113
	v_mul_f32_e32 v124, v114, v114
	v_max_f32_e32 v114, 0, v125
	v_max_f32_e32 v115, 0, v115
	v_mul_f32_e32 v114, v114, v114
	v_mul_f32_e32 v115, v115, v115
	v_cvt_pk_bf16_f32 v112, v122, v112
	v_cvt_pk_bf16_f32 v113, v113, v114
	v_add_u32_e32 v122, 0x80, v170
	v_cvt_pk_bf16_f32 v114, v126, v123
	v_cvt_pk_bf16_f32 v115, v124, v115
	global_store_dwordx4 v122, v[112:115], s[16:17] nt
	ds_read_b64 v[112:113], v164 offset:128
	v_cndmask_b32_e64 v123, v108, v100, s[12:13]
	v_mov_b32_e32 v124, 0
	v_cndmask_b32_e64 v127, v104, v96, s[12:13]
	v_mov_b32_e32 v134, 0
	v_cndmask_b32_e64 v122, v109, v101, s[12:13]
	v_mov_b32_dpp v124, v123 quad_perm:[1,0,3,2] row_mask:0xf bank_mask:0xf
	v_mov_b32_e32 v123, 0
	v_cndmask_b32_e64 v126, v105, v97, s[12:13]
	v_mov_b32_dpp v134, v127 quad_perm:[1,0,3,2] row_mask:0xf bank_mask:0xf
	v_mov_b32_e32 v127, 0
	v_cndmask_b32_e64 v115, v110, v102, s[12:13]
	v_mov_b32_dpp v123, v122 quad_perm:[1,0,3,2] row_mask:0xf bank_mask:0xf
	v_mov_b32_e32 v122, 0
	v_mov_b32_dpp v127, v126 quad_perm:[1,0,3,2] row_mask:0xf bank_mask:0xf
	v_cndmask_b32_e64 v114, v111, v103, s[12:13]
	v_mov_b32_dpp v122, v115 quad_perm:[1,0,3,2] row_mask:0xf bank_mask:0xf
	v_mov_b32_e32 v115, 0
	v_cndmask_b32_e64 v125, v106, v98, s[12:13]
	v_mov_b32_e32 v126, 0
	v_cndmask_b32_e64 v105, v127, v105, s[12:13]
	v_cndmask_b32_e64 v104, v134, v104, s[12:13]
	v_mov_b32_dpp v115, v114 quad_perm:[1,0,3,2] row_mask:0xf bank_mask:0xf
	v_cndmask_b32_e64 v114, v107, v99, s[12:13]
	v_mov_b32_dpp v126, v125 quad_perm:[1,0,3,2] row_mask:0xf bank_mask:0xf
	v_mov_b32_e32 v125, 0
	s_waitcnt lgkmcnt(0)
;     __device__ __forceinline__ void operator()(const f32x4 (&acc)[2][2][4][2], const Unit& u, int wr, int wc, int fr, int fq, const EpiCtx& X) const {
;     ...
;         EPI_PIECES({ const unsigned off = lo + (unsigned)(rl * RP) * 2u; LN_ONE(p1a, p1b, rl, off); LN_ONE(p2a, p2b, rl + 1, off + RP * 2); })
	v_pk_fma_f32 v[104:105], v[132:133], v[112:113], v[104:105] op_sel_hi:[1,0,1] neg_lo:[1,0,0] neg_hi:[1,0,0]
	v_cndmask_b32_e64 v111, v115, v111, s[12:13]
	v_mov_b32_dpp v125, v114 quad_perm:[1,0,3,2] row_mask:0xf bank_mask:0xf
	v_cndmask_b32_e64 v110, v122, v110, s[12:13]
	v_cndmask_b32_e64 v109, v123, v109, s[12:13]
	v_cndmask_b32_e64 v108, v124, v108, s[12:13]
	v_pk_fma_f32 v[104:105], v[112:113], v[104:105], v[128:129] op_sel:[1,0,0]
	v_cndmask_b32_e64 v107, v125, v107, s[12:13]
	v_cndmask_b32_e64 v106, v126, v106, s[12:13]
	v_cndmask_b32_e64 v103, v103, v115, s[12:13]
	v_cndmask_b32_e64 v115, v101, v123, s[12:13]
	v_cndmask_b32_e64 v114, v100, v124, s[12:13]
	v_pk_fma_f32 v[100:101], v[120:121], v[112:113], v[108:109] op_sel_hi:[1,0,1] neg_lo:[1,0,0] neg_hi:[1,0,0]
	v_pk_fma_f32 v[108:109], v[116:117], v[112:113], v[110:111] op_sel_hi:[1,0,1]
	v_max_f32_e32 v104, 0, v104
	v_pk_fma_f32 v[108:109], v[112:113], v[108:109], v[138:139] op_sel:[1,0,0]
	v_pk_fma_f32 v[106:107], v[118:119], v[112:113], v[106:107] op_sel_hi:[1,0,1]
	v_mul_f32_e32 v110, v104, v104
	v_max_f32_e32 v104, 0, v105
	v_pk_fma_f32 v[100:101], v[112:113], v[100:101], v[136:137] op_sel:[1,0,0]
	v_pk_fma_f32 v[106:107], v[112:113], v[106:107], v[130:131] op_sel:[1,0,0]
	v_mul_f32_e32 v111, v104, v104
	v_max_f32_e32 v104, 0, v108
	v_max_f32_e32 v100, 0, v100
	v_max_f32_e32 v101, 0, v101
	v_max_f32_e32 v105, 0, v106
	v_mul_f32_e32 v106, v104, v104
	v_max_f32_e32 v104, 0, v109
	v_mul_f32_e32 v100, v100, v100
	v_mul_f32_e32 v101, v101, v101
	v_mul_f32_e32 v108, v105, v105
	v_max_f32_e32 v105, 0, v107
	v_mul_f32_e32 v107, v104, v104
	v_mul_f32_e32 v109, v105, v105
	v_cndmask_b32_e64 v105, v99, v125, s[12:13]
	v_cndmask_b32_e64 v104, v98, v126, s[12:13]
	v_cvt_pk_bf16_f32 v98, v100, v101
	v_cvt_pk_bf16_f32 v99, v106, v107
	v_cvt_pk_bf16_f32 v100, v110, v111
	v_cvt_pk_bf16_f32 v101, v108, v109
	ds_read_b64 v[106:107], v164 offset:136
	v_cndmask_b32_e64 v97, v97, v127, s[12:13]
	v_cndmask_b32_e64 v96, v96, v134, s[12:13]
	v_cndmask_b32_e64 v102, v102, v122, s[12:13]
	v_add_u32_e32 v108, 0x800, v170
	s_waitcnt lgkmcnt(0)
	v_pk_fma_f32 v[96:97], v[132:133], v[106:107], v[96:97] op_sel_hi:[1,0,1] neg_lo:[1,0,0] neg_hi:[1,0,0]
	global_store_dwordx4 v108, v[98:101], s[16:17] nt
	v_pk_fma_f32 v[96:97], v[106:107], v[96:97], v[128:129] op_sel:[1,0,0]
	s_andn2_b64 vcc, exec, s[14:15]
	v_pk_fma_f32 v[98:99], v[120:121], v[106:107], v[114:115] op_sel_hi:[1,0,1] neg_lo:[1,0,0] neg_hi:[1,0,0]
	v_pk_fma_f32 v[100:101], v[116:117], v[106:107], v[102:103] op_sel_hi:[1,0,1]
	v_pk_fma_f32 v[102:103], v[118:119], v[106:107], v[104:105] op_sel_hi:[1,0,1]
	v_pk_fma_f32 v[100:101], v[106:107], v[100:101], v[138:139] op_sel:[1,0,0]
	v_pk_fma_f32 v[98:99], v[106:107], v[98:99], v[136:137] op_sel:[1,0,0]
	v_pk_fma_f32 v[102:103], v[106:107], v[102:103], v[130:131] op_sel:[1,0,0]
	v_max_f32_e32 v96, 0, v96
	v_max_f32_e32 v97, 0, v97
	v_max_f32_e32 v98, 0, v98
	v_mul_f32_e32 v104, v96, v96
	v_max_f32_e32 v96, 0, v99
	v_mul_f32_e32 v99, v97, v97
	v_max_f32_e32 v97, 0, v100
	v_max_f32_e32 v100, 0, v102
	v_mul_f32_e32 v98, v98, v98
	v_mul_f32_e32 v96, v96, v96
	v_mul_f32_e32 v97, v97, v97
	v_mul_f32_e32 v100, v100, v100
	v_max_f32_e32 v101, 0, v101
	v_max_f32_e32 v102, 0, v103
	v_mul_f32_e32 v101, v101, v101
	v_mul_f32_e32 v102, v102, v102
	v_cvt_pk_bf16_f32 v96, v98, v96
	v_cvt_pk_bf16_f32 v97, v97, v101
	v_cvt_pk_bf16_f32 v98, v104, v99
	v_cvt_pk_bf16_f32 v99, v100, v102
	v_add_u32_e32 v100, 0x880, v170
	global_store_dwordx4 v100, v[96:99], s[16:17] nt
	v_mov_b32_e32 v100, 0
	v_cndmask_b32_e64 v103, v88, v80, s[12:13]
	v_cndmask_b32_e64 v99, v92, v84, s[12:13]
	v_cndmask_b32_e64 v98, v93, v85, s[12:13]
	v_mov_b32_e32 v104, 0
	v_mov_b32_dpp v100, v99 quad_perm:[1,0,3,2] row_mask:0xf bank_mask:0xf
	v_mov_b32_e32 v99, 0
	v_cndmask_b32_e64 v96, v95, v87, s[12:13]
	v_cndmask_b32_e64 v97, v94, v86, s[12:13]
	v_mov_b32_dpp v99, v98 quad_perm:[1,0,3,2] row_mask:0xf bank_mask:0xf
	v_mov_b32_e32 v98, 0
	v_mov_b32_e32 v101, 0
	v_cndmask_b32_e64 v102, v89, v81, s[12:13]
	v_mov_b32_dpp v104, v103 quad_perm:[1,0,3,2] row_mask:0xf bank_mask:0xf
	v_mov_b32_e32 v103, 0
	v_mov_b32_dpp v98, v97 quad_perm:[1,0,3,2] row_mask:0xf bank_mask:0xf
	v_mov_b32_dpp v101, v96 quad_perm:[1,0,3,2] row_mask:0xf bank_mask:0xf
	v_cndmask_b32_e64 v96, v91, v83, s[12:13]
	v_cndmask_b32_e64 v97, v90, v82, s[12:13]
	v_mov_b32_dpp v103, v102 quad_perm:[1,0,3,2] row_mask:0xf bank_mask:0xf
	v_mov_b32_e32 v102, 0
	v_mov_b32_e32 v105, 0
	v_cndmask_b32_e64 v89, v103, v89, s[12:13]
	v_mov_b32_dpp v102, v97 quad_perm:[1,0,3,2] row_mask:0xf bank_mask:0xf
	v_mov_b32_dpp v105, v96 quad_perm:[1,0,3,2] row_mask:0xf bank_mask:0xf
	ds_read_b64 v[96:97], v164 offset:256
	v_cndmask_b32_e64 v88, v104, v88, s[12:13]
	v_cndmask_b32_e64 v95, v101, v95, s[12:13]
	v_cndmask_b32_e64 v94, v98, v94, s[12:13]
	v_cndmask_b32_e64 v93, v99, v93, s[12:13]
	s_waitcnt lgkmcnt(0)
;     __device__ __forceinline__ void operator()(const f32x4 (&acc)[2][2][4][2], const Unit& u, int wr, int wc, int fr, int fq, const EpiCtx& X) const {
;     ...
;         EPI_PIECES({ const unsigned off = lo + (unsigned)(rl * RP) * 2u; LN_ONE(p1a, p1b, rl, off); LN_ONE(p2a, p2b, rl + 1, off + RP * 2); })
	v_pk_fma_f32 v[88:89], v[132:133], v[96:97], v[88:89] op_sel_hi:[1,0,1] neg_lo:[1,0,0] neg_hi:[1,0,0]
	v_cndmask_b32_e64 v92, v100, v92, s[12:13]
	v_pk_fma_f32 v[88:89], v[96:97], v[88:89], v[128:129] op_sel:[1,0,0]
	v_cndmask_b32_e64 v91, v105, v91, s[12:13]
	v_cndmask_b32_e64 v90, v102, v90, s[12:13]
	v_cndmask_b32_e64 v86, v86, v98, s[12:13]
	v_cndmask_b32_e64 v99, v85, v99, s[12:13]
	v_cndmask_b32_e64 v98, v84, v100, s[12:13]
	v_pk_fma_f32 v[84:85], v[120:121], v[96:97], v[92:93] op_sel_hi:[1,0,1] neg_lo:[1,0,0] neg_hi:[1,0,0]
	v_pk_fma_f32 v[92:93], v[116:117], v[96:97], v[94:95] op_sel_hi:[1,0,1]
	v_max_f32_e32 v88, 0, v88
	v_pk_fma_f32 v[92:93], v[96:97], v[92:93], v[138:139] op_sel:[1,0,0]
	v_pk_fma_f32 v[90:91], v[118:119], v[96:97], v[90:91] op_sel_hi:[1,0,1]
	v_mul_f32_e32 v94, v88, v88
	v_max_f32_e32 v88, 0, v89
	v_pk_fma_f32 v[84:85], v[96:97], v[84:85], v[136:137] op_sel:[1,0,0]
	v_pk_fma_f32 v[90:91], v[96:97], v[90:91], v[130:131] op_sel:[1,0,0]
	v_mul_f32_e32 v95, v88, v88
	v_max_f32_e32 v88, 0, v92
	v_max_f32_e32 v84, 0, v84
	v_max_f32_e32 v85, 0, v85
	v_max_f32_e32 v89, 0, v90
	v_mul_f32_e32 v90, v88, v88
	v_max_f32_e32 v88, 0, v93
	v_mul_f32_e32 v84, v84, v84
	v_mul_f32_e32 v85, v85, v85
	v_mul_f32_e32 v92, v89, v89
	v_max_f32_e32 v89, 0, v91
	v_mul_f32_e32 v91, v88, v88
	v_mul_f32_e32 v93, v89, v89
	v_cndmask_b32_e64 v89, v83, v105, s[12:13]
	v_cndmask_b32_e64 v88, v82, v102, s[12:13]
	v_cvt_pk_bf16_f32 v82, v84, v85
	v_cvt_pk_bf16_f32 v83, v90, v91
	v_cvt_pk_bf16_f32 v84, v94, v95
	v_cvt_pk_bf16_f32 v85, v92, v93
	ds_read_b64 v[90:91], v164 offset:264
	v_cndmask_b32_e64 v81, v81, v103, s[12:13]
	v_cndmask_b32_e64 v80, v80, v104, s[12:13]
	v_cndmask_b32_e64 v87, v87, v101, s[12:13]
	v_add_u32_e32 v92, 0x1000, v170
	s_waitcnt lgkmcnt(0)
	v_pk_fma_f32 v[80:81], v[132:133], v[90:91], v[80:81] op_sel_hi:[1,0,1] neg_lo:[1,0,0] neg_hi:[1,0,0]
	global_store_dwordx4 v92, v[82:85], s[16:17] nt
	v_pk_fma_f32 v[80:81], v[90:91], v[80:81], v[128:129] op_sel:[1,0,0]
	s_mov_b64 s[14:15], -1
	v_pk_fma_f32 v[82:83], v[120:121], v[90:91], v[98:99] op_sel_hi:[1,0,1] neg_lo:[1,0,0] neg_hi:[1,0,0]
	v_pk_fma_f32 v[84:85], v[116:117], v[90:91], v[86:87] op_sel_hi:[1,0,1]
	v_pk_fma_f32 v[86:87], v[118:119], v[90:91], v[88:89] op_sel_hi:[1,0,1]
	v_pk_fma_f32 v[84:85], v[90:91], v[84:85], v[138:139] op_sel:[1,0,0]
	v_pk_fma_f32 v[82:83], v[90:91], v[82:83], v[136:137] op_sel:[1,0,0]
	v_pk_fma_f32 v[86:87], v[90:91], v[86:87], v[130:131] op_sel:[1,0,0]
	v_max_f32_e32 v80, 0, v80
	v_max_f32_e32 v81, 0, v81
	v_max_f32_e32 v82, 0, v82
	v_mul_f32_e32 v88, v80, v80
	v_max_f32_e32 v80, 0, v83
	v_mul_f32_e32 v83, v81, v81
	v_max_f32_e32 v81, 0, v84
	v_max_f32_e32 v84, 0, v86
	v_mul_f32_e32 v82, v82, v82
	v_mul_f32_e32 v80, v80, v80
	v_mul_f32_e32 v81, v81, v81
	v_mul_f32_e32 v84, v84, v84
	v_max_f32_e32 v85, 0, v85
	v_max_f32_e32 v86, 0, v87
	v_mul_f32_e32 v85, v85, v85
	v_mul_f32_e32 v86, v86, v86
	v_cvt_pk_bf16_f32 v80, v82, v80
	v_cvt_pk_bf16_f32 v81, v81, v85
	v_cvt_pk_bf16_f32 v82, v88, v83
	v_cvt_pk_bf16_f32 v83, v84, v86
	v_add_u32_e32 v84, 0x1080, v170
	global_store_dwordx4 v84, v[80:83], s[16:17] nt
	ds_read_b64 v[80:81], v164 offset:384
	v_cndmask_b32_e64 v85, v76, v68, s[12:13]
	v_mov_b32_e32 v86, 0
	v_cndmask_b32_e64 v89, v72, v64, s[12:13]
	v_mov_b32_e32 v90, 0
	v_cndmask_b32_e64 v84, v77, v69, s[12:13]
	v_mov_b32_dpp v86, v85 quad_perm:[1,0,3,2] row_mask:0xf bank_mask:0xf
	v_mov_b32_e32 v85, 0
	v_cndmask_b32_e64 v88, v73, v65, s[12:13]
	v_mov_b32_dpp v90, v89 quad_perm:[1,0,3,2] row_mask:0xf bank_mask:0xf
	v_mov_b32_e32 v89, 0
	v_cndmask_b32_e64 v83, v78, v70, s[12:13]
	v_mov_b32_dpp v85, v84 quad_perm:[1,0,3,2] row_mask:0xf bank_mask:0xf
	v_mov_b32_e32 v84, 0
	v_mov_b32_dpp v89, v88 quad_perm:[1,0,3,2] row_mask:0xf bank_mask:0xf
	v_cndmask_b32_e64 v82, v79, v71, s[12:13]
	v_mov_b32_dpp v84, v83 quad_perm:[1,0,3,2] row_mask:0xf bank_mask:0xf
	v_mov_b32_e32 v83, 0
	v_cndmask_b32_e64 v87, v74, v66, s[12:13]
	v_mov_b32_e32 v88, 0
	v_cndmask_b32_e64 v73, v89, v73, s[12:13]
	v_cndmask_b32_e64 v72, v90, v72, s[12:13]
	v_mov_b32_dpp v83, v82 quad_perm:[1,0,3,2] row_mask:0xf bank_mask:0xf
	v_cndmask_b32_e64 v82, v75, v67, s[12:13]
	v_mov_b32_dpp v88, v87 quad_perm:[1,0,3,2] row_mask:0xf bank_mask:0xf
	v_mov_b32_e32 v87, 0
	s_waitcnt lgkmcnt(0)
	v_pk_fma_f32 v[72:73], v[132:133], v[80:81], v[72:73] op_sel_hi:[1,0,1] neg_lo:[1,0,0] neg_hi:[1,0,0]
	v_cndmask_b32_e64 v79, v83, v79, s[12:13]
	v_mov_b32_dpp v87, v82 quad_perm:[1,0,3,2] row_mask:0xf bank_mask:0xf
	v_cndmask_b32_e64 v78, v84, v78, s[12:13]
	v_cndmask_b32_e64 v77, v85, v77, s[12:13]
	v_cndmask_b32_e64 v76, v86, v76, s[12:13]
	v_pk_fma_f32 v[72:73], v[80:81], v[72:73], v[128:129] op_sel:[1,0,0]
	v_cndmask_b32_e64 v75, v87, v75, s[12:13]
	v_cndmask_b32_e64 v74, v88, v74, s[12:13]
	v_cndmask_b32_e64 v71, v71, v83, s[12:13]
	v_cndmask_b32_e64 v83, v69, v85, s[12:13]
	v_cndmask_b32_e64 v82, v68, v86, s[12:13]
	v_pk_fma_f32 v[68:69], v[120:121], v[80:81], v[76:77] op_sel_hi:[1,0,1] neg_lo:[1,0,0] neg_hi:[1,0,0]
	v_pk_fma_f32 v[76:77], v[116:117], v[80:81], v[78:79] op_sel_hi:[1,0,1]
	v_max_f32_e32 v72, 0, v72
	v_pk_fma_f32 v[76:77], v[80:81], v[76:77], v[138:139] op_sel:[1,0,0]
	v_pk_fma_f32 v[74:75], v[118:119], v[80:81], v[74:75] op_sel_hi:[1,0,1]
	v_mul_f32_e32 v78, v72, v72
	v_max_f32_e32 v72, 0, v73
	v_pk_fma_f32 v[68:69], v[80:81], v[68:69], v[136:137] op_sel:[1,0,0]
	v_pk_fma_f32 v[74:75], v[80:81], v[74:75], v[130:131] op_sel:[1,0,0]
	v_mul_f32_e32 v79, v72, v72
	v_max_f32_e32 v72, 0, v76
	v_max_f32_e32 v68, 0, v68
	v_max_f32_e32 v69, 0, v69
	v_max_f32_e32 v73, 0, v74
	v_mul_f32_e32 v74, v72, v72
	v_max_f32_e32 v72, 0, v77
	v_mul_f32_e32 v68, v68, v68
	v_mul_f32_e32 v69, v69, v69
	v_mul_f32_e32 v76, v73, v73
	v_max_f32_e32 v73, 0, v75
	v_mul_f32_e32 v75, v72, v72
	v_mul_f32_e32 v77, v73, v73
	v_cndmask_b32_e64 v73, v67, v87, s[12:13]
	v_cndmask_b32_e64 v72, v66, v88, s[12:13]
	v_cvt_pk_bf16_f32 v66, v68, v69
	v_cvt_pk_bf16_f32 v67, v74, v75
	v_cvt_pk_bf16_f32 v68, v78, v79
	v_cvt_pk_bf16_f32 v69, v76, v77
	ds_read_b64 v[74:75], v164 offset:392
	v_cndmask_b32_e64 v65, v65, v89, s[12:13]
	v_cndmask_b32_e64 v64, v64, v90, s[12:13]
	v_cndmask_b32_e64 v70, v70, v84, s[12:13]
	v_add_u32_e32 v76, 0x1800, v170
	s_waitcnt lgkmcnt(0)
;     __device__ __forceinline__ void operator()(const f32x4 (&acc)[2][2][4][2], const Unit& u, int wr, int wc, int fr, int fq, const EpiCtx& X) const {
;     ...
;         EPI_PIECES({ const unsigned off = lo + (unsigned)(rl * RP) * 2u; LN_ONE(p1a, p1b, rl, off); LN_ONE(p2a, p2b, rl + 1, off + RP * 2); })
	v_pk_fma_f32 v[64:65], v[132:133], v[74:75], v[64:65] op_sel_hi:[1,0,1] neg_lo:[1,0,0] neg_hi:[1,0,0]
	global_store_dwordx4 v76, v[66:69], s[16:17] nt
	v_pk_fma_f32 v[64:65], v[74:75], v[64:65], v[128:129] op_sel:[1,0,0]
	s_nop 0
	v_pk_fma_f32 v[66:67], v[120:121], v[74:75], v[82:83] op_sel_hi:[1,0,1] neg_lo:[1,0,0] neg_hi:[1,0,0]
	v_pk_fma_f32 v[68:69], v[116:117], v[74:75], v[70:71] op_sel_hi:[1,0,1]
	v_pk_fma_f32 v[70:71], v[118:119], v[74:75], v[72:73] op_sel_hi:[1,0,1]
	v_pk_fma_f32 v[68:69], v[74:75], v[68:69], v[138:139] op_sel:[1,0,0]
	v_pk_fma_f32 v[66:67], v[74:75], v[66:67], v[136:137] op_sel:[1,0,0]
	v_pk_fma_f32 v[70:71], v[74:75], v[70:71], v[130:131] op_sel:[1,0,0]
	v_max_f32_e32 v64, 0, v64
	v_max_f32_e32 v65, 0, v65
	v_max_f32_e32 v66, 0, v66
	v_mul_f32_e32 v72, v64, v64
	v_max_f32_e32 v64, 0, v67
	v_mul_f32_e32 v67, v65, v65
	v_max_f32_e32 v65, 0, v68
	v_max_f32_e32 v68, 0, v70
	v_mul_f32_e32 v66, v66, v66
	v_mul_f32_e32 v64, v64, v64
	v_mul_f32_e32 v65, v65, v65
	v_mul_f32_e32 v68, v68, v68
	v_max_f32_e32 v69, 0, v69
	v_max_f32_e32 v70, 0, v71
	v_mul_f32_e32 v69, v69, v69
	v_mul_f32_e32 v70, v70, v70
	v_cvt_pk_bf16_f32 v64, v66, v64
	v_cvt_pk_bf16_f32 v65, v65, v69
	v_cvt_pk_bf16_f32 v66, v72, v67
	v_cvt_pk_bf16_f32 v67, v68, v70
	v_add_u32_e32 v68, 0x1880, v170
	global_store_dwordx4 v68, v[64:67], s[16:17] nt
	v_mov_b32_e32 v68, 0
	v_cndmask_b32_e64 v71, v56, v48, s[12:13]
	v_cndmask_b32_e64 v67, v60, v52, s[12:13]
	v_cndmask_b32_e64 v66, v61, v53, s[12:13]
	v_mov_b32_e32 v72, 0
	v_mov_b32_dpp v68, v67 quad_perm:[1,0,3,2] row_mask:0xf bank_mask:0xf
	v_mov_b32_e32 v67, 0
	v_cndmask_b32_e64 v64, v63, v55, s[12:13]
	v_cndmask_b32_e64 v65, v62, v54, s[12:13]
	v_mov_b32_dpp v67, v66 quad_perm:[1,0,3,2] row_mask:0xf bank_mask:0xf
	v_mov_b32_e32 v66, 0
	v_mov_b32_e32 v69, 0
	v_cndmask_b32_e64 v70, v57, v49, s[12:13]
	v_mov_b32_dpp v72, v71 quad_perm:[1,0,3,2] row_mask:0xf bank_mask:0xf
	v_mov_b32_e32 v71, 0
	v_mov_b32_dpp v66, v65 quad_perm:[1,0,3,2] row_mask:0xf bank_mask:0xf
	v_mov_b32_dpp v69, v64 quad_perm:[1,0,3,2] row_mask:0xf bank_mask:0xf
	v_cndmask_b32_e64 v64, v59, v51, s[12:13]
	v_cndmask_b32_e64 v65, v58, v50, s[12:13]
	v_mov_b32_dpp v71, v70 quad_perm:[1,0,3,2] row_mask:0xf bank_mask:0xf
	v_mov_b32_e32 v70, 0
	v_mov_b32_e32 v73, 0
	v_cndmask_b32_e64 v57, v71, v57, s[12:13]
	v_mov_b32_dpp v70, v65 quad_perm:[1,0,3,2] row_mask:0xf bank_mask:0xf
	v_mov_b32_dpp v73, v64 quad_perm:[1,0,3,2] row_mask:0xf bank_mask:0xf
	ds_read_b64 v[64:65], v164 offset:1024
	v_cndmask_b32_e64 v56, v72, v56, s[12:13]
	v_cndmask_b32_e64 v63, v69, v63, s[12:13]
	v_cndmask_b32_e64 v62, v66, v62, s[12:13]
	v_cndmask_b32_e64 v61, v67, v61, s[12:13]
	s_waitcnt lgkmcnt(0)
	v_pk_fma_f32 v[56:57], v[132:133], v[64:65], v[56:57] op_sel_hi:[1,0,1] neg_lo:[1,0,0] neg_hi:[1,0,0]
	v_cndmask_b32_e64 v60, v68, v60, s[12:13]
	v_pk_fma_f32 v[56:57], v[64:65], v[56:57], v[128:129] op_sel:[1,0,0]
	v_cndmask_b32_e64 v59, v73, v59, s[12:13]
	v_cndmask_b32_e64 v58, v70, v58, s[12:13]
	v_cndmask_b32_e64 v54, v54, v66, s[12:13]
	v_cndmask_b32_e64 v67, v53, v67, s[12:13]
	v_cndmask_b32_e64 v66, v52, v68, s[12:13]
	v_pk_fma_f32 v[52:53], v[120:121], v[64:65], v[60:61] op_sel_hi:[1,0,1] neg_lo:[1,0,0] neg_hi:[1,0,0]
	v_pk_fma_f32 v[60:61], v[116:117], v[64:65], v[62:63] op_sel_hi:[1,0,1]
	v_max_f32_e32 v56, 0, v56
	v_pk_fma_f32 v[60:61], v[64:65], v[60:61], v[138:139] op_sel:[1,0,0]
	v_pk_fma_f32 v[58:59], v[118:119], v[64:65], v[58:59] op_sel_hi:[1,0,1]
	v_mul_f32_e32 v62, v56, v56
	v_max_f32_e32 v56, 0, v57
	v_pk_fma_f32 v[52:53], v[64:65], v[52:53], v[136:137] op_sel:[1,0,0]
	v_pk_fma_f32 v[58:59], v[64:65], v[58:59], v[130:131] op_sel:[1,0,0]
	v_mul_f32_e32 v63, v56, v56
	v_max_f32_e32 v56, 0, v60
	v_max_f32_e32 v52, 0, v52
	v_max_f32_e32 v53, 0, v53
	v_max_f32_e32 v57, 0, v58
	v_mul_f32_e32 v58, v56, v56
	v_max_f32_e32 v56, 0, v61
	v_mul_f32_e32 v52, v52, v52
	v_mul_f32_e32 v53, v53, v53
	v_mul_f32_e32 v60, v57, v57
	v_max_f32_e32 v57, 0, v59
	v_mul_f32_e32 v59, v56, v56
	v_mul_f32_e32 v61, v57, v57
	v_cndmask_b32_e64 v57, v51, v73, s[12:13]
	v_cndmask_b32_e64 v56, v50, v70, s[12:13]
	v_cvt_pk_bf16_f32 v50, v52, v53
	v_cvt_pk_bf16_f32 v51, v58, v59
	v_cvt_pk_bf16_f32 v52, v62, v63
	v_cvt_pk_bf16_f32 v53, v60, v61
	ds_read_b64 v[58:59], v164 offset:1032
	v_cndmask_b32_e64 v49, v49, v71, s[12:13]
	v_cndmask_b32_e64 v48, v48, v72, s[12:13]
	v_cndmask_b32_e64 v55, v55, v69, s[12:13]
	v_add_u32_e32 v60, 0x4000, v170
	s_waitcnt lgkmcnt(0)
;     __device__ __forceinline__ void operator()(const f32x4 (&acc)[2][2][4][2], const Unit& u, int wr, int wc, int fr, int fq, const EpiCtx& X) const {
;     ...
;         EPI_PIECES({ const unsigned off = lo + (unsigned)(rl * RP) * 2u; LN_ONE(p1a, p1b, rl, off); LN_ONE(p2a, p2b, rl + 1, off + RP * 2); })
	v_pk_fma_f32 v[48:49], v[132:133], v[58:59], v[48:49] op_sel_hi:[1,0,1] neg_lo:[1,0,0] neg_hi:[1,0,0]
	global_store_dwordx4 v60, v[50:53], s[16:17] nt
	v_pk_fma_f32 v[48:49], v[58:59], v[48:49], v[128:129] op_sel:[1,0,0]
	s_nop 0
	v_pk_fma_f32 v[50:51], v[120:121], v[58:59], v[66:67] op_sel_hi:[1,0,1] neg_lo:[1,0,0] neg_hi:[1,0,0]
	v_pk_fma_f32 v[52:53], v[116:117], v[58:59], v[54:55] op_sel_hi:[1,0,1]
	v_pk_fma_f32 v[54:55], v[118:119], v[58:59], v[56:57] op_sel_hi:[1,0,1]
	v_pk_fma_f32 v[52:53], v[58:59], v[52:53], v[138:139] op_sel:[1,0,0]
	v_pk_fma_f32 v[50:51], v[58:59], v[50:51], v[136:137] op_sel:[1,0,0]
	v_pk_fma_f32 v[54:55], v[58:59], v[54:55], v[130:131] op_sel:[1,0,0]
	v_max_f32_e32 v48, 0, v48
	v_max_f32_e32 v49, 0, v49
	v_max_f32_e32 v50, 0, v50
	v_mul_f32_e32 v56, v48, v48
	v_max_f32_e32 v48, 0, v51
	v_mul_f32_e32 v51, v49, v49
	v_max_f32_e32 v49, 0, v52
	v_max_f32_e32 v52, 0, v54
	v_mul_f32_e32 v50, v50, v50
	v_mul_f32_e32 v48, v48, v48
	v_mul_f32_e32 v49, v49, v49
	v_mul_f32_e32 v52, v52, v52
	v_max_f32_e32 v53, 0, v53
	v_max_f32_e32 v54, 0, v55
	v_mul_f32_e32 v53, v53, v53
	v_mul_f32_e32 v54, v54, v54
	v_cvt_pk_bf16_f32 v48, v50, v48
	v_cvt_pk_bf16_f32 v49, v49, v53
	v_cvt_pk_bf16_f32 v50, v56, v51
	v_cvt_pk_bf16_f32 v51, v52, v54
	v_add_u32_e32 v52, 0x4080, v170
	global_store_dwordx4 v52, v[48:51], s[16:17] nt
	ds_read_b64 v[48:49], v164 offset:1152
	v_cndmask_b32_e64 v53, v44, v36, s[12:13]
	v_mov_b32_e32 v54, 0
	v_cndmask_b32_e64 v57, v40, v32, s[12:13]
	v_mov_b32_e32 v58, 0
	v_cndmask_b32_e64 v52, v45, v37, s[12:13]
	v_mov_b32_dpp v54, v53 quad_perm:[1,0,3,2] row_mask:0xf bank_mask:0xf
	v_mov_b32_e32 v53, 0
	v_cndmask_b32_e64 v56, v41, v33, s[12:13]
	v_mov_b32_dpp v58, v57 quad_perm:[1,0,3,2] row_mask:0xf bank_mask:0xf
	v_mov_b32_e32 v57, 0
	v_cndmask_b32_e64 v51, v46, v38, s[12:13]
	v_mov_b32_dpp v53, v52 quad_perm:[1,0,3,2] row_mask:0xf bank_mask:0xf
	v_mov_b32_e32 v52, 0
	v_mov_b32_dpp v57, v56 quad_perm:[1,0,3,2] row_mask:0xf bank_mask:0xf
	v_cndmask_b32_e64 v50, v47, v39, s[12:13]
	v_mov_b32_dpp v52, v51 quad_perm:[1,0,3,2] row_mask:0xf bank_mask:0xf
	v_mov_b32_e32 v51, 0
	v_cndmask_b32_e64 v55, v42, v34, s[12:13]
	v_mov_b32_e32 v56, 0
	v_cndmask_b32_e64 v41, v57, v41, s[12:13]
	v_cndmask_b32_e64 v40, v58, v40, s[12:13]
	v_mov_b32_dpp v51, v50 quad_perm:[1,0,3,2] row_mask:0xf bank_mask:0xf
	v_cndmask_b32_e64 v50, v43, v35, s[12:13]
	v_mov_b32_dpp v56, v55 quad_perm:[1,0,3,2] row_mask:0xf bank_mask:0xf
	v_mov_b32_e32 v55, 0
	s_waitcnt lgkmcnt(0)
	v_pk_fma_f32 v[40:41], v[132:133], v[48:49], v[40:41] op_sel_hi:[1,0,1] neg_lo:[1,0,0] neg_hi:[1,0,0]
	v_cndmask_b32_e64 v47, v51, v47, s[12:13]
	v_mov_b32_dpp v55, v50 quad_perm:[1,0,3,2] row_mask:0xf bank_mask:0xf
	v_cndmask_b32_e64 v46, v52, v46, s[12:13]
	v_cndmask_b32_e64 v45, v53, v45, s[12:13]
	v_cndmask_b32_e64 v44, v54, v44, s[12:13]
	v_pk_fma_f32 v[40:41], v[48:49], v[40:41], v[128:129] op_sel:[1,0,0]
	v_cndmask_b32_e64 v43, v55, v43, s[12:13]
	v_cndmask_b32_e64 v42, v56, v42, s[12:13]
	v_cndmask_b32_e64 v39, v39, v51, s[12:13]
	v_cndmask_b32_e64 v51, v37, v53, s[12:13]
	v_cndmask_b32_e64 v50, v36, v54, s[12:13]
	v_pk_fma_f32 v[36:37], v[120:121], v[48:49], v[44:45] op_sel_hi:[1,0,1] neg_lo:[1,0,0] neg_hi:[1,0,0]
	v_pk_fma_f32 v[44:45], v[116:117], v[48:49], v[46:47] op_sel_hi:[1,0,1]
	v_max_f32_e32 v40, 0, v40
	v_pk_fma_f32 v[44:45], v[48:49], v[44:45], v[138:139] op_sel:[1,0,0]
	v_pk_fma_f32 v[42:43], v[118:119], v[48:49], v[42:43] op_sel_hi:[1,0,1]
	v_mul_f32_e32 v46, v40, v40
	v_max_f32_e32 v40, 0, v41
	v_pk_fma_f32 v[36:37], v[48:49], v[36:37], v[136:137] op_sel:[1,0,0]
	v_pk_fma_f32 v[42:43], v[48:49], v[42:43], v[130:131] op_sel:[1,0,0]
	v_mul_f32_e32 v47, v40, v40
	v_max_f32_e32 v40, 0, v44
	v_max_f32_e32 v36, 0, v36
	v_max_f32_e32 v37, 0, v37
	v_max_f32_e32 v41, 0, v42
	v_mul_f32_e32 v42, v40, v40
	v_max_f32_e32 v40, 0, v45
	v_mul_f32_e32 v36, v36, v36
	v_mul_f32_e32 v37, v37, v37
	v_mul_f32_e32 v44, v41, v41
	v_max_f32_e32 v41, 0, v43
	v_mul_f32_e32 v43, v40, v40
	v_mul_f32_e32 v45, v41, v41
	v_cndmask_b32_e64 v41, v35, v55, s[12:13]
	v_cndmask_b32_e64 v40, v34, v56, s[12:13]
	v_cvt_pk_bf16_f32 v34, v36, v37
	v_cvt_pk_bf16_f32 v35, v42, v43
	v_cvt_pk_bf16_f32 v36, v46, v47
	v_cvt_pk_bf16_f32 v37, v44, v45
	ds_read_b64 v[42:43], v164 offset:1160
	v_cndmask_b32_e64 v33, v33, v57, s[12:13]
	v_cndmask_b32_e64 v32, v32, v58, s[12:13]
	v_cndmask_b32_e64 v38, v38, v52, s[12:13]
	v_add_u32_e32 v44, 0x4800, v170
	s_waitcnt lgkmcnt(0)
;     __device__ __forceinline__ void operator()(const f32x4 (&acc)[2][2][4][2], const Unit& u, int wr, int wc, int fr, int fq, const EpiCtx& X) const {
;     ...
;         EPI_PIECES({ const unsigned off = lo + (unsigned)(rl * RP) * 2u; LN_ONE(p1a, p1b, rl, off); LN_ONE(p2a, p2b, rl + 1, off + RP * 2); })
	v_pk_fma_f32 v[32:33], v[132:133], v[42:43], v[32:33] op_sel_hi:[1,0,1] neg_lo:[1,0,0] neg_hi:[1,0,0]
	global_store_dwordx4 v44, v[34:37], s[16:17] nt
	v_pk_fma_f32 v[32:33], v[42:43], v[32:33], v[128:129] op_sel:[1,0,0]
	s_nop 0
	v_pk_fma_f32 v[34:35], v[120:121], v[42:43], v[50:51] op_sel_hi:[1,0,1] neg_lo:[1,0,0] neg_hi:[1,0,0]
	v_pk_fma_f32 v[36:37], v[116:117], v[42:43], v[38:39] op_sel_hi:[1,0,1]
	v_pk_fma_f32 v[38:39], v[118:119], v[42:43], v[40:41] op_sel_hi:[1,0,1]
	v_pk_fma_f32 v[36:37], v[42:43], v[36:37], v[138:139] op_sel:[1,0,0]
	v_pk_fma_f32 v[34:35], v[42:43], v[34:35], v[136:137] op_sel:[1,0,0]
	v_pk_fma_f32 v[38:39], v[42:43], v[38:39], v[130:131] op_sel:[1,0,0]
	v_max_f32_e32 v32, 0, v32
	v_max_f32_e32 v33, 0, v33
	v_max_f32_e32 v34, 0, v34
	v_mul_f32_e32 v40, v32, v32
	v_max_f32_e32 v32, 0, v35
	v_mul_f32_e32 v35, v33, v33
	v_max_f32_e32 v33, 0, v36
	v_max_f32_e32 v36, 0, v38
	v_mul_f32_e32 v34, v34, v34
	v_mul_f32_e32 v32, v32, v32
	v_mul_f32_e32 v33, v33, v33
	v_mul_f32_e32 v36, v36, v36
	v_max_f32_e32 v37, 0, v37
	v_max_f32_e32 v38, 0, v39
	v_mul_f32_e32 v37, v37, v37
	v_mul_f32_e32 v38, v38, v38
	v_cvt_pk_bf16_f32 v32, v34, v32
	v_cvt_pk_bf16_f32 v33, v33, v37
	v_cvt_pk_bf16_f32 v34, v40, v35
	v_cvt_pk_bf16_f32 v35, v36, v38
	v_add_u32_e32 v36, 0x4880, v170
	global_store_dwordx4 v36, v[32:35], s[16:17] nt
	v_mov_b32_e32 v36, 0
	v_cndmask_b32_e64 v39, v24, v16, s[12:13]
	v_cndmask_b32_e64 v35, v28, v20, s[12:13]
	v_cndmask_b32_e64 v34, v29, v21, s[12:13]
	v_mov_b32_e32 v40, 0
	v_mov_b32_dpp v36, v35 quad_perm:[1,0,3,2] row_mask:0xf bank_mask:0xf
	v_mov_b32_e32 v35, 0
	v_cndmask_b32_e64 v32, v31, v23, s[12:13]
	v_cndmask_b32_e64 v33, v30, v22, s[12:13]
	v_mov_b32_dpp v35, v34 quad_perm:[1,0,3,2] row_mask:0xf bank_mask:0xf
	v_mov_b32_e32 v34, 0
	v_mov_b32_e32 v37, 0
	v_cndmask_b32_e64 v38, v25, v17, s[12:13]
	v_mov_b32_dpp v40, v39 quad_perm:[1,0,3,2] row_mask:0xf bank_mask:0xf
	v_mov_b32_e32 v39, 0
	v_mov_b32_dpp v34, v33 quad_perm:[1,0,3,2] row_mask:0xf bank_mask:0xf
	v_mov_b32_dpp v37, v32 quad_perm:[1,0,3,2] row_mask:0xf bank_mask:0xf
	v_cndmask_b32_e64 v32, v27, v19, s[12:13]
	v_cndmask_b32_e64 v33, v26, v18, s[12:13]
	v_mov_b32_dpp v39, v38 quad_perm:[1,0,3,2] row_mask:0xf bank_mask:0xf
	v_mov_b32_e32 v38, 0
	v_mov_b32_e32 v41, 0
	v_cndmask_b32_e64 v25, v39, v25, s[12:13]
	v_mov_b32_dpp v38, v33 quad_perm:[1,0,3,2] row_mask:0xf bank_mask:0xf
	v_mov_b32_dpp v41, v32 quad_perm:[1,0,3,2] row_mask:0xf bank_mask:0xf
	ds_read_b64 v[32:33], v164 offset:1280
	v_cndmask_b32_e64 v24, v40, v24, s[12:13]
	v_cndmask_b32_e64 v31, v37, v31, s[12:13]
	v_cndmask_b32_e64 v30, v34, v30, s[12:13]
	v_cndmask_b32_e64 v29, v35, v29, s[12:13]
	s_waitcnt lgkmcnt(0)
	v_pk_fma_f32 v[24:25], v[132:133], v[32:33], v[24:25] op_sel_hi:[1,0,1] neg_lo:[1,0,0] neg_hi:[1,0,0]
	v_cndmask_b32_e64 v28, v36, v28, s[12:13]
	v_pk_fma_f32 v[24:25], v[32:33], v[24:25], v[128:129] op_sel:[1,0,0]
	v_cndmask_b32_e64 v27, v41, v27, s[12:13]
	v_cndmask_b32_e64 v26, v38, v26, s[12:13]
	v_cndmask_b32_e64 v22, v22, v34, s[12:13]
	v_cndmask_b32_e64 v35, v21, v35, s[12:13]
	v_cndmask_b32_e64 v34, v20, v36, s[12:13]
	v_pk_fma_f32 v[20:21], v[120:121], v[32:33], v[28:29] op_sel_hi:[1,0,1] neg_lo:[1,0,0] neg_hi:[1,0,0]
	v_pk_fma_f32 v[28:29], v[116:117], v[32:33], v[30:31] op_sel_hi:[1,0,1]
	v_max_f32_e32 v24, 0, v24
	v_pk_fma_f32 v[28:29], v[32:33], v[28:29], v[138:139] op_sel:[1,0,0]
	v_pk_fma_f32 v[26:27], v[118:119], v[32:33], v[26:27] op_sel_hi:[1,0,1]
	v_mul_f32_e32 v30, v24, v24
	v_max_f32_e32 v24, 0, v25
	v_pk_fma_f32 v[20:21], v[32:33], v[20:21], v[136:137] op_sel:[1,0,0]
	v_pk_fma_f32 v[26:27], v[32:33], v[26:27], v[130:131] op_sel:[1,0,0]
	v_mul_f32_e32 v31, v24, v24
	v_max_f32_e32 v24, 0, v28
	v_max_f32_e32 v20, 0, v20
	v_max_f32_e32 v21, 0, v21
	v_max_f32_e32 v25, 0, v26
	v_mul_f32_e32 v26, v24, v24
	v_max_f32_e32 v24, 0, v29
	v_mul_f32_e32 v20, v20, v20
	v_mul_f32_e32 v21, v21, v21
	v_mul_f32_e32 v28, v25, v25
	v_max_f32_e32 v25, 0, v27
	v_mul_f32_e32 v27, v24, v24
	v_mul_f32_e32 v29, v25, v25
	v_cndmask_b32_e64 v25, v19, v41, s[12:13]
	v_cndmask_b32_e64 v24, v18, v38, s[12:13]
	v_cvt_pk_bf16_f32 v18, v20, v21
	v_cvt_pk_bf16_f32 v19, v26, v27
	v_cvt_pk_bf16_f32 v20, v30, v31
	v_cvt_pk_bf16_f32 v21, v28, v29
	ds_read_b64 v[26:27], v164 offset:1288
	v_cndmask_b32_e64 v17, v17, v39, s[12:13]
	v_cndmask_b32_e64 v16, v16, v40, s[12:13]
	v_cndmask_b32_e64 v23, v23, v37, s[12:13]
	v_add_u32_e32 v28, 0x5000, v170
	s_waitcnt lgkmcnt(0)
;     __device__ __forceinline__ void operator()(const f32x4 (&acc)[2][2][4][2], const Unit& u, int wr, int wc, int fr, int fq, const EpiCtx& X) const {
;     ...
;         EPI_PIECES({ const unsigned off = lo + (unsigned)(rl * RP) * 2u; LN_ONE(p1a, p1b, rl, off); LN_ONE(p2a, p2b, rl + 1, off + RP * 2); })
	v_pk_fma_f32 v[16:17], v[132:133], v[26:27], v[16:17] op_sel_hi:[1,0,1] neg_lo:[1,0,0] neg_hi:[1,0,0]
	global_store_dwordx4 v28, v[18:21], s[16:17] nt
	v_pk_fma_f32 v[16:17], v[26:27], v[16:17], v[128:129] op_sel:[1,0,0]
	s_nop 0
	v_pk_fma_f32 v[18:19], v[120:121], v[26:27], v[34:35] op_sel_hi:[1,0,1] neg_lo:[1,0,0] neg_hi:[1,0,0]
	v_pk_fma_f32 v[20:21], v[116:117], v[26:27], v[22:23] op_sel_hi:[1,0,1]
	v_pk_fma_f32 v[22:23], v[118:119], v[26:27], v[24:25] op_sel_hi:[1,0,1]
	v_pk_fma_f32 v[20:21], v[26:27], v[20:21], v[138:139] op_sel:[1,0,0]
	v_pk_fma_f32 v[18:19], v[26:27], v[18:19], v[136:137] op_sel:[1,0,0]
	v_pk_fma_f32 v[22:23], v[26:27], v[22:23], v[130:131] op_sel:[1,0,0]
	v_max_f32_e32 v16, 0, v16
	v_max_f32_e32 v17, 0, v17
	v_max_f32_e32 v18, 0, v18
	v_mul_f32_e32 v24, v16, v16
	v_max_f32_e32 v16, 0, v19
	v_mul_f32_e32 v19, v17, v17
	v_max_f32_e32 v17, 0, v20
	v_max_f32_e32 v20, 0, v22
	v_mul_f32_e32 v18, v18, v18
	v_mul_f32_e32 v16, v16, v16
	v_mul_f32_e32 v17, v17, v17
	v_mul_f32_e32 v20, v20, v20
	v_max_f32_e32 v21, 0, v21
	v_max_f32_e32 v22, 0, v23
	v_mul_f32_e32 v21, v21, v21
	v_mul_f32_e32 v22, v22, v22
	v_cvt_pk_bf16_f32 v16, v18, v16
	v_cvt_pk_bf16_f32 v17, v17, v21
	v_cvt_pk_bf16_f32 v18, v24, v19
	v_cvt_pk_bf16_f32 v19, v20, v22
	v_add_u32_e32 v20, 0x5080, v170
	global_store_dwordx4 v20, v[16:19], s[16:17] nt
	ds_read_b64 v[16:17], v164 offset:1408
	v_cndmask_b32_e64 v21, v12, v4, s[12:13]
	v_mov_b32_e32 v22, 0
	v_cndmask_b32_e64 v25, v8, v0, s[12:13]
	v_mov_b32_e32 v26, 0
	v_cndmask_b32_e64 v20, v13, v5, s[12:13]
	v_mov_b32_dpp v22, v21 quad_perm:[1,0,3,2] row_mask:0xf bank_mask:0xf
	v_mov_b32_e32 v21, 0
	v_cndmask_b32_e64 v24, v9, v1, s[12:13]
	v_mov_b32_dpp v26, v25 quad_perm:[1,0,3,2] row_mask:0xf bank_mask:0xf
	v_mov_b32_e32 v25, 0
	v_cndmask_b32_e64 v19, v14, v6, s[12:13]
	v_mov_b32_dpp v21, v20 quad_perm:[1,0,3,2] row_mask:0xf bank_mask:0xf
	v_mov_b32_e32 v20, 0
	v_mov_b32_dpp v25, v24 quad_perm:[1,0,3,2] row_mask:0xf bank_mask:0xf
	v_cndmask_b32_e64 v18, v15, v7, s[12:13]
	v_mov_b32_dpp v20, v19 quad_perm:[1,0,3,2] row_mask:0xf bank_mask:0xf
	v_mov_b32_e32 v19, 0
	v_cndmask_b32_e64 v23, v10, v2, s[12:13]
	v_mov_b32_e32 v24, 0
	v_cndmask_b32_e64 v9, v25, v9, s[12:13]
	v_cndmask_b32_e64 v8, v26, v8, s[12:13]
	v_mov_b32_dpp v19, v18 quad_perm:[1,0,3,2] row_mask:0xf bank_mask:0xf
	v_cndmask_b32_e64 v18, v11, v3, s[12:13]
	v_mov_b32_dpp v24, v23 quad_perm:[1,0,3,2] row_mask:0xf bank_mask:0xf
	v_mov_b32_e32 v23, 0
	s_waitcnt lgkmcnt(0)
	v_pk_fma_f32 v[8:9], v[132:133], v[16:17], v[8:9] op_sel_hi:[1,0,1] neg_lo:[1,0,0] neg_hi:[1,0,0]
	v_cndmask_b32_e64 v15, v19, v15, s[12:13]
	v_mov_b32_dpp v23, v18 quad_perm:[1,0,3,2] row_mask:0xf bank_mask:0xf
	v_cndmask_b32_e64 v14, v20, v14, s[12:13]
	v_cndmask_b32_e64 v13, v21, v13, s[12:13]
	v_cndmask_b32_e64 v12, v22, v12, s[12:13]
	v_pk_fma_f32 v[8:9], v[16:17], v[8:9], v[128:129] op_sel:[1,0,0]
	v_cndmask_b32_e64 v11, v23, v11, s[12:13]
	v_cndmask_b32_e64 v10, v24, v10, s[12:13]
	v_cndmask_b32_e64 v7, v7, v19, s[12:13]
	v_cndmask_b32_e64 v19, v5, v21, s[12:13]
	v_cndmask_b32_e64 v18, v4, v22, s[12:13]
	v_pk_fma_f32 v[4:5], v[120:121], v[16:17], v[12:13] op_sel_hi:[1,0,1] neg_lo:[1,0,0] neg_hi:[1,0,0]
	v_pk_fma_f32 v[12:13], v[116:117], v[16:17], v[14:15] op_sel_hi:[1,0,1]
	v_max_f32_e32 v8, 0, v8
	v_pk_fma_f32 v[12:13], v[16:17], v[12:13], v[138:139] op_sel:[1,0,0]
	v_pk_fma_f32 v[10:11], v[118:119], v[16:17], v[10:11] op_sel_hi:[1,0,1]
	v_mul_f32_e32 v14, v8, v8
	v_max_f32_e32 v8, 0, v9
	v_pk_fma_f32 v[4:5], v[16:17], v[4:5], v[136:137] op_sel:[1,0,0]
	v_pk_fma_f32 v[10:11], v[16:17], v[10:11], v[130:131] op_sel:[1,0,0]
	v_mul_f32_e32 v15, v8, v8
	v_max_f32_e32 v8, 0, v12
	v_max_f32_e32 v4, 0, v4
	v_max_f32_e32 v5, 0, v5
	v_max_f32_e32 v9, 0, v10
	v_mul_f32_e32 v10, v8, v8
	v_max_f32_e32 v8, 0, v13
	v_mul_f32_e32 v4, v4, v4
	v_mul_f32_e32 v5, v5, v5
	v_mul_f32_e32 v12, v9, v9
	v_max_f32_e32 v9, 0, v11
	v_mul_f32_e32 v11, v8, v8
	v_mul_f32_e32 v13, v9, v9
	v_cndmask_b32_e64 v9, v3, v23, s[12:13]
	v_cndmask_b32_e64 v8, v2, v24, s[12:13]
	v_cvt_pk_bf16_f32 v2, v4, v5
	v_cvt_pk_bf16_f32 v3, v10, v11
	v_cvt_pk_bf16_f32 v4, v14, v15
	v_cvt_pk_bf16_f32 v5, v12, v13
	ds_read_b64 v[10:11], v164 offset:1416
	v_cndmask_b32_e64 v1, v1, v25, s[12:13]
	v_cndmask_b32_e64 v0, v0, v26, s[12:13]
	v_cndmask_b32_e64 v6, v6, v20, s[12:13]
	v_add_u32_e32 v12, 0x5800, v170
	s_waitcnt lgkmcnt(0)
	v_pk_fma_f32 v[0:1], v[132:133], v[10:11], v[0:1] op_sel_hi:[1,0,1] neg_lo:[1,0,0] neg_hi:[1,0,0]
	global_store_dwordx4 v12, v[2:5], s[16:17] nt
	v_pk_fma_f32 v[0:1], v[10:11], v[0:1], v[128:129] op_sel:[1,0,0]
	s_nop 0
	v_pk_fma_f32 v[2:3], v[120:121], v[10:11], v[18:19] op_sel_hi:[1,0,1] neg_lo:[1,0,0] neg_hi:[1,0,0]
	v_pk_fma_f32 v[4:5], v[116:117], v[10:11], v[6:7] op_sel_hi:[1,0,1]
	v_pk_fma_f32 v[6:7], v[118:119], v[10:11], v[8:9] op_sel_hi:[1,0,1]
	v_pk_fma_f32 v[4:5], v[10:11], v[4:5], v[138:139] op_sel:[1,0,0]
	v_pk_fma_f32 v[2:3], v[10:11], v[2:3], v[136:137] op_sel:[1,0,0]
	v_pk_fma_f32 v[6:7], v[10:11], v[6:7], v[130:131] op_sel:[1,0,0]
	v_max_f32_e32 v0, 0, v0
	v_max_f32_e32 v1, 0, v1
	v_max_f32_e32 v2, 0, v2
	v_mul_f32_e32 v8, v0, v0
	v_max_f32_e32 v0, 0, v3
	v_mul_f32_e32 v3, v1, v1
	v_max_f32_e32 v1, 0, v4
	v_max_f32_e32 v4, 0, v6
	v_mul_f32_e32 v2, v2, v2
	v_mul_f32_e32 v0, v0, v0
	v_mul_f32_e32 v1, v1, v1
	v_mul_f32_e32 v4, v4, v4
	v_max_f32_e32 v5, 0, v5
	v_max_f32_e32 v6, 0, v7
	v_mul_f32_e32 v5, v5, v5
	v_mul_f32_e32 v6, v6, v6
	v_cvt_pk_bf16_f32 v0, v2, v0
	v_cvt_pk_bf16_f32 v1, v1, v5
	v_cvt_pk_bf16_f32 v2, v8, v3
	v_cvt_pk_bf16_f32 v3, v4, v6
	v_add_u32_e32 v4, 0x5880, v170
	global_store_dwordx4 v4, v[0:3], s[16:17] nt
	s_cbranch_vccnz .LBB0_1560
	s_and_b64 vcc, exec, s[6:7]
	s_cbranch_vccnz .LBB0_1559
	s_barrier
	s_branch .LBB0_1559
